# plus: removed mid-MFMA-block setprio 0/1 toggles and redundant post-barrier lgkmcnt(0) in all 12 GEMM K-loops
# baseline (speedup 1.0000x reference)
.LBB0_70:
	v_add_u32_e32 v186, s42, v167
	v_add_u32_e32 v202, s43, v167
	ds_read_b128 v[172:175], v186
	ds_read_b128 v[178:181], v186 offset:1024
	ds_read_b128 v[182:185], v186 offset:2048
	ds_read_b128 v[186:189], v186 offset:3072
	ds_read_b128 v[190:193], v202
	ds_read_b128 v[194:197], v202 offset:1024
	ds_read_b128 v[198:201], v202 offset:2048
	ds_read_b128 v[202:205], v202 offset:3072
	v_lshl_add_u64 v[206:207], v[162:163], 0, s[20:21]
	v_cndmask_b32_e64 v239, v207, v157, s[6:7]
	v_cndmask_b32_e64 v238, v206, v156, s[6:7]
	v_cndmask_b32_e64 v241, v161, v159, s[6:7]
	v_cndmask_b32_e64 v240, v160, v158, s[6:7]
	v_lshl_add_u64 v[242:243], v[162:163], 0, v[146:147]
	s_add_i32 m0, s29, 0xc000
	ds_read_b128 v[206:209], v170
	ds_read_b128 v[210:213], v170 offset:1024
	ds_read_b128 v[214:217], v170 offset:2048
	ds_read_b128 v[218:221], v170 offset:3072
	ds_read_b128 v[222:225], v170 offset:4096
	ds_read_b128 v[226:229], v170 offset:5120
	ds_read_b128 v[230:233], v170 offset:6144
	ds_read_b128 v[234:237], v170 offset:7168
	global_load_lds_dwordx4 v[242:243], off
	v_lshl_add_u64 v[242:243], v[162:163], 0, v[144:145]
	s_add_i32 m0, s29, 0xe000
	s_nop 0
	global_load_lds_dwordx4 v[242:243], off
	s_waitcnt vmcnt(8)
	s_waitcnt lgkmcnt(0)
	s_barrier
	s_setprio 1
	v_mfma_f32_16x16x32_bf16 v[124:127], v[172:175], v[206:209], v[124:127]
	v_mfma_f32_16x16x32_bf16 v[116:119], v[182:185], v[206:209], v[116:119]
	v_mfma_f32_16x16x32_bf16 v[108:111], v[172:175], v[214:217], v[108:111]
	v_mfma_f32_16x16x32_bf16 v[100:103], v[182:185], v[214:217], v[100:103]
	v_mfma_f32_16x16x32_bf16 v[92:95], v[172:175], v[222:225], v[92:95]
	v_mfma_f32_16x16x32_bf16 v[84:87], v[182:185], v[222:225], v[84:87]
	v_mfma_f32_16x16x32_bf16 v[76:79], v[172:175], v[230:233], v[76:79]
	v_mfma_f32_16x16x32_bf16 v[68:71], v[182:185], v[230:233], v[68:71]
	v_mfma_f32_16x16x32_bf16 v[124:127], v[178:181], v[210:213], v[124:127]
	v_mfma_f32_16x16x32_bf16 v[116:119], v[186:189], v[210:213], v[116:119]
	v_mfma_f32_16x16x32_bf16 v[108:111], v[178:181], v[218:221], v[108:111]
	v_mfma_f32_16x16x32_bf16 v[100:103], v[186:189], v[218:221], v[100:103]
	v_mfma_f32_16x16x32_bf16 v[92:95], v[178:181], v[226:229], v[92:95]
	v_mfma_f32_16x16x32_bf16 v[84:87], v[186:189], v[226:229], v[84:87]
	v_mfma_f32_16x16x32_bf16 v[76:79], v[178:181], v[234:237], v[76:79]
	v_mfma_f32_16x16x32_bf16 v[68:71], v[186:189], v[234:237], v[68:71]
	v_mfma_f32_16x16x32_bf16 v[120:123], v[190:193], v[206:209], v[120:123]
	v_mfma_f32_16x16x32_bf16 v[112:115], v[198:201], v[206:209], v[112:115]
	v_mfma_f32_16x16x32_bf16 v[104:107], v[190:193], v[214:217], v[104:107]
	v_mfma_f32_16x16x32_bf16 v[96:99], v[198:201], v[214:217], v[96:99]
	v_mfma_f32_16x16x32_bf16 v[88:91], v[190:193], v[222:225], v[88:91]
	v_mfma_f32_16x16x32_bf16 v[80:83], v[198:201], v[222:225], v[80:83]
	v_mfma_f32_16x16x32_bf16 v[72:75], v[190:193], v[230:233], v[72:75]
	v_mfma_f32_16x16x32_bf16 v[64:67], v[198:201], v[230:233], v[64:67]
	v_mfma_f32_16x16x32_bf16 v[120:123], v[194:197], v[210:213], v[120:123]
	v_mfma_f32_16x16x32_bf16 v[112:115], v[202:205], v[210:213], v[112:115]
	v_mfma_f32_16x16x32_bf16 v[104:107], v[194:197], v[218:221], v[104:107]
	v_mfma_f32_16x16x32_bf16 v[96:99], v[202:205], v[218:221], v[96:99]
	v_mfma_f32_16x16x32_bf16 v[88:91], v[194:197], v[226:229], v[88:91]
	v_mfma_f32_16x16x32_bf16 v[80:83], v[202:205], v[226:229], v[80:83]
	v_mfma_f32_16x16x32_bf16 v[72:75], v[194:197], v[234:237], v[72:75]
	v_mfma_f32_16x16x32_bf16 v[64:67], v[202:205], v[234:237], v[64:67]
	s_setprio 0
	s_barrier
	s_add_i32 s6, s42, s3
	v_lshl_add_u64 v[242:243], v[240:241], 0, v[136:137]
	s_mov_b32 m0, s6
	ds_read_b128 v[206:209], v170 offset:16384
	ds_read_b128 v[210:213], v170 offset:17408
	ds_read_b128 v[214:217], v170 offset:18432
	ds_read_b128 v[218:221], v170 offset:19456
	ds_read_b128 v[222:225], v170 offset:20480
	ds_read_b128 v[226:229], v170 offset:21504
	ds_read_b128 v[230:233], v170 offset:22528
	ds_read_b128 v[234:237], v170 offset:23552
	global_load_lds_dwordx4 v[242:243], off
	v_lshl_add_u64 v[244:245], v[240:241], 0, v[140:141]
	s_add_i32 m0, s6, 0x2000
	v_lshl_add_u64 v[246:247], v[240:241], 0, s[8:9]
	s_add_i32 s6, s43, s3
	global_load_lds_dwordx4 v[244:245], off
	v_lshl_add_u64 v[248:249], v[246:247], 0, v[136:137]
	s_mov_b32 m0, s6
	v_lshl_add_u64 v[246:247], v[246:247], 0, v[140:141]
	global_load_lds_dwordx4 v[248:249], off
	s_add_i32 m0, s6, 0x2000
	v_lshl_add_u64 v[248:249], v[238:239], 0, v[138:139]
	global_load_lds_dwordx4 v[246:247], off
	v_lshl_add_u64 v[246:247], v[238:239], 0, v[134:135]
	s_mov_b32 m0, s29
	s_nop 0
	global_load_lds_dwordx4 v[246:247], off
	s_mov_b32 m0, s31
	s_nop 0
	global_load_lds_dwordx4 v[248:249], off
	s_waitcnt vmcnt(8)
	s_waitcnt lgkmcnt(0)
	s_barrier
	s_setprio 1
	v_mfma_f32_16x16x32_bf16 v[60:63], v[172:175], v[206:209], v[60:63]
	v_mfma_f32_16x16x32_bf16 v[52:55], v[182:185], v[206:209], v[52:55]
	v_mfma_f32_16x16x32_bf16 v[44:47], v[172:175], v[214:217], v[44:47]
	v_mfma_f32_16x16x32_bf16 v[36:39], v[182:185], v[214:217], v[36:39]
	v_mfma_f32_16x16x32_bf16 v[28:31], v[172:175], v[222:225], v[28:31]
	v_mfma_f32_16x16x32_bf16 v[20:23], v[182:185], v[222:225], v[20:23]
	v_mfma_f32_16x16x32_bf16 v[12:15], v[172:175], v[230:233], v[12:15]
	v_mfma_f32_16x16x32_bf16 v[4:7], v[182:185], v[230:233], v[4:7]
	v_mfma_f32_16x16x32_bf16 v[60:63], v[178:181], v[210:213], v[60:63]
	v_mfma_f32_16x16x32_bf16 v[52:55], v[186:189], v[210:213], v[52:55]
	v_mfma_f32_16x16x32_bf16 v[44:47], v[178:181], v[218:221], v[44:47]
	v_mfma_f32_16x16x32_bf16 v[36:39], v[186:189], v[218:221], v[36:39]
	v_mfma_f32_16x16x32_bf16 v[28:31], v[178:181], v[226:229], v[28:31]
	v_mfma_f32_16x16x32_bf16 v[20:23], v[186:189], v[226:229], v[20:23]
	v_mfma_f32_16x16x32_bf16 v[12:15], v[178:181], v[234:237], v[12:15]
	v_mfma_f32_16x16x32_bf16 v[4:7], v[186:189], v[234:237], v[4:7]
	v_mfma_f32_16x16x32_bf16 v[56:59], v[190:193], v[206:209], v[56:59]
	v_mfma_f32_16x16x32_bf16 v[48:51], v[198:201], v[206:209], v[48:51]
	v_mfma_f32_16x16x32_bf16 v[40:43], v[190:193], v[214:217], v[40:43]
	v_mfma_f32_16x16x32_bf16 v[32:35], v[198:201], v[214:217], v[32:35]
	v_mfma_f32_16x16x32_bf16 v[24:27], v[190:193], v[222:225], v[24:27]
	v_mfma_f32_16x16x32_bf16 v[16:19], v[198:201], v[222:225], v[16:19]
	v_mfma_f32_16x16x32_bf16 v[8:11], v[190:193], v[230:233], v[8:11]
	v_mfma_f32_16x16x32_bf16 v[0:3], v[198:201], v[230:233], v[0:3]
	v_mfma_f32_16x16x32_bf16 v[56:59], v[194:197], v[210:213], v[56:59]
	v_mfma_f32_16x16x32_bf16 v[48:51], v[202:205], v[210:213], v[48:51]
	v_mfma_f32_16x16x32_bf16 v[40:43], v[194:197], v[218:221], v[40:43]
	v_mfma_f32_16x16x32_bf16 v[32:35], v[202:205], v[218:221], v[32:35]
	v_mfma_f32_16x16x32_bf16 v[24:27], v[194:197], v[226:229], v[24:27]
	v_mfma_f32_16x16x32_bf16 v[16:19], v[202:205], v[226:229], v[16:19]
	v_mfma_f32_16x16x32_bf16 v[8:11], v[194:197], v[234:237], v[8:11]
	v_mfma_f32_16x16x32_bf16 v[0:3], v[202:205], v[234:237], v[0:3]
	s_setprio 0
	s_barrier
	s_add_i32 s6, 0, 0x18000
	s_add_i32 s7, 0, 0x1c000
	v_add_u32_e32 v186, s6, v167
	v_add_u32_e32 v202, s7, v167
	ds_read_b128 v[172:175], v186
	ds_read_b128 v[178:181], v186 offset:1024
	ds_read_b128 v[182:185], v186 offset:2048
	ds_read_b128 v[186:189], v186 offset:3072
	ds_read_b128 v[190:193], v202
	ds_read_b128 v[194:197], v202 offset:1024
	ds_read_b128 v[198:201], v202 offset:2048
	ds_read_b128 v[202:205], v202 offset:3072
	v_lshl_add_u64 v[238:239], v[238:239], 0, s[8:9]
	s_mov_b32 m0, s34
	v_lshl_add_u64 v[250:251], v[238:239], 0, v[134:135]
	ds_read_b128 v[206:209], v170 offset:32768
	ds_read_b128 v[210:213], v170 offset:33792
	ds_read_b128 v[214:217], v170 offset:34816
	ds_read_b128 v[218:221], v170 offset:35840
	ds_read_b128 v[222:225], v170 offset:36864
	ds_read_b128 v[226:229], v170 offset:37888
	ds_read_b128 v[230:233], v170 offset:38912
	ds_read_b128 v[234:237], v170 offset:39936
	global_load_lds_dwordx4 v[250:251], off
	v_lshl_add_u64 v[238:239], v[238:239], 0, v[138:139]
	s_mov_b32 m0, s35
	s_nop 0
	global_load_lds_dwordx4 v[238:239], off
	s_waitcnt vmcnt(8)
	s_waitcnt lgkmcnt(0)
	s_barrier
	s_setprio 1
	v_mfma_f32_16x16x32_bf16 v[124:127], v[172:175], v[206:209], v[124:127]
	v_mfma_f32_16x16x32_bf16 v[116:119], v[182:185], v[206:209], v[116:119]
	v_mfma_f32_16x16x32_bf16 v[108:111], v[172:175], v[214:217], v[108:111]
	v_mfma_f32_16x16x32_bf16 v[100:103], v[182:185], v[214:217], v[100:103]
	v_mfma_f32_16x16x32_bf16 v[92:95], v[172:175], v[222:225], v[92:95]
	v_mfma_f32_16x16x32_bf16 v[84:87], v[182:185], v[222:225], v[84:87]
	v_mfma_f32_16x16x32_bf16 v[76:79], v[172:175], v[230:233], v[76:79]
	v_mfma_f32_16x16x32_bf16 v[68:71], v[182:185], v[230:233], v[68:71]
	v_mfma_f32_16x16x32_bf16 v[124:127], v[178:181], v[210:213], v[124:127]
	v_mfma_f32_16x16x32_bf16 v[116:119], v[186:189], v[210:213], v[116:119]
	v_mfma_f32_16x16x32_bf16 v[108:111], v[178:181], v[218:221], v[108:111]
	v_mfma_f32_16x16x32_bf16 v[100:103], v[186:189], v[218:221], v[100:103]
	v_mfma_f32_16x16x32_bf16 v[92:95], v[178:181], v[226:229], v[92:95]
	v_mfma_f32_16x16x32_bf16 v[84:87], v[186:189], v[226:229], v[84:87]
	v_mfma_f32_16x16x32_bf16 v[76:79], v[178:181], v[234:237], v[76:79]
	v_mfma_f32_16x16x32_bf16 v[68:71], v[186:189], v[234:237], v[68:71]
	v_mfma_f32_16x16x32_bf16 v[120:123], v[190:193], v[206:209], v[120:123]
	v_mfma_f32_16x16x32_bf16 v[112:115], v[198:201], v[206:209], v[112:115]
	v_mfma_f32_16x16x32_bf16 v[104:107], v[190:193], v[214:217], v[104:107]
	v_mfma_f32_16x16x32_bf16 v[96:99], v[198:201], v[214:217], v[96:99]
	v_mfma_f32_16x16x32_bf16 v[88:91], v[190:193], v[222:225], v[88:91]
	v_mfma_f32_16x16x32_bf16 v[80:83], v[198:201], v[222:225], v[80:83]
	v_mfma_f32_16x16x32_bf16 v[72:75], v[190:193], v[230:233], v[72:75]
	v_mfma_f32_16x16x32_bf16 v[64:67], v[198:201], v[230:233], v[64:67]
	v_mfma_f32_16x16x32_bf16 v[120:123], v[194:197], v[210:213], v[120:123]
	v_mfma_f32_16x16x32_bf16 v[112:115], v[202:205], v[210:213], v[112:115]
	v_mfma_f32_16x16x32_bf16 v[104:107], v[194:197], v[218:221], v[104:107]
	v_mfma_f32_16x16x32_bf16 v[96:99], v[202:205], v[218:221], v[96:99]
	v_mfma_f32_16x16x32_bf16 v[88:91], v[194:197], v[226:229], v[88:91]
	v_mfma_f32_16x16x32_bf16 v[80:83], v[202:205], v[226:229], v[80:83]
	v_mfma_f32_16x16x32_bf16 v[72:75], v[194:197], v[234:237], v[72:75]
	v_mfma_f32_16x16x32_bf16 v[64:67], v[202:205], v[234:237], v[64:67]
	s_setprio 0
	s_barrier
	s_add_i32 s6, s6, s3
	v_lshl_add_u64 v[238:239], v[242:243], 0, s[12:13]
	s_mov_b32 m0, s6
	ds_read_b128 v[206:209], v170 offset:49152
	ds_read_b128 v[210:213], v170 offset:50176
	ds_read_b128 v[214:217], v170 offset:51200
	ds_read_b128 v[218:221], v170 offset:52224
	ds_read_b128 v[222:225], v170 offset:53248
	ds_read_b128 v[226:229], v170 offset:54272
	ds_read_b128 v[230:233], v170 offset:55296
	ds_read_b128 v[234:237], v170 offset:56320
	global_load_lds_dwordx4 v[238:239], off
	v_lshl_add_u64 v[238:239], v[244:245], 0, s[12:13]
	s_add_i32 m0, s6, 0x2000
	s_add_i32 s6, s7, s3
	global_load_lds_dwordx4 v[238:239], off
	v_lshl_add_u64 v[238:239], v[240:241], 0, s[14:15]
	v_lshl_add_u64 v[240:241], v[238:239], 0, v[136:137]
	s_mov_b32 m0, s6
	v_lshl_add_u64 v[238:239], v[238:239], 0, v[140:141]
	global_load_lds_dwordx4 v[240:241], off
	s_add_i32 m0, s6, 0x2000
	s_nop 0
	global_load_lds_dwordx4 v[238:239], off
	v_lshl_add_u64 v[238:239], v[246:247], 0, s[12:13]
	s_mov_b32 m0, s36
	s_nop 0
	global_load_lds_dwordx4 v[238:239], off
	v_lshl_add_u64 v[238:239], v[248:249], 0, s[12:13]
	s_mov_b32 m0, s37
	s_nop 0
	global_load_lds_dwordx4 v[238:239], off
	s_waitcnt vmcnt(8)
	s_waitcnt lgkmcnt(0)
	s_barrier
	s_setprio 1
	v_mfma_f32_16x16x32_bf16 v[60:63], v[172:175], v[206:209], v[60:63]
	v_mfma_f32_16x16x32_bf16 v[52:55], v[182:185], v[206:209], v[52:55]
	v_mfma_f32_16x16x32_bf16 v[44:47], v[172:175], v[214:217], v[44:47]
	v_mfma_f32_16x16x32_bf16 v[36:39], v[182:185], v[214:217], v[36:39]
	v_mfma_f32_16x16x32_bf16 v[28:31], v[172:175], v[222:225], v[28:31]
	v_mfma_f32_16x16x32_bf16 v[20:23], v[182:185], v[222:225], v[20:23]
	v_mfma_f32_16x16x32_bf16 v[12:15], v[172:175], v[230:233], v[12:15]
	v_mfma_f32_16x16x32_bf16 v[4:7], v[182:185], v[230:233], v[4:7]
	v_mfma_f32_16x16x32_bf16 v[60:63], v[178:181], v[210:213], v[60:63]
	v_mfma_f32_16x16x32_bf16 v[52:55], v[186:189], v[210:213], v[52:55]
	v_mfma_f32_16x16x32_bf16 v[44:47], v[178:181], v[218:221], v[44:47]
	v_mfma_f32_16x16x32_bf16 v[36:39], v[186:189], v[218:221], v[36:39]
	v_mfma_f32_16x16x32_bf16 v[28:31], v[178:181], v[226:229], v[28:31]
	v_mfma_f32_16x16x32_bf16 v[20:23], v[186:189], v[226:229], v[20:23]
	v_mfma_f32_16x16x32_bf16 v[12:15], v[178:181], v[234:237], v[12:15]
	v_mfma_f32_16x16x32_bf16 v[4:7], v[186:189], v[234:237], v[4:7]
	v_mfma_f32_16x16x32_bf16 v[56:59], v[190:193], v[206:209], v[56:59]
	v_mfma_f32_16x16x32_bf16 v[48:51], v[198:201], v[206:209], v[48:51]
	v_mfma_f32_16x16x32_bf16 v[40:43], v[190:193], v[214:217], v[40:43]
	v_mfma_f32_16x16x32_bf16 v[32:35], v[198:201], v[214:217], v[32:35]
	v_mfma_f32_16x16x32_bf16 v[24:27], v[190:193], v[222:225], v[24:27]
	v_mfma_f32_16x16x32_bf16 v[16:19], v[198:201], v[222:225], v[16:19]
	v_mfma_f32_16x16x32_bf16 v[8:11], v[190:193], v[230:233], v[8:11]
	v_mfma_f32_16x16x32_bf16 v[0:3], v[198:201], v[230:233], v[0:3]
	v_mfma_f32_16x16x32_bf16 v[56:59], v[194:197], v[210:213], v[56:59]
	v_mfma_f32_16x16x32_bf16 v[48:51], v[202:205], v[210:213], v[48:51]
	v_mfma_f32_16x16x32_bf16 v[40:43], v[194:197], v[218:221], v[40:43]
	v_mfma_f32_16x16x32_bf16 v[32:35], v[202:205], v[218:221], v[32:35]
	v_mfma_f32_16x16x32_bf16 v[24:27], v[194:197], v[226:229], v[24:27]
	v_mfma_f32_16x16x32_bf16 v[16:19], v[202:205], v[226:229], v[16:19]
	v_mfma_f32_16x16x32_bf16 v[8:11], v[194:197], v[234:237], v[8:11]
	v_mfma_f32_16x16x32_bf16 v[0:3], v[202:205], v[234:237], v[0:3]
	s_setprio 0
	s_barrier
	s_add_i32 s27, s27, 2
	v_lshl_add_u64 v[160:161], v[160:161], 0, s[18:19]
	s_cmp_gt_u32 s27, 13
	v_lshl_add_u64 v[162:163], v[162:163], 0, s[18:19]
	s_cbranch_scc1 .LBB0_74

.LBB0_147:
	ds_read_b128 v[120:123], v221
	ds_read_b128 v[124:127], v221 offset:1024
	ds_read_b128 v[144:147], v221 offset:2048
	ds_read_b128 v[148:151], v221 offset:3072
	ds_read_b128 v[152:155], v222
	ds_read_b128 v[156:159], v222 offset:1024
	ds_read_b128 v[160:163], v222 offset:2048
	ds_read_b128 v[164:167], v222 offset:3072
	s_cmp_eq_u32 s8, 40
	v_lshl_add_u64 v[108:109], v[106:107], 0, s[28:29]
	s_cselect_b64 vcc, -1, 0
	v_cndmask_b32_e32 v215, v109, v199, vcc
	v_cndmask_b32_e32 v214, v108, v198, vcc
	v_cndmask_b32_e32 v241, v105, v201, vcc
	v_cndmask_b32_e32 v240, v104, v200, vcc
	s_mov_b32 m0, s66
	v_lshl_add_u64 v[110:111], v[106:107], 0, v[192:193]
	ds_read_b128 v[168:171], v223
	ds_read_b128 v[172:175], v223 offset:1024
	ds_read_b128 v[202:205], v223 offset:2048
	ds_read_b128 v[206:209], v223 offset:3072
	ds_read_b128 v[210:213], v223 offset:4096
	ds_read_b128 v[228:231], v223 offset:5120
	ds_read_b128 v[232:235], v223 offset:6144
	ds_read_b128 v[236:239], v223 offset:7168
	global_load_lds_dwordx4 v[110:111], off
	v_lshl_add_u64 v[106:107], v[106:107], 0, v[190:191]
	s_mov_b32 m0, s67
	s_nop 0
	global_load_lds_dwordx4 v[106:107], off
	s_waitcnt vmcnt(8)
	s_waitcnt lgkmcnt(0)
	s_barrier
	s_setprio 1
	v_mfma_f32_16x16x32_bf16 v[140:143], v[120:123], v[168:171], v[140:143]
	v_mfma_f32_16x16x32_bf16 v[136:139], v[144:147], v[168:171], v[136:139]
	v_mfma_f32_16x16x32_bf16 v[116:119], v[120:123], v[202:205], v[116:119]
	v_mfma_f32_16x16x32_bf16 v[110:113], v[144:147], v[202:205], v[112:115]
	v_mfma_f32_16x16x32_bf16 v[92:95], v[120:123], v[210:213], v[92:95]
	v_mfma_f32_16x16x32_bf16 v[88:91], v[144:147], v[210:213], v[88:91]
	v_mfma_f32_16x16x32_bf16 v[76:79], v[120:123], v[232:235], v[76:79]
	v_mfma_f32_16x16x32_bf16 v[72:75], v[144:147], v[232:235], v[72:75]
	v_mfma_f32_16x16x32_bf16 v[140:143], v[124:127], v[172:175], v[140:143]
	v_mfma_f32_16x16x32_bf16 v[136:139], v[148:151], v[172:175], v[136:139]
	v_mfma_f32_16x16x32_bf16 v[116:119], v[124:127], v[206:209], v[116:119]
	v_mfma_f32_16x16x32_bf16 v[110:113], v[148:151], v[206:209], v[110:113]
	v_mfma_f32_16x16x32_bf16 v[92:95], v[124:127], v[228:231], v[92:95]
	v_mfma_f32_16x16x32_bf16 v[88:91], v[148:151], v[228:231], v[88:91]
	v_mfma_f32_16x16x32_bf16 v[76:79], v[124:127], v[236:239], v[76:79]
	v_mfma_f32_16x16x32_bf16 v[72:75], v[148:151], v[236:239], v[72:75]
	v_mfma_f32_16x16x32_bf16 v[132:135], v[152:155], v[168:171], v[132:135]
	v_mfma_f32_16x16x32_bf16 v[128:131], v[160:163], v[168:171], v[128:131]
	v_mfma_f32_16x16x32_bf16 v[100:103], v[152:155], v[202:205], v[100:103]
	v_mfma_f32_16x16x32_bf16 v[96:99], v[160:163], v[202:205], v[96:99]
	v_mfma_f32_16x16x32_bf16 v[84:87], v[152:155], v[210:213], v[84:87]
	v_mfma_f32_16x16x32_bf16 v[80:83], v[160:163], v[210:213], v[80:83]
	v_mfma_f32_16x16x32_bf16 v[68:71], v[152:155], v[232:235], v[68:71]
	v_mfma_f32_16x16x32_bf16 v[64:67], v[160:163], v[232:235], v[64:67]
	v_mfma_f32_16x16x32_bf16 v[132:135], v[156:159], v[172:175], v[132:135]
	v_mfma_f32_16x16x32_bf16 v[128:131], v[164:167], v[172:175], v[128:131]
	v_mfma_f32_16x16x32_bf16 v[100:103], v[156:159], v[206:209], v[100:103]
	v_mfma_f32_16x16x32_bf16 v[96:99], v[164:167], v[206:209], v[96:99]
	v_mfma_f32_16x16x32_bf16 v[84:87], v[156:159], v[228:231], v[84:87]
	v_mfma_f32_16x16x32_bf16 v[80:83], v[164:167], v[228:231], v[80:83]
	v_mfma_f32_16x16x32_bf16 v[68:71], v[156:159], v[236:239], v[68:71]
	v_mfma_f32_16x16x32_bf16 v[64:67], v[164:167], v[236:239], v[64:67]
	s_setprio 0
	s_barrier
	s_mov_b32 m0, s69
	v_lshl_add_u64 v[106:107], v[240:241], 0, v[184:185]
	ds_read_b128 v[168:171], v223 offset:16384
	ds_read_b128 v[172:175], v223 offset:17408
	ds_read_b128 v[202:205], v223 offset:18432
	ds_read_b128 v[206:209], v223 offset:19456
	ds_read_b128 v[210:213], v223 offset:20480
	ds_read_b128 v[228:231], v223 offset:21504
	ds_read_b128 v[232:235], v223 offset:22528
	ds_read_b128 v[236:239], v223 offset:23552
	global_load_lds_dwordx4 v[106:107], off
	v_lshl_add_u64 v[242:243], v[240:241], 0, v[188:189]
	s_mov_b32 m0, s70
	v_lshl_add_u64 v[114:115], v[240:241], 0, s[14:15]
	s_add_i32 s9, s65, s3
	global_load_lds_dwordx4 v[242:243], off
	v_lshl_add_u64 v[244:245], v[114:115], 0, v[184:185]
	s_mov_b32 m0, s9
	v_lshl_add_u64 v[114:115], v[114:115], 0, v[188:189]
	global_load_lds_dwordx4 v[244:245], off
	s_add_i32 m0, s9, 0x2000
	v_lshl_add_u64 v[244:245], v[214:215], 0, v[182:183]
	global_load_lds_dwordx4 v[114:115], off
	s_mov_b32 m0, s42
	v_lshl_add_u64 v[246:247], v[214:215], 0, v[186:187]
	global_load_lds_dwordx4 v[244:245], off
	s_mov_b32 m0, s43
	s_nop 0
	global_load_lds_dwordx4 v[246:247], off
	s_waitcnt vmcnt(8)
	s_waitcnt lgkmcnt(0)
	s_barrier
	s_setprio 1
	v_mfma_f32_16x16x32_bf16 v[60:63], v[120:123], v[168:171], v[60:63]
	v_mfma_f32_16x16x32_bf16 v[56:59], v[144:147], v[168:171], v[56:59]
	v_mfma_f32_16x16x32_bf16 v[44:47], v[120:123], v[202:205], v[44:47]
	v_mfma_f32_16x16x32_bf16 v[40:43], v[144:147], v[202:205], v[40:43]
	v_mfma_f32_16x16x32_bf16 v[28:31], v[120:123], v[210:213], v[28:31]
	v_mfma_f32_16x16x32_bf16 v[24:27], v[144:147], v[210:213], v[24:27]
	v_mfma_f32_16x16x32_bf16 v[12:15], v[120:123], v[232:235], v[12:15]
	v_mfma_f32_16x16x32_bf16 v[8:11], v[144:147], v[232:235], v[8:11]
	v_mfma_f32_16x16x32_bf16 v[60:63], v[124:127], v[172:175], v[60:63]
	v_mfma_f32_16x16x32_bf16 v[56:59], v[148:151], v[172:175], v[56:59]
	v_mfma_f32_16x16x32_bf16 v[44:47], v[124:127], v[206:209], v[44:47]
	v_mfma_f32_16x16x32_bf16 v[40:43], v[148:151], v[206:209], v[40:43]
	v_mfma_f32_16x16x32_bf16 v[28:31], v[124:127], v[228:231], v[28:31]
	v_mfma_f32_16x16x32_bf16 v[24:27], v[148:151], v[228:231], v[24:27]
	v_mfma_f32_16x16x32_bf16 v[12:15], v[124:127], v[236:239], v[12:15]
	v_mfma_f32_16x16x32_bf16 v[8:11], v[148:151], v[236:239], v[8:11]
	v_mfma_f32_16x16x32_bf16 v[52:55], v[152:155], v[168:171], v[52:55]
	v_mfma_f32_16x16x32_bf16 v[48:51], v[160:163], v[168:171], v[48:51]
	v_mfma_f32_16x16x32_bf16 v[36:39], v[152:155], v[202:205], v[36:39]
	v_mfma_f32_16x16x32_bf16 v[32:35], v[160:163], v[202:205], v[32:35]
	v_mfma_f32_16x16x32_bf16 v[20:23], v[152:155], v[210:213], v[20:23]
	v_mfma_f32_16x16x32_bf16 v[16:19], v[160:163], v[210:213], v[16:19]
	v_mfma_f32_16x16x32_bf16 v[4:7], v[152:155], v[232:235], v[4:7]
	v_mfma_f32_16x16x32_bf16 v[0:3], v[160:163], v[232:235], v[0:3]
	v_mfma_f32_16x16x32_bf16 v[52:55], v[156:159], v[172:175], v[52:55]
	v_mfma_f32_16x16x32_bf16 v[48:51], v[164:167], v[172:175], v[48:51]
	v_mfma_f32_16x16x32_bf16 v[36:39], v[156:159], v[206:209], v[36:39]
	v_mfma_f32_16x16x32_bf16 v[32:35], v[164:167], v[206:209], v[32:35]
	v_mfma_f32_16x16x32_bf16 v[20:23], v[156:159], v[228:231], v[20:23]
	v_mfma_f32_16x16x32_bf16 v[16:19], v[164:167], v[228:231], v[16:19]
	v_mfma_f32_16x16x32_bf16 v[4:7], v[156:159], v[236:239], v[4:7]
	v_mfma_f32_16x16x32_bf16 v[0:3], v[164:167], v[236:239], v[0:3]
	s_setprio 0
	s_barrier
	s_add_i32 s9, 0, 0x18000
	v_add_u32_e32 v114, s9, v220
	s_add_i32 s11, 0, 0x1c000
	ds_read_b128 v[120:123], v114
	ds_read_b128 v[124:127], v114 offset:1024
	ds_read_b128 v[144:147], v114 offset:2048
	ds_read_b128 v[148:151], v114 offset:3072
	v_add_u32_e32 v114, s11, v220
	ds_read_b128 v[152:155], v114
	ds_read_b128 v[156:159], v114 offset:1024
	ds_read_b128 v[160:163], v114 offset:2048
	ds_read_b128 v[164:167], v114 offset:3072
	v_lshl_add_u64 v[114:115], v[214:215], 0, s[14:15]
	s_mov_b32 m0, s44
	v_lshl_add_u64 v[214:215], v[114:115], 0, v[182:183]
	ds_read_b128 v[168:171], v223 offset:32768
	ds_read_b128 v[172:175], v223 offset:33792
	ds_read_b128 v[202:205], v223 offset:34816
	ds_read_b128 v[206:209], v223 offset:35840
	ds_read_b128 v[210:213], v223 offset:36864
	ds_read_b128 v[228:231], v223 offset:37888
	ds_read_b128 v[232:235], v223 offset:38912
	ds_read_b128 v[236:239], v223 offset:39936
	global_load_lds_dwordx4 v[214:215], off
	v_lshl_add_u64 v[114:115], v[114:115], 0, v[186:187]
	s_mov_b32 m0, s45
	s_nop 0
	global_load_lds_dwordx4 v[114:115], off
	s_waitcnt vmcnt(8)
	s_waitcnt lgkmcnt(0)
	s_barrier
	s_setprio 1
	v_mfma_f32_16x16x32_bf16 v[140:143], v[120:123], v[168:171], v[140:143]
	v_mfma_f32_16x16x32_bf16 v[136:139], v[144:147], v[168:171], v[136:139]
	v_mfma_f32_16x16x32_bf16 v[114:117], v[120:123], v[202:205], v[116:119]
	v_mfma_f32_16x16x32_bf16 v[110:113], v[144:147], v[202:205], v[110:113]
	v_mfma_f32_16x16x32_bf16 v[92:95], v[120:123], v[210:213], v[92:95]
	v_mfma_f32_16x16x32_bf16 v[88:91], v[144:147], v[210:213], v[88:91]
	v_mfma_f32_16x16x32_bf16 v[76:79], v[120:123], v[232:235], v[76:79]
	v_mfma_f32_16x16x32_bf16 v[72:75], v[144:147], v[232:235], v[72:75]
	v_mfma_f32_16x16x32_bf16 v[140:143], v[124:127], v[172:175], v[140:143]
	v_mfma_f32_16x16x32_bf16 v[136:139], v[148:151], v[172:175], v[136:139]
	v_mfma_f32_16x16x32_bf16 v[116:119], v[124:127], v[206:209], v[114:117]
	v_mfma_f32_16x16x32_bf16 v[112:115], v[148:151], v[206:209], v[110:113]
	v_mfma_f32_16x16x32_bf16 v[92:95], v[124:127], v[228:231], v[92:95]
	v_mfma_f32_16x16x32_bf16 v[88:91], v[148:151], v[228:231], v[88:91]
	v_mfma_f32_16x16x32_bf16 v[76:79], v[124:127], v[236:239], v[76:79]
	v_mfma_f32_16x16x32_bf16 v[72:75], v[148:151], v[236:239], v[72:75]
	v_mfma_f32_16x16x32_bf16 v[132:135], v[152:155], v[168:171], v[132:135]
	v_mfma_f32_16x16x32_bf16 v[128:131], v[160:163], v[168:171], v[128:131]
	v_mfma_f32_16x16x32_bf16 v[100:103], v[152:155], v[202:205], v[100:103]
	v_mfma_f32_16x16x32_bf16 v[96:99], v[160:163], v[202:205], v[96:99]
	v_mfma_f32_16x16x32_bf16 v[84:87], v[152:155], v[210:213], v[84:87]
	v_mfma_f32_16x16x32_bf16 v[80:83], v[160:163], v[210:213], v[80:83]
	v_mfma_f32_16x16x32_bf16 v[68:71], v[152:155], v[232:235], v[68:71]
	v_mfma_f32_16x16x32_bf16 v[64:67], v[160:163], v[232:235], v[64:67]
	v_mfma_f32_16x16x32_bf16 v[132:135], v[156:159], v[172:175], v[132:135]
	v_mfma_f32_16x16x32_bf16 v[128:131], v[164:167], v[172:175], v[128:131]
	v_mfma_f32_16x16x32_bf16 v[100:103], v[156:159], v[206:209], v[100:103]
	v_mfma_f32_16x16x32_bf16 v[96:99], v[164:167], v[206:209], v[96:99]
	v_mfma_f32_16x16x32_bf16 v[84:87], v[156:159], v[228:231], v[84:87]
	v_mfma_f32_16x16x32_bf16 v[80:83], v[164:167], v[228:231], v[80:83]
	v_mfma_f32_16x16x32_bf16 v[68:71], v[156:159], v[236:239], v[68:71]
	v_mfma_f32_16x16x32_bf16 v[64:67], v[164:167], v[236:239], v[64:67]
	s_setprio 0
	s_barrier
	s_add_i32 s9, s9, s3
	v_lshl_add_u64 v[106:107], v[106:107], 0, s[20:21]
	s_mov_b32 m0, s9
	ds_read_b128 v[168:171], v223 offset:49152
	ds_read_b128 v[172:175], v223 offset:50176
	ds_read_b128 v[202:205], v223 offset:51200
	ds_read_b128 v[206:209], v223 offset:52224
	ds_read_b128 v[210:213], v223 offset:53248
	ds_read_b128 v[228:231], v223 offset:54272
	ds_read_b128 v[232:235], v223 offset:55296
	ds_read_b128 v[236:239], v223 offset:56320
	global_load_lds_dwordx4 v[106:107], off
	v_lshl_add_u64 v[106:107], v[242:243], 0, s[20:21]
	s_add_i32 m0, s9, 0x2000
	s_add_i32 s9, s11, s3
	global_load_lds_dwordx4 v[106:107], off
	v_lshl_add_u64 v[106:107], v[240:241], 0, s[22:23]
	v_lshl_add_u64 v[110:111], v[106:107], 0, v[184:185]
	s_mov_b32 m0, s9
	v_lshl_add_u64 v[106:107], v[106:107], 0, v[188:189]
	global_load_lds_dwordx4 v[110:111], off
	s_add_i32 m0, s9, 0x2000
	s_nop 0
	global_load_lds_dwordx4 v[106:107], off
	v_lshl_add_u64 v[106:107], v[244:245], 0, s[20:21]
	s_mov_b32 m0, s61
	s_nop 0
	global_load_lds_dwordx4 v[106:107], off
	v_lshl_add_u64 v[106:107], v[246:247], 0, s[20:21]
	s_mov_b32 m0, s62
	s_nop 0
	global_load_lds_dwordx4 v[106:107], off
	s_waitcnt vmcnt(8)
	s_waitcnt lgkmcnt(0)
	s_barrier
	s_setprio 1
	v_mfma_f32_16x16x32_bf16 v[60:63], v[120:123], v[168:171], v[60:63]
	v_mfma_f32_16x16x32_bf16 v[56:59], v[144:147], v[168:171], v[56:59]
	v_mfma_f32_16x16x32_bf16 v[44:47], v[120:123], v[202:205], v[44:47]
	v_mfma_f32_16x16x32_bf16 v[40:43], v[144:147], v[202:205], v[40:43]
	v_mfma_f32_16x16x32_bf16 v[28:31], v[120:123], v[210:213], v[28:31]
	v_mfma_f32_16x16x32_bf16 v[24:27], v[144:147], v[210:213], v[24:27]
	v_mfma_f32_16x16x32_bf16 v[12:15], v[120:123], v[232:235], v[12:15]
	v_mfma_f32_16x16x32_bf16 v[8:11], v[144:147], v[232:235], v[8:11]
	v_mfma_f32_16x16x32_bf16 v[60:63], v[124:127], v[172:175], v[60:63]
	v_mfma_f32_16x16x32_bf16 v[56:59], v[148:151], v[172:175], v[56:59]
	v_mfma_f32_16x16x32_bf16 v[44:47], v[124:127], v[206:209], v[44:47]
	v_mfma_f32_16x16x32_bf16 v[40:43], v[148:151], v[206:209], v[40:43]
	v_mfma_f32_16x16x32_bf16 v[28:31], v[124:127], v[228:231], v[28:31]
	v_mfma_f32_16x16x32_bf16 v[24:27], v[148:151], v[228:231], v[24:27]
	v_mfma_f32_16x16x32_bf16 v[12:15], v[124:127], v[236:239], v[12:15]
	v_mfma_f32_16x16x32_bf16 v[8:11], v[148:151], v[236:239], v[8:11]
	v_mfma_f32_16x16x32_bf16 v[52:55], v[152:155], v[168:171], v[52:55]
	v_mfma_f32_16x16x32_bf16 v[48:51], v[160:163], v[168:171], v[48:51]
	v_mfma_f32_16x16x32_bf16 v[36:39], v[152:155], v[202:205], v[36:39]
	v_mfma_f32_16x16x32_bf16 v[32:35], v[160:163], v[202:205], v[32:35]
	v_mfma_f32_16x16x32_bf16 v[20:23], v[152:155], v[210:213], v[20:23]
	v_mfma_f32_16x16x32_bf16 v[16:19], v[160:163], v[210:213], v[16:19]
	v_mfma_f32_16x16x32_bf16 v[4:7], v[152:155], v[232:235], v[4:7]
	v_mfma_f32_16x16x32_bf16 v[0:3], v[160:163], v[232:235], v[0:3]
	v_mfma_f32_16x16x32_bf16 v[52:55], v[156:159], v[172:175], v[52:55]
	v_mfma_f32_16x16x32_bf16 v[48:51], v[164:167], v[172:175], v[48:51]
	v_mfma_f32_16x16x32_bf16 v[36:39], v[156:159], v[206:209], v[36:39]
	v_mfma_f32_16x16x32_bf16 v[32:35], v[164:167], v[206:209], v[32:35]
	v_mfma_f32_16x16x32_bf16 v[20:23], v[156:159], v[228:231], v[20:23]
	v_mfma_f32_16x16x32_bf16 v[16:19], v[164:167], v[228:231], v[16:19]
	v_mfma_f32_16x16x32_bf16 v[4:7], v[156:159], v[236:239], v[4:7]
	v_mfma_f32_16x16x32_bf16 v[0:3], v[164:167], v[236:239], v[0:3]
	s_setprio 0
	s_barrier
	s_add_i32 s8, s8, 2
	v_lshl_add_u64 v[104:105], v[104:105], 0, s[28:29]
	s_cmp_gt_u32 s8, 41
	v_mov_b64_e32 v[106:107], v[108:109]
	s_cbranch_scc0 .LBB0_147
	s_and_b64 vcc, exec, s[26:27]
	s_cbranch_vccz .LBB0_150
	s_barrier

.LBB0_258:
	v_add_u32_e32 v186, s42, v167
	v_add_u32_e32 v202, s43, v167
	ds_read_b128 v[172:175], v186
	ds_read_b128 v[178:181], v186 offset:1024
	ds_read_b128 v[182:185], v186 offset:2048
	ds_read_b128 v[186:189], v186 offset:3072
	ds_read_b128 v[190:193], v202
	ds_read_b128 v[194:197], v202 offset:1024
	ds_read_b128 v[198:201], v202 offset:2048
	ds_read_b128 v[202:205], v202 offset:3072
	v_lshl_add_u64 v[206:207], v[164:165], 0, s[22:23]
	v_cndmask_b32_e64 v239, v207, v157, s[8:9]
	v_cndmask_b32_e64 v238, v206, v156, s[8:9]
	v_cndmask_b32_e64 v241, v163, v159, s[8:9]
	v_cndmask_b32_e64 v240, v162, v158, s[8:9]
	s_mov_b32 m0, s44
	v_lshl_add_u64 v[242:243], v[164:165], 0, v[146:147]
	ds_read_b128 v[206:209], v170
	ds_read_b128 v[210:213], v170 offset:1024
	ds_read_b128 v[214:217], v170 offset:2048
	ds_read_b128 v[218:221], v170 offset:3072
	ds_read_b128 v[222:225], v170 offset:4096
	ds_read_b128 v[226:229], v170 offset:5120
	ds_read_b128 v[230:233], v170 offset:6144
	ds_read_b128 v[234:237], v170 offset:7168
	global_load_lds_dwordx4 v[242:243], off
	v_lshl_add_u64 v[242:243], v[164:165], 0, v[144:145]
	s_mov_b32 m0, s45
	s_nop 0
	global_load_lds_dwordx4 v[242:243], off
	s_waitcnt vmcnt(8)
	s_waitcnt lgkmcnt(0)
	s_barrier
	s_setprio 1
	v_mfma_f32_16x16x32_bf16 v[124:127], v[172:175], v[206:209], v[124:127]
	v_mfma_f32_16x16x32_bf16 v[120:123], v[182:185], v[206:209], v[120:123]
	v_mfma_f32_16x16x32_bf16 v[108:111], v[172:175], v[214:217], v[108:111]
	v_mfma_f32_16x16x32_bf16 v[104:107], v[182:185], v[214:217], v[104:107]
	v_mfma_f32_16x16x32_bf16 v[92:95], v[172:175], v[222:225], v[92:95]
	v_mfma_f32_16x16x32_bf16 v[88:91], v[182:185], v[222:225], v[88:91]
	v_mfma_f32_16x16x32_bf16 v[76:79], v[172:175], v[230:233], v[76:79]
	v_mfma_f32_16x16x32_bf16 v[72:75], v[182:185], v[230:233], v[72:75]
	v_mfma_f32_16x16x32_bf16 v[124:127], v[178:181], v[210:213], v[124:127]
	v_mfma_f32_16x16x32_bf16 v[120:123], v[186:189], v[210:213], v[120:123]
	v_mfma_f32_16x16x32_bf16 v[108:111], v[178:181], v[218:221], v[108:111]
	v_mfma_f32_16x16x32_bf16 v[104:107], v[186:189], v[218:221], v[104:107]
	v_mfma_f32_16x16x32_bf16 v[92:95], v[178:181], v[226:229], v[92:95]
	v_mfma_f32_16x16x32_bf16 v[88:91], v[186:189], v[226:229], v[88:91]
	v_mfma_f32_16x16x32_bf16 v[76:79], v[178:181], v[234:237], v[76:79]
	v_mfma_f32_16x16x32_bf16 v[72:75], v[186:189], v[234:237], v[72:75]
	v_mfma_f32_16x16x32_bf16 v[116:119], v[190:193], v[206:209], v[116:119]
	v_mfma_f32_16x16x32_bf16 v[112:115], v[198:201], v[206:209], v[112:115]
	v_mfma_f32_16x16x32_bf16 v[100:103], v[190:193], v[214:217], v[100:103]
	v_mfma_f32_16x16x32_bf16 v[96:99], v[198:201], v[214:217], v[96:99]
	v_mfma_f32_16x16x32_bf16 v[84:87], v[190:193], v[222:225], v[84:87]
	v_mfma_f32_16x16x32_bf16 v[80:83], v[198:201], v[222:225], v[80:83]
	v_mfma_f32_16x16x32_bf16 v[68:71], v[190:193], v[230:233], v[68:71]
	v_mfma_f32_16x16x32_bf16 v[64:67], v[198:201], v[230:233], v[64:67]
	v_mfma_f32_16x16x32_bf16 v[116:119], v[194:197], v[210:213], v[116:119]
	v_mfma_f32_16x16x32_bf16 v[112:115], v[202:205], v[210:213], v[112:115]
	v_mfma_f32_16x16x32_bf16 v[100:103], v[194:197], v[218:221], v[100:103]
	v_mfma_f32_16x16x32_bf16 v[96:99], v[202:205], v[218:221], v[96:99]
	v_mfma_f32_16x16x32_bf16 v[84:87], v[194:197], v[226:229], v[84:87]
	v_mfma_f32_16x16x32_bf16 v[80:83], v[202:205], v[226:229], v[80:83]
	v_mfma_f32_16x16x32_bf16 v[68:71], v[194:197], v[234:237], v[68:71]
	v_mfma_f32_16x16x32_bf16 v[64:67], v[202:205], v[234:237], v[64:67]
	s_setprio 0
	s_barrier
	s_add_i32 s8, s42, s3
	v_lshl_add_u64 v[242:243], v[240:241], 0, v[134:135]
	s_mov_b32 m0, s8
	ds_read_b128 v[206:209], v170 offset:16384
	ds_read_b128 v[210:213], v170 offset:17408
	ds_read_b128 v[214:217], v170 offset:18432
	ds_read_b128 v[218:221], v170 offset:19456
	ds_read_b128 v[222:225], v170 offset:20480
	ds_read_b128 v[226:229], v170 offset:21504
	ds_read_b128 v[230:233], v170 offset:22528
	ds_read_b128 v[234:237], v170 offset:23552
	global_load_lds_dwordx4 v[242:243], off
	v_lshl_add_u64 v[244:245], v[240:241], 0, v[140:141]
	s_add_i32 m0, s8, 0x2000
	v_lshl_add_u64 v[246:247], v[240:241], 0, s[10:11]
	s_add_i32 s8, s43, s3
	global_load_lds_dwordx4 v[244:245], off
	v_lshl_add_u64 v[248:249], v[246:247], 0, v[134:135]
	s_mov_b32 m0, s8
	v_lshl_add_u64 v[246:247], v[246:247], 0, v[140:141]
	global_load_lds_dwordx4 v[248:249], off
	s_add_i32 m0, s8, 0x2000
	v_lshl_add_u64 v[248:249], v[238:239], 0, v[138:139]
	global_load_lds_dwordx4 v[246:247], off
	v_lshl_add_u64 v[246:247], v[238:239], 0, v[136:137]
	s_mov_b32 m0, s31
	s_nop 0
	global_load_lds_dwordx4 v[246:247], off
	s_mov_b32 m0, s34
	s_nop 0
	global_load_lds_dwordx4 v[248:249], off
	s_waitcnt vmcnt(8)
	s_waitcnt lgkmcnt(0)
	s_barrier
	s_setprio 1
	v_mfma_f32_16x16x32_bf16 v[60:63], v[172:175], v[206:209], v[60:63]
	v_mfma_f32_16x16x32_bf16 v[56:59], v[182:185], v[206:209], v[56:59]
	v_mfma_f32_16x16x32_bf16 v[44:47], v[172:175], v[214:217], v[44:47]
	v_mfma_f32_16x16x32_bf16 v[40:43], v[182:185], v[214:217], v[40:43]
	v_mfma_f32_16x16x32_bf16 v[28:31], v[172:175], v[222:225], v[28:31]
	v_mfma_f32_16x16x32_bf16 v[24:27], v[182:185], v[222:225], v[24:27]
	v_mfma_f32_16x16x32_bf16 v[12:15], v[172:175], v[230:233], v[12:15]
	v_mfma_f32_16x16x32_bf16 v[8:11], v[182:185], v[230:233], v[8:11]
	v_mfma_f32_16x16x32_bf16 v[60:63], v[178:181], v[210:213], v[60:63]
	v_mfma_f32_16x16x32_bf16 v[56:59], v[186:189], v[210:213], v[56:59]
	v_mfma_f32_16x16x32_bf16 v[44:47], v[178:181], v[218:221], v[44:47]
	v_mfma_f32_16x16x32_bf16 v[40:43], v[186:189], v[218:221], v[40:43]
	v_mfma_f32_16x16x32_bf16 v[28:31], v[178:181], v[226:229], v[28:31]
	v_mfma_f32_16x16x32_bf16 v[24:27], v[186:189], v[226:229], v[24:27]
	v_mfma_f32_16x16x32_bf16 v[12:15], v[178:181], v[234:237], v[12:15]
	v_mfma_f32_16x16x32_bf16 v[8:11], v[186:189], v[234:237], v[8:11]
	v_mfma_f32_16x16x32_bf16 v[52:55], v[190:193], v[206:209], v[52:55]
	v_mfma_f32_16x16x32_bf16 v[48:51], v[198:201], v[206:209], v[48:51]
	v_mfma_f32_16x16x32_bf16 v[36:39], v[190:193], v[214:217], v[36:39]
	v_mfma_f32_16x16x32_bf16 v[32:35], v[198:201], v[214:217], v[32:35]
	v_mfma_f32_16x16x32_bf16 v[20:23], v[190:193], v[222:225], v[20:23]
	v_mfma_f32_16x16x32_bf16 v[16:19], v[198:201], v[222:225], v[16:19]
	v_mfma_f32_16x16x32_bf16 v[4:7], v[190:193], v[230:233], v[4:7]
	v_mfma_f32_16x16x32_bf16 v[0:3], v[198:201], v[230:233], v[0:3]
	v_mfma_f32_16x16x32_bf16 v[52:55], v[194:197], v[210:213], v[52:55]
	v_mfma_f32_16x16x32_bf16 v[48:51], v[202:205], v[210:213], v[48:51]
	v_mfma_f32_16x16x32_bf16 v[36:39], v[194:197], v[218:221], v[36:39]
	v_mfma_f32_16x16x32_bf16 v[32:35], v[202:205], v[218:221], v[32:35]
	v_mfma_f32_16x16x32_bf16 v[20:23], v[194:197], v[226:229], v[20:23]
	v_mfma_f32_16x16x32_bf16 v[16:19], v[202:205], v[226:229], v[16:19]
	v_mfma_f32_16x16x32_bf16 v[4:7], v[194:197], v[234:237], v[4:7]
	v_mfma_f32_16x16x32_bf16 v[0:3], v[202:205], v[234:237], v[0:3]
	s_setprio 0
	s_barrier
	s_add_i32 s8, 0, 0x18000
	s_add_i32 s9, 0, 0x1c000
	v_add_u32_e32 v186, s8, v167
	v_add_u32_e32 v202, s9, v167
	ds_read_b128 v[172:175], v186
	ds_read_b128 v[178:181], v186 offset:1024
	ds_read_b128 v[182:185], v186 offset:2048
	ds_read_b128 v[186:189], v186 offset:3072
	ds_read_b128 v[190:193], v202
	ds_read_b128 v[194:197], v202 offset:1024
	ds_read_b128 v[198:201], v202 offset:2048
	ds_read_b128 v[202:205], v202 offset:3072
	v_lshl_add_u64 v[238:239], v[238:239], 0, s[10:11]
	s_mov_b32 m0, s35
	v_lshl_add_u64 v[250:251], v[238:239], 0, v[136:137]
	ds_read_b128 v[206:209], v170 offset:32768
	ds_read_b128 v[210:213], v170 offset:33792
	ds_read_b128 v[214:217], v170 offset:34816
	ds_read_b128 v[218:221], v170 offset:35840
	ds_read_b128 v[222:225], v170 offset:36864
	ds_read_b128 v[226:229], v170 offset:37888
	ds_read_b128 v[230:233], v170 offset:38912
	ds_read_b128 v[234:237], v170 offset:39936
	global_load_lds_dwordx4 v[250:251], off
	v_lshl_add_u64 v[238:239], v[238:239], 0, v[138:139]
	s_mov_b32 m0, s36
	s_nop 0
	global_load_lds_dwordx4 v[238:239], off
	s_waitcnt vmcnt(8)
	s_waitcnt lgkmcnt(0)
	s_barrier
	s_setprio 1
	v_mfma_f32_16x16x32_bf16 v[124:127], v[172:175], v[206:209], v[124:127]
	v_mfma_f32_16x16x32_bf16 v[120:123], v[182:185], v[206:209], v[120:123]
	v_mfma_f32_16x16x32_bf16 v[108:111], v[172:175], v[214:217], v[108:111]
	v_mfma_f32_16x16x32_bf16 v[104:107], v[182:185], v[214:217], v[104:107]
	v_mfma_f32_16x16x32_bf16 v[92:95], v[172:175], v[222:225], v[92:95]
	v_mfma_f32_16x16x32_bf16 v[88:91], v[182:185], v[222:225], v[88:91]
	v_mfma_f32_16x16x32_bf16 v[76:79], v[172:175], v[230:233], v[76:79]
	v_mfma_f32_16x16x32_bf16 v[72:75], v[182:185], v[230:233], v[72:75]
	v_mfma_f32_16x16x32_bf16 v[124:127], v[178:181], v[210:213], v[124:127]
	v_mfma_f32_16x16x32_bf16 v[120:123], v[186:189], v[210:213], v[120:123]
	v_mfma_f32_16x16x32_bf16 v[108:111], v[178:181], v[218:221], v[108:111]
	v_mfma_f32_16x16x32_bf16 v[104:107], v[186:189], v[218:221], v[104:107]
	v_mfma_f32_16x16x32_bf16 v[92:95], v[178:181], v[226:229], v[92:95]
	v_mfma_f32_16x16x32_bf16 v[88:91], v[186:189], v[226:229], v[88:91]
	v_mfma_f32_16x16x32_bf16 v[76:79], v[178:181], v[234:237], v[76:79]
	v_mfma_f32_16x16x32_bf16 v[72:75], v[186:189], v[234:237], v[72:75]
	v_mfma_f32_16x16x32_bf16 v[116:119], v[190:193], v[206:209], v[116:119]
	v_mfma_f32_16x16x32_bf16 v[112:115], v[198:201], v[206:209], v[112:115]
	v_mfma_f32_16x16x32_bf16 v[100:103], v[190:193], v[214:217], v[100:103]
	v_mfma_f32_16x16x32_bf16 v[96:99], v[198:201], v[214:217], v[96:99]
	v_mfma_f32_16x16x32_bf16 v[84:87], v[190:193], v[222:225], v[84:87]
	v_mfma_f32_16x16x32_bf16 v[80:83], v[198:201], v[222:225], v[80:83]
	v_mfma_f32_16x16x32_bf16 v[68:71], v[190:193], v[230:233], v[68:71]
	v_mfma_f32_16x16x32_bf16 v[64:67], v[198:201], v[230:233], v[64:67]
	v_mfma_f32_16x16x32_bf16 v[116:119], v[194:197], v[210:213], v[116:119]
	v_mfma_f32_16x16x32_bf16 v[112:115], v[202:205], v[210:213], v[112:115]
	v_mfma_f32_16x16x32_bf16 v[100:103], v[194:197], v[218:221], v[100:103]
	v_mfma_f32_16x16x32_bf16 v[96:99], v[202:205], v[218:221], v[96:99]
	v_mfma_f32_16x16x32_bf16 v[84:87], v[194:197], v[226:229], v[84:87]
	v_mfma_f32_16x16x32_bf16 v[80:83], v[202:205], v[226:229], v[80:83]
	v_mfma_f32_16x16x32_bf16 v[68:71], v[194:197], v[234:237], v[68:71]
	v_mfma_f32_16x16x32_bf16 v[64:67], v[202:205], v[234:237], v[64:67]
	s_setprio 0
	s_barrier
	s_add_i32 s8, s8, s3
	v_lshl_add_u64 v[238:239], v[242:243], 0, s[14:15]
	s_mov_b32 m0, s8
	ds_read_b128 v[206:209], v170 offset:49152
	ds_read_b128 v[210:213], v170 offset:50176
	ds_read_b128 v[214:217], v170 offset:51200
	ds_read_b128 v[218:221], v170 offset:52224
	ds_read_b128 v[222:225], v170 offset:53248
	ds_read_b128 v[226:229], v170 offset:54272
	ds_read_b128 v[230:233], v170 offset:55296
	ds_read_b128 v[234:237], v170 offset:56320
	global_load_lds_dwordx4 v[238:239], off
	v_lshl_add_u64 v[238:239], v[244:245], 0, s[14:15]
	s_add_i32 m0, s8, 0x2000
	s_add_i32 s8, s9, s3
	global_load_lds_dwordx4 v[238:239], off
	v_lshl_add_u64 v[238:239], v[240:241], 0, s[16:17]
	v_lshl_add_u64 v[240:241], v[238:239], 0, v[134:135]
	s_mov_b32 m0, s8
	v_lshl_add_u64 v[238:239], v[238:239], 0, v[140:141]
	global_load_lds_dwordx4 v[240:241], off
	s_add_i32 m0, s8, 0x2000
	s_nop 0
	global_load_lds_dwordx4 v[238:239], off
	v_lshl_add_u64 v[238:239], v[246:247], 0, s[14:15]
	s_mov_b32 m0, s37
	s_nop 0
	global_load_lds_dwordx4 v[238:239], off
	v_lshl_add_u64 v[238:239], v[248:249], 0, s[14:15]
	s_mov_b32 m0, s38
	s_nop 0
	global_load_lds_dwordx4 v[238:239], off
	s_waitcnt vmcnt(8)
	s_waitcnt lgkmcnt(0)
	s_barrier
	s_setprio 1
	v_mfma_f32_16x16x32_bf16 v[60:63], v[172:175], v[206:209], v[60:63]
	v_mfma_f32_16x16x32_bf16 v[56:59], v[182:185], v[206:209], v[56:59]
	v_mfma_f32_16x16x32_bf16 v[44:47], v[172:175], v[214:217], v[44:47]
	v_mfma_f32_16x16x32_bf16 v[40:43], v[182:185], v[214:217], v[40:43]
	v_mfma_f32_16x16x32_bf16 v[28:31], v[172:175], v[222:225], v[28:31]
	v_mfma_f32_16x16x32_bf16 v[24:27], v[182:185], v[222:225], v[24:27]
	v_mfma_f32_16x16x32_bf16 v[12:15], v[172:175], v[230:233], v[12:15]
	v_mfma_f32_16x16x32_bf16 v[8:11], v[182:185], v[230:233], v[8:11]
	v_mfma_f32_16x16x32_bf16 v[60:63], v[178:181], v[210:213], v[60:63]
	v_mfma_f32_16x16x32_bf16 v[56:59], v[186:189], v[210:213], v[56:59]
	v_mfma_f32_16x16x32_bf16 v[44:47], v[178:181], v[218:221], v[44:47]
	v_mfma_f32_16x16x32_bf16 v[40:43], v[186:189], v[218:221], v[40:43]
	v_mfma_f32_16x16x32_bf16 v[28:31], v[178:181], v[226:229], v[28:31]
	v_mfma_f32_16x16x32_bf16 v[24:27], v[186:189], v[226:229], v[24:27]
	v_mfma_f32_16x16x32_bf16 v[12:15], v[178:181], v[234:237], v[12:15]
	v_mfma_f32_16x16x32_bf16 v[8:11], v[186:189], v[234:237], v[8:11]
	v_mfma_f32_16x16x32_bf16 v[52:55], v[190:193], v[206:209], v[52:55]
	v_mfma_f32_16x16x32_bf16 v[48:51], v[198:201], v[206:209], v[48:51]
	v_mfma_f32_16x16x32_bf16 v[36:39], v[190:193], v[214:217], v[36:39]
	v_mfma_f32_16x16x32_bf16 v[32:35], v[198:201], v[214:217], v[32:35]
	v_mfma_f32_16x16x32_bf16 v[20:23], v[190:193], v[222:225], v[20:23]
	v_mfma_f32_16x16x32_bf16 v[16:19], v[198:201], v[222:225], v[16:19]
	v_mfma_f32_16x16x32_bf16 v[4:7], v[190:193], v[230:233], v[4:7]
	v_mfma_f32_16x16x32_bf16 v[0:3], v[198:201], v[230:233], v[0:3]
	v_mfma_f32_16x16x32_bf16 v[52:55], v[194:197], v[210:213], v[52:55]
	v_mfma_f32_16x16x32_bf16 v[48:51], v[202:205], v[210:213], v[48:51]
	v_mfma_f32_16x16x32_bf16 v[36:39], v[194:197], v[218:221], v[36:39]
	v_mfma_f32_16x16x32_bf16 v[32:35], v[202:205], v[218:221], v[32:35]
	v_mfma_f32_16x16x32_bf16 v[20:23], v[194:197], v[226:229], v[20:23]
	v_mfma_f32_16x16x32_bf16 v[16:19], v[202:205], v[226:229], v[16:19]
	v_mfma_f32_16x16x32_bf16 v[4:7], v[194:197], v[234:237], v[4:7]
	v_mfma_f32_16x16x32_bf16 v[0:3], v[202:205], v[234:237], v[0:3]
	s_setprio 0
	s_barrier
	s_add_i32 s29, s29, 2
	v_lshl_add_u64 v[162:163], v[162:163], 0, s[20:21]
	s_cmp_gt_u32 s29, 13
	v_lshl_add_u64 v[164:165], v[164:165], 0, s[20:21]
	s_cbranch_scc1 .LBB0_262

.LBB0_508:
	ds_read_b128 v[120:123], v220
	ds_read_b128 v[124:127], v220 offset:1024
	ds_read_b128 v[144:147], v220 offset:2048
	ds_read_b128 v[148:151], v220 offset:3072
	ds_read_b128 v[152:155], v221
	ds_read_b128 v[156:159], v221 offset:1024
	ds_read_b128 v[160:163], v221 offset:2048
	ds_read_b128 v[164:167], v221 offset:3072
	s_cmp_eq_u32 s9, 12
	v_lshl_add_u64 v[168:169], v[110:111], 0, s[30:31]
	s_cselect_b64 vcc, -1, 0
	v_cndmask_b32_e32 v215, v169, v105, vcc
	v_cndmask_b32_e32 v214, v168, v104, vcc
	v_cndmask_b32_e32 v243, v109, v107, vcc
	v_cndmask_b32_e32 v242, v108, v106, vcc
	s_mov_b32 m0, s74
	v_lshl_add_u64 v[244:245], v[110:111], 0, v[192:193]
	ds_read_b128 v[168:171], v222
	ds_read_b128 v[172:175], v222 offset:1024
	ds_read_b128 v[202:205], v222 offset:2048
	ds_read_b128 v[206:209], v222 offset:3072
	ds_read_b128 v[210:213], v222 offset:4096
	ds_read_b128 v[230:233], v222 offset:5120
	ds_read_b128 v[234:237], v222 offset:6144
	ds_read_b128 v[238:241], v222 offset:7168
	global_load_lds_dwordx4 v[244:245], off
	v_lshl_add_u64 v[244:245], v[110:111], 0, v[190:191]
	s_mov_b32 m0, s75
	s_nop 0
	global_load_lds_dwordx4 v[244:245], off
	s_waitcnt vmcnt(8)
	s_waitcnt lgkmcnt(0)
	s_barrier
	s_setprio 1
	v_mfma_f32_16x16x32_bf16 v[140:143], v[120:123], v[168:171], v[140:143]
	v_mfma_f32_16x16x32_bf16 v[136:139], v[144:147], v[168:171], v[136:139]
	v_mfma_f32_16x16x32_bf16 v[116:119], v[120:123], v[202:205], v[116:119]
	v_mfma_f32_16x16x32_bf16 v[112:115], v[144:147], v[202:205], v[112:115]
	v_mfma_f32_16x16x32_bf16 v[92:95], v[120:123], v[210:213], v[92:95]
	v_mfma_f32_16x16x32_bf16 v[88:91], v[144:147], v[210:213], v[88:91]
	v_mfma_f32_16x16x32_bf16 v[76:79], v[120:123], v[234:237], v[76:79]
	v_mfma_f32_16x16x32_bf16 v[72:75], v[144:147], v[234:237], v[72:75]
	v_mfma_f32_16x16x32_bf16 v[140:143], v[124:127], v[172:175], v[140:143]
	v_mfma_f32_16x16x32_bf16 v[136:139], v[148:151], v[172:175], v[136:139]
	v_mfma_f32_16x16x32_bf16 v[116:119], v[124:127], v[206:209], v[116:119]
	v_mfma_f32_16x16x32_bf16 v[112:115], v[148:151], v[206:209], v[112:115]
	v_mfma_f32_16x16x32_bf16 v[92:95], v[124:127], v[230:233], v[92:95]
	v_mfma_f32_16x16x32_bf16 v[88:91], v[148:151], v[230:233], v[88:91]
	v_mfma_f32_16x16x32_bf16 v[76:79], v[124:127], v[238:241], v[76:79]
	v_mfma_f32_16x16x32_bf16 v[72:75], v[148:151], v[238:241], v[72:75]
	v_mfma_f32_16x16x32_bf16 v[132:135], v[152:155], v[168:171], v[132:135]
	v_mfma_f32_16x16x32_bf16 v[128:131], v[160:163], v[168:171], v[128:131]
	v_mfma_f32_16x16x32_bf16 v[100:103], v[152:155], v[202:205], v[100:103]
	v_mfma_f32_16x16x32_bf16 v[96:99], v[160:163], v[202:205], v[96:99]
	v_mfma_f32_16x16x32_bf16 v[84:87], v[152:155], v[210:213], v[84:87]
	v_mfma_f32_16x16x32_bf16 v[80:83], v[160:163], v[210:213], v[80:83]
	v_mfma_f32_16x16x32_bf16 v[68:71], v[152:155], v[234:237], v[68:71]
	v_mfma_f32_16x16x32_bf16 v[64:67], v[160:163], v[234:237], v[64:67]
	v_mfma_f32_16x16x32_bf16 v[132:135], v[156:159], v[172:175], v[132:135]
	v_mfma_f32_16x16x32_bf16 v[128:131], v[164:167], v[172:175], v[128:131]
	v_mfma_f32_16x16x32_bf16 v[100:103], v[156:159], v[206:209], v[100:103]
	v_mfma_f32_16x16x32_bf16 v[96:99], v[164:167], v[206:209], v[96:99]
	v_mfma_f32_16x16x32_bf16 v[84:87], v[156:159], v[230:233], v[84:87]
	v_mfma_f32_16x16x32_bf16 v[80:83], v[164:167], v[230:233], v[80:83]
	v_mfma_f32_16x16x32_bf16 v[68:71], v[156:159], v[238:241], v[68:71]
	v_mfma_f32_16x16x32_bf16 v[64:67], v[164:167], v[238:241], v[64:67]
	s_setprio 0
	s_barrier
	s_mov_b32 m0, s76
	v_lshl_add_u64 v[244:245], v[242:243], 0, v[184:185]
	ds_read_b128 v[168:171], v222 offset:16384
	ds_read_b128 v[172:175], v222 offset:17408
	ds_read_b128 v[202:205], v222 offset:18432
	ds_read_b128 v[206:209], v222 offset:19456
	ds_read_b128 v[210:213], v222 offset:20480
	ds_read_b128 v[230:233], v222 offset:21504
	ds_read_b128 v[234:237], v222 offset:22528
	ds_read_b128 v[238:241], v222 offset:23552
	global_load_lds_dwordx4 v[244:245], off
	v_lshl_add_u64 v[246:247], v[242:243], 0, v[188:189]
	s_mov_b32 m0, s77
	v_lshl_add_u64 v[248:249], v[242:243], 0, s[14:15]
	global_load_lds_dwordx4 v[246:247], off
	v_lshl_add_u64 v[250:251], v[248:249], 0, v[184:185]
	s_mov_b32 m0, s78
	v_lshl_add_u64 v[248:249], v[248:249], 0, v[188:189]
	global_load_lds_dwordx4 v[250:251], off
	s_mov_b32 m0, s79
	v_lshl_add_u64 v[250:251], v[214:215], 0, v[186:187]
	global_load_lds_dwordx4 v[248:249], off
	v_lshl_add_u64 v[248:249], v[214:215], 0, v[182:183]
	s_mov_b32 m0, s42
	s_nop 0
	global_load_lds_dwordx4 v[248:249], off
	s_mov_b32 m0, s43
	s_nop 0
	global_load_lds_dwordx4 v[250:251], off
	s_waitcnt vmcnt(8)
	s_waitcnt lgkmcnt(0)
	s_barrier
	s_setprio 1
	v_mfma_f32_16x16x32_bf16 v[60:63], v[120:123], v[168:171], v[60:63]
	v_mfma_f32_16x16x32_bf16 v[56:59], v[144:147], v[168:171], v[56:59]
	v_mfma_f32_16x16x32_bf16 v[44:47], v[120:123], v[202:205], v[44:47]
	v_mfma_f32_16x16x32_bf16 v[40:43], v[144:147], v[202:205], v[40:43]
	v_mfma_f32_16x16x32_bf16 v[28:31], v[120:123], v[210:213], v[28:31]
	v_mfma_f32_16x16x32_bf16 v[24:27], v[144:147], v[210:213], v[24:27]
	v_mfma_f32_16x16x32_bf16 v[12:15], v[120:123], v[234:237], v[12:15]
	v_mfma_f32_16x16x32_bf16 v[8:11], v[144:147], v[234:237], v[8:11]
	v_mfma_f32_16x16x32_bf16 v[60:63], v[124:127], v[172:175], v[60:63]
	v_mfma_f32_16x16x32_bf16 v[56:59], v[148:151], v[172:175], v[56:59]
	v_mfma_f32_16x16x32_bf16 v[44:47], v[124:127], v[206:209], v[44:47]
	v_mfma_f32_16x16x32_bf16 v[40:43], v[148:151], v[206:209], v[40:43]
	v_mfma_f32_16x16x32_bf16 v[28:31], v[124:127], v[230:233], v[28:31]
	v_mfma_f32_16x16x32_bf16 v[24:27], v[148:151], v[230:233], v[24:27]
	v_mfma_f32_16x16x32_bf16 v[12:15], v[124:127], v[238:241], v[12:15]
	v_mfma_f32_16x16x32_bf16 v[8:11], v[148:151], v[238:241], v[8:11]
	v_mfma_f32_16x16x32_bf16 v[52:55], v[152:155], v[168:171], v[52:55]
	v_mfma_f32_16x16x32_bf16 v[48:51], v[160:163], v[168:171], v[48:51]
	v_mfma_f32_16x16x32_bf16 v[36:39], v[152:155], v[202:205], v[36:39]
	v_mfma_f32_16x16x32_bf16 v[32:35], v[160:163], v[202:205], v[32:35]
	v_mfma_f32_16x16x32_bf16 v[20:23], v[152:155], v[210:213], v[20:23]
	v_mfma_f32_16x16x32_bf16 v[16:19], v[160:163], v[210:213], v[16:19]
	v_mfma_f32_16x16x32_bf16 v[4:7], v[152:155], v[234:237], v[4:7]
	v_mfma_f32_16x16x32_bf16 v[0:3], v[160:163], v[234:237], v[0:3]
	v_mfma_f32_16x16x32_bf16 v[52:55], v[156:159], v[172:175], v[52:55]
	v_mfma_f32_16x16x32_bf16 v[48:51], v[164:167], v[172:175], v[48:51]
	v_mfma_f32_16x16x32_bf16 v[36:39], v[156:159], v[206:209], v[36:39]
	v_mfma_f32_16x16x32_bf16 v[32:35], v[164:167], v[206:209], v[32:35]
	v_mfma_f32_16x16x32_bf16 v[20:23], v[156:159], v[230:233], v[20:23]
	v_mfma_f32_16x16x32_bf16 v[16:19], v[164:167], v[230:233], v[16:19]
	v_mfma_f32_16x16x32_bf16 v[4:7], v[156:159], v[238:241], v[4:7]
	v_mfma_f32_16x16x32_bf16 v[0:3], v[164:167], v[238:241], v[0:3]
	s_setprio 0
	s_barrier
	ds_read_b128 v[120:123], v223
	ds_read_b128 v[124:127], v223 offset:1024
	ds_read_b128 v[144:147], v223 offset:2048
	ds_read_b128 v[148:151], v223 offset:3072
	ds_read_b128 v[152:155], v224
	ds_read_b128 v[156:159], v224 offset:1024
	ds_read_b128 v[160:163], v224 offset:2048
	ds_read_b128 v[164:167], v224 offset:3072
	v_lshl_add_u64 v[214:215], v[214:215], 0, s[14:15]
	s_mov_b32 m0, s44
	v_lshl_add_u64 v[252:253], v[214:215], 0, v[182:183]
	ds_read_b128 v[168:171], v222 offset:32768
	ds_read_b128 v[172:175], v222 offset:33792
	ds_read_b128 v[202:205], v222 offset:34816
	ds_read_b128 v[206:209], v222 offset:35840
	ds_read_b128 v[210:213], v222 offset:36864
	ds_read_b128 v[230:233], v222 offset:37888
	ds_read_b128 v[234:237], v222 offset:38912
	ds_read_b128 v[238:241], v222 offset:39936
	global_load_lds_dwordx4 v[252:253], off
	v_lshl_add_u64 v[214:215], v[214:215], 0, v[186:187]
	s_mov_b32 m0, s45
	s_nop 0
	global_load_lds_dwordx4 v[214:215], off
	s_waitcnt vmcnt(8)
	s_waitcnt lgkmcnt(0)
	s_barrier
	s_setprio 1
	v_mfma_f32_16x16x32_bf16 v[140:143], v[120:123], v[168:171], v[140:143]
	v_mfma_f32_16x16x32_bf16 v[136:139], v[144:147], v[168:171], v[136:139]
	v_mfma_f32_16x16x32_bf16 v[116:119], v[120:123], v[202:205], v[116:119]
	v_mfma_f32_16x16x32_bf16 v[112:115], v[144:147], v[202:205], v[112:115]
	v_mfma_f32_16x16x32_bf16 v[92:95], v[120:123], v[210:213], v[92:95]
	v_mfma_f32_16x16x32_bf16 v[88:91], v[144:147], v[210:213], v[88:91]
	v_mfma_f32_16x16x32_bf16 v[76:79], v[120:123], v[234:237], v[76:79]
	v_mfma_f32_16x16x32_bf16 v[72:75], v[144:147], v[234:237], v[72:75]
	v_mfma_f32_16x16x32_bf16 v[140:143], v[124:127], v[172:175], v[140:143]
	v_mfma_f32_16x16x32_bf16 v[136:139], v[148:151], v[172:175], v[136:139]
	v_mfma_f32_16x16x32_bf16 v[116:119], v[124:127], v[206:209], v[116:119]
	v_mfma_f32_16x16x32_bf16 v[112:115], v[148:151], v[206:209], v[112:115]
	v_mfma_f32_16x16x32_bf16 v[92:95], v[124:127], v[230:233], v[92:95]
	v_mfma_f32_16x16x32_bf16 v[88:91], v[148:151], v[230:233], v[88:91]
	v_mfma_f32_16x16x32_bf16 v[76:79], v[124:127], v[238:241], v[76:79]
	v_mfma_f32_16x16x32_bf16 v[72:75], v[148:151], v[238:241], v[72:75]
	v_mfma_f32_16x16x32_bf16 v[132:135], v[152:155], v[168:171], v[132:135]
	v_mfma_f32_16x16x32_bf16 v[128:131], v[160:163], v[168:171], v[128:131]
	v_mfma_f32_16x16x32_bf16 v[100:103], v[152:155], v[202:205], v[100:103]
	v_mfma_f32_16x16x32_bf16 v[96:99], v[160:163], v[202:205], v[96:99]
	v_mfma_f32_16x16x32_bf16 v[84:87], v[152:155], v[210:213], v[84:87]
	v_mfma_f32_16x16x32_bf16 v[80:83], v[160:163], v[210:213], v[80:83]
	v_mfma_f32_16x16x32_bf16 v[68:71], v[152:155], v[234:237], v[68:71]
	v_mfma_f32_16x16x32_bf16 v[64:67], v[160:163], v[234:237], v[64:67]
	v_mfma_f32_16x16x32_bf16 v[132:135], v[156:159], v[172:175], v[132:135]
	v_mfma_f32_16x16x32_bf16 v[128:131], v[164:167], v[172:175], v[128:131]
	v_mfma_f32_16x16x32_bf16 v[100:103], v[156:159], v[206:209], v[100:103]
	v_mfma_f32_16x16x32_bf16 v[96:99], v[164:167], v[206:209], v[96:99]
	v_mfma_f32_16x16x32_bf16 v[84:87], v[156:159], v[230:233], v[84:87]
	v_mfma_f32_16x16x32_bf16 v[80:83], v[164:167], v[230:233], v[80:83]
	v_mfma_f32_16x16x32_bf16 v[68:71], v[156:159], v[238:241], v[68:71]
	v_mfma_f32_16x16x32_bf16 v[64:67], v[164:167], v[238:241], v[64:67]
	s_setprio 0
	s_barrier
	s_mov_b32 m0, s81
	v_lshl_add_u64 v[214:215], v[244:245], 0, s[20:21]
	ds_read_b128 v[168:171], v222 offset:49152
	ds_read_b128 v[172:175], v222 offset:50176
	ds_read_b128 v[202:205], v222 offset:51200
	ds_read_b128 v[206:209], v222 offset:52224
	ds_read_b128 v[210:213], v222 offset:53248
	ds_read_b128 v[230:233], v222 offset:54272
	ds_read_b128 v[234:237], v222 offset:55296
	ds_read_b128 v[238:241], v222 offset:56320
	global_load_lds_dwordx4 v[214:215], off
	v_lshl_add_u64 v[214:215], v[246:247], 0, s[20:21]
	s_mov_b32 m0, s82
	s_add_i32 s10, s80, s3
	global_load_lds_dwordx4 v[214:215], off
	v_lshl_add_u64 v[214:215], v[242:243], 0, s[22:23]
	v_lshl_add_u64 v[242:243], v[214:215], 0, v[184:185]
	s_mov_b32 m0, s10
	v_lshl_add_u64 v[214:215], v[214:215], 0, v[188:189]
	global_load_lds_dwordx4 v[242:243], off
	s_add_i32 m0, s10, 0x2000
	s_nop 0
	global_load_lds_dwordx4 v[214:215], off
	v_lshl_add_u64 v[214:215], v[248:249], 0, s[20:21]
	s_mov_b32 m0, s71
	s_nop 0
	global_load_lds_dwordx4 v[214:215], off
	v_lshl_add_u64 v[214:215], v[250:251], 0, s[20:21]
	s_mov_b32 m0, s72
	s_nop 0
	global_load_lds_dwordx4 v[214:215], off
	s_waitcnt vmcnt(8)
	s_waitcnt lgkmcnt(0)
	s_barrier
	s_setprio 1
	v_mfma_f32_16x16x32_bf16 v[60:63], v[120:123], v[168:171], v[60:63]
	v_mfma_f32_16x16x32_bf16 v[56:59], v[144:147], v[168:171], v[56:59]
	v_mfma_f32_16x16x32_bf16 v[44:47], v[120:123], v[202:205], v[44:47]
	v_mfma_f32_16x16x32_bf16 v[40:43], v[144:147], v[202:205], v[40:43]
	v_mfma_f32_16x16x32_bf16 v[28:31], v[120:123], v[210:213], v[28:31]
	v_mfma_f32_16x16x32_bf16 v[24:27], v[144:147], v[210:213], v[24:27]
	v_mfma_f32_16x16x32_bf16 v[12:15], v[120:123], v[234:237], v[12:15]
	v_mfma_f32_16x16x32_bf16 v[8:11], v[144:147], v[234:237], v[8:11]
	v_mfma_f32_16x16x32_bf16 v[60:63], v[124:127], v[172:175], v[60:63]
	v_mfma_f32_16x16x32_bf16 v[56:59], v[148:151], v[172:175], v[56:59]
	v_mfma_f32_16x16x32_bf16 v[44:47], v[124:127], v[206:209], v[44:47]
	v_mfma_f32_16x16x32_bf16 v[40:43], v[148:151], v[206:209], v[40:43]
	v_mfma_f32_16x16x32_bf16 v[28:31], v[124:127], v[230:233], v[28:31]
	v_mfma_f32_16x16x32_bf16 v[24:27], v[148:151], v[230:233], v[24:27]
	v_mfma_f32_16x16x32_bf16 v[12:15], v[124:127], v[238:241], v[12:15]
	v_mfma_f32_16x16x32_bf16 v[8:11], v[148:151], v[238:241], v[8:11]
	v_mfma_f32_16x16x32_bf16 v[52:55], v[152:155], v[168:171], v[52:55]
	v_mfma_f32_16x16x32_bf16 v[48:51], v[160:163], v[168:171], v[48:51]
	v_mfma_f32_16x16x32_bf16 v[36:39], v[152:155], v[202:205], v[36:39]
	v_mfma_f32_16x16x32_bf16 v[32:35], v[160:163], v[202:205], v[32:35]
	v_mfma_f32_16x16x32_bf16 v[20:23], v[152:155], v[210:213], v[20:23]
	v_mfma_f32_16x16x32_bf16 v[16:19], v[160:163], v[210:213], v[16:19]
	v_mfma_f32_16x16x32_bf16 v[4:7], v[152:155], v[234:237], v[4:7]
	v_mfma_f32_16x16x32_bf16 v[0:3], v[160:163], v[234:237], v[0:3]
	v_mfma_f32_16x16x32_bf16 v[52:55], v[156:159], v[172:175], v[52:55]
	v_mfma_f32_16x16x32_bf16 v[48:51], v[164:167], v[172:175], v[48:51]
	v_mfma_f32_16x16x32_bf16 v[36:39], v[156:159], v[206:209], v[36:39]
	v_mfma_f32_16x16x32_bf16 v[32:35], v[164:167], v[206:209], v[32:35]
	v_mfma_f32_16x16x32_bf16 v[20:23], v[156:159], v[230:233], v[20:23]
	v_mfma_f32_16x16x32_bf16 v[16:19], v[164:167], v[230:233], v[16:19]
	v_mfma_f32_16x16x32_bf16 v[4:7], v[156:159], v[238:241], v[4:7]
	v_mfma_f32_16x16x32_bf16 v[0:3], v[164:167], v[238:241], v[0:3]
	s_setprio 0
	s_barrier
	s_add_i32 s9, s9, 2
	v_lshl_add_u64 v[108:109], v[108:109], 0, s[28:29]
	s_cmp_gt_u32 s9, 13
	v_lshl_add_u64 v[110:111], v[110:111], 0, s[28:29]
	s_cbranch_scc0 .LBB0_508
	s_and_b64 vcc, exec, s[26:27]
	s_cbranch_vccz .LBB0_511
	s_barrier

.LBB0_619:
	v_add_u32_e32 v186, s43, v167
	v_add_u32_e32 v202, s44, v167
	ds_read_b128 v[172:175], v186
	ds_read_b128 v[178:181], v186 offset:1024
	ds_read_b128 v[182:185], v186 offset:2048
	ds_read_b128 v[186:189], v186 offset:3072
	ds_read_b128 v[190:193], v202
	ds_read_b128 v[194:197], v202 offset:1024
	ds_read_b128 v[198:201], v202 offset:2048
	ds_read_b128 v[202:205], v202 offset:3072
	v_lshl_add_u64 v[206:207], v[164:165], 0, s[26:27]
	v_cndmask_b32_e64 v215, v207, v157, s[10:11]
	v_cndmask_b32_e64 v214, v206, v156, s[10:11]
	v_cndmask_b32_e64 v243, v163, v159, s[10:11]
	v_cndmask_b32_e64 v242, v162, v158, s[10:11]
	s_mov_b32 m0, s45
	v_lshl_add_u64 v[244:245], v[164:165], 0, v[146:147]
	ds_read_b128 v[206:209], v170
	ds_read_b128 v[210:213], v170 offset:1024
	ds_read_b128 v[218:221], v170 offset:2048
	ds_read_b128 v[222:225], v170 offset:3072
	ds_read_b128 v[226:229], v170 offset:4096
	ds_read_b128 v[230:233], v170 offset:5120
	ds_read_b128 v[234:237], v170 offset:6144
	ds_read_b128 v[238:241], v170 offset:7168
	global_load_lds_dwordx4 v[244:245], off
	v_lshl_add_u64 v[244:245], v[164:165], 0, v[144:145]
	s_mov_b32 m0, s50
	s_nop 0
	global_load_lds_dwordx4 v[244:245], off
	s_waitcnt vmcnt(8)
	s_waitcnt lgkmcnt(0)
	s_barrier
	s_setprio 1
	v_mfma_f32_16x16x32_bf16 v[124:127], v[172:175], v[206:209], v[124:127]
	v_mfma_f32_16x16x32_bf16 v[116:119], v[182:185], v[206:209], v[116:119]
	v_mfma_f32_16x16x32_bf16 v[108:111], v[172:175], v[218:221], v[108:111]
	v_mfma_f32_16x16x32_bf16 v[100:103], v[182:185], v[218:221], v[100:103]
	v_mfma_f32_16x16x32_bf16 v[92:95], v[172:175], v[226:229], v[92:95]
	v_mfma_f32_16x16x32_bf16 v[84:87], v[182:185], v[226:229], v[84:87]
	v_mfma_f32_16x16x32_bf16 v[76:79], v[172:175], v[234:237], v[76:79]
	v_mfma_f32_16x16x32_bf16 v[68:71], v[182:185], v[234:237], v[68:71]
	v_mfma_f32_16x16x32_bf16 v[124:127], v[178:181], v[210:213], v[124:127]
	v_mfma_f32_16x16x32_bf16 v[116:119], v[186:189], v[210:213], v[116:119]
	v_mfma_f32_16x16x32_bf16 v[108:111], v[178:181], v[222:225], v[108:111]
	v_mfma_f32_16x16x32_bf16 v[100:103], v[186:189], v[222:225], v[100:103]
	v_mfma_f32_16x16x32_bf16 v[92:95], v[178:181], v[230:233], v[92:95]
	v_mfma_f32_16x16x32_bf16 v[84:87], v[186:189], v[230:233], v[84:87]
	v_mfma_f32_16x16x32_bf16 v[76:79], v[178:181], v[238:241], v[76:79]
	v_mfma_f32_16x16x32_bf16 v[68:71], v[186:189], v[238:241], v[68:71]
	v_mfma_f32_16x16x32_bf16 v[120:123], v[190:193], v[206:209], v[120:123]
	v_mfma_f32_16x16x32_bf16 v[112:115], v[198:201], v[206:209], v[112:115]
	v_mfma_f32_16x16x32_bf16 v[104:107], v[190:193], v[218:221], v[104:107]
	v_mfma_f32_16x16x32_bf16 v[96:99], v[198:201], v[218:221], v[96:99]
	v_mfma_f32_16x16x32_bf16 v[88:91], v[190:193], v[226:229], v[88:91]
	v_mfma_f32_16x16x32_bf16 v[80:83], v[198:201], v[226:229], v[80:83]
	v_mfma_f32_16x16x32_bf16 v[72:75], v[190:193], v[234:237], v[72:75]
	v_mfma_f32_16x16x32_bf16 v[64:67], v[198:201], v[234:237], v[64:67]
	v_mfma_f32_16x16x32_bf16 v[120:123], v[194:197], v[210:213], v[120:123]
	v_mfma_f32_16x16x32_bf16 v[112:115], v[202:205], v[210:213], v[112:115]
	v_mfma_f32_16x16x32_bf16 v[104:107], v[194:197], v[222:225], v[104:107]
	v_mfma_f32_16x16x32_bf16 v[96:99], v[202:205], v[222:225], v[96:99]
	v_mfma_f32_16x16x32_bf16 v[88:91], v[194:197], v[230:233], v[88:91]
	v_mfma_f32_16x16x32_bf16 v[80:83], v[202:205], v[230:233], v[80:83]
	v_mfma_f32_16x16x32_bf16 v[72:75], v[194:197], v[238:241], v[72:75]
	v_mfma_f32_16x16x32_bf16 v[64:67], v[202:205], v[238:241], v[64:67]
	s_setprio 0
	s_barrier
	s_add_i32 s10, s43, s3
	v_lshl_add_u64 v[244:245], v[242:243], 0, v[136:137]
	s_mov_b32 m0, s10
	ds_read_b128 v[206:209], v170 offset:16384
	ds_read_b128 v[210:213], v170 offset:17408
	ds_read_b128 v[218:221], v170 offset:18432
	ds_read_b128 v[222:225], v170 offset:19456
	ds_read_b128 v[226:229], v170 offset:20480
	ds_read_b128 v[230:233], v170 offset:21504
	ds_read_b128 v[234:237], v170 offset:22528
	ds_read_b128 v[238:241], v170 offset:23552
	global_load_lds_dwordx4 v[244:245], off
	v_lshl_add_u64 v[246:247], v[242:243], 0, v[140:141]
	s_add_i32 m0, s10, 0x2000
	v_lshl_add_u64 v[248:249], v[242:243], 0, s[12:13]
	s_add_i32 s10, s44, s3
	global_load_lds_dwordx4 v[246:247], off
	v_lshl_add_u64 v[250:251], v[248:249], 0, v[136:137]
	s_mov_b32 m0, s10
	v_lshl_add_u64 v[248:249], v[248:249], 0, v[140:141]
	global_load_lds_dwordx4 v[250:251], off
	s_add_i32 m0, s10, 0x2000
	v_lshl_add_u64 v[250:251], v[214:215], 0, v[138:139]
	global_load_lds_dwordx4 v[248:249], off
	v_lshl_add_u64 v[248:249], v[214:215], 0, v[134:135]
	s_mov_b32 m0, s35
	s_nop 0
	global_load_lds_dwordx4 v[248:249], off
	s_mov_b32 m0, s37
	s_nop 0
	global_load_lds_dwordx4 v[250:251], off
	s_waitcnt vmcnt(8)
	s_waitcnt lgkmcnt(0)
	s_barrier
	s_setprio 1
	v_mfma_f32_16x16x32_bf16 v[60:63], v[172:175], v[206:209], v[60:63]
	v_mfma_f32_16x16x32_bf16 v[52:55], v[182:185], v[206:209], v[52:55]
	v_mfma_f32_16x16x32_bf16 v[44:47], v[172:175], v[218:221], v[44:47]
	v_mfma_f32_16x16x32_bf16 v[36:39], v[182:185], v[218:221], v[36:39]
	v_mfma_f32_16x16x32_bf16 v[28:31], v[172:175], v[226:229], v[28:31]
	v_mfma_f32_16x16x32_bf16 v[20:23], v[182:185], v[226:229], v[20:23]
	v_mfma_f32_16x16x32_bf16 v[12:15], v[172:175], v[234:237], v[12:15]
	v_mfma_f32_16x16x32_bf16 v[4:7], v[182:185], v[234:237], v[4:7]
	v_mfma_f32_16x16x32_bf16 v[60:63], v[178:181], v[210:213], v[60:63]
	v_mfma_f32_16x16x32_bf16 v[52:55], v[186:189], v[210:213], v[52:55]
	v_mfma_f32_16x16x32_bf16 v[44:47], v[178:181], v[222:225], v[44:47]
	v_mfma_f32_16x16x32_bf16 v[36:39], v[186:189], v[222:225], v[36:39]
	v_mfma_f32_16x16x32_bf16 v[28:31], v[178:181], v[230:233], v[28:31]
	v_mfma_f32_16x16x32_bf16 v[20:23], v[186:189], v[230:233], v[20:23]
	v_mfma_f32_16x16x32_bf16 v[12:15], v[178:181], v[238:241], v[12:15]
	v_mfma_f32_16x16x32_bf16 v[4:7], v[186:189], v[238:241], v[4:7]
	v_mfma_f32_16x16x32_bf16 v[56:59], v[190:193], v[206:209], v[56:59]
	v_mfma_f32_16x16x32_bf16 v[48:51], v[198:201], v[206:209], v[48:51]
	v_mfma_f32_16x16x32_bf16 v[40:43], v[190:193], v[218:221], v[40:43]
	v_mfma_f32_16x16x32_bf16 v[32:35], v[198:201], v[218:221], v[32:35]
	v_mfma_f32_16x16x32_bf16 v[24:27], v[190:193], v[226:229], v[24:27]
	v_mfma_f32_16x16x32_bf16 v[16:19], v[198:201], v[226:229], v[16:19]
	v_mfma_f32_16x16x32_bf16 v[8:11], v[190:193], v[234:237], v[8:11]
	v_mfma_f32_16x16x32_bf16 v[0:3], v[198:201], v[234:237], v[0:3]
	v_mfma_f32_16x16x32_bf16 v[56:59], v[194:197], v[210:213], v[56:59]
	v_mfma_f32_16x16x32_bf16 v[48:51], v[202:205], v[210:213], v[48:51]
	v_mfma_f32_16x16x32_bf16 v[40:43], v[194:197], v[222:225], v[40:43]
	v_mfma_f32_16x16x32_bf16 v[32:35], v[202:205], v[222:225], v[32:35]
	v_mfma_f32_16x16x32_bf16 v[24:27], v[194:197], v[230:233], v[24:27]
	v_mfma_f32_16x16x32_bf16 v[16:19], v[202:205], v[230:233], v[16:19]
	v_mfma_f32_16x16x32_bf16 v[8:11], v[194:197], v[238:241], v[8:11]
	v_mfma_f32_16x16x32_bf16 v[0:3], v[202:205], v[238:241], v[0:3]
	s_setprio 0
	s_barrier
	s_add_i32 s10, 0, 0x18000
	s_add_i32 s11, 0, 0x1c000
	v_add_u32_e32 v186, s10, v167
	v_add_u32_e32 v202, s11, v167
	ds_read_b128 v[172:175], v186
	ds_read_b128 v[178:181], v186 offset:1024
	ds_read_b128 v[182:185], v186 offset:2048
	ds_read_b128 v[186:189], v186 offset:3072
	ds_read_b128 v[190:193], v202
	ds_read_b128 v[194:197], v202 offset:1024
	ds_read_b128 v[198:201], v202 offset:2048
	ds_read_b128 v[202:205], v202 offset:3072
	v_lshl_add_u64 v[214:215], v[214:215], 0, s[12:13]
	s_mov_b32 m0, s38
	v_lshl_add_u64 v[252:253], v[214:215], 0, v[134:135]
	ds_read_b128 v[206:209], v170 offset:32768
	ds_read_b128 v[210:213], v170 offset:33792
	ds_read_b128 v[218:221], v170 offset:34816
	ds_read_b128 v[222:225], v170 offset:35840
	ds_read_b128 v[226:229], v170 offset:36864
	ds_read_b128 v[230:233], v170 offset:37888
	ds_read_b128 v[234:237], v170 offset:38912
	ds_read_b128 v[238:241], v170 offset:39936
	global_load_lds_dwordx4 v[252:253], off
	v_lshl_add_u64 v[214:215], v[214:215], 0, v[138:139]
	s_mov_b32 m0, s39
	s_nop 0
	global_load_lds_dwordx4 v[214:215], off
	s_waitcnt vmcnt(8)
	s_waitcnt lgkmcnt(0)
	s_barrier
	s_setprio 1
	v_mfma_f32_16x16x32_bf16 v[124:127], v[172:175], v[206:209], v[124:127]
	v_mfma_f32_16x16x32_bf16 v[116:119], v[182:185], v[206:209], v[116:119]
	v_mfma_f32_16x16x32_bf16 v[108:111], v[172:175], v[218:221], v[108:111]
	v_mfma_f32_16x16x32_bf16 v[100:103], v[182:185], v[218:221], v[100:103]
	v_mfma_f32_16x16x32_bf16 v[92:95], v[172:175], v[226:229], v[92:95]
	v_mfma_f32_16x16x32_bf16 v[84:87], v[182:185], v[226:229], v[84:87]
	v_mfma_f32_16x16x32_bf16 v[76:79], v[172:175], v[234:237], v[76:79]
	v_mfma_f32_16x16x32_bf16 v[68:71], v[182:185], v[234:237], v[68:71]
	v_mfma_f32_16x16x32_bf16 v[124:127], v[178:181], v[210:213], v[124:127]
	v_mfma_f32_16x16x32_bf16 v[116:119], v[186:189], v[210:213], v[116:119]
	v_mfma_f32_16x16x32_bf16 v[108:111], v[178:181], v[222:225], v[108:111]
	v_mfma_f32_16x16x32_bf16 v[100:103], v[186:189], v[222:225], v[100:103]
	v_mfma_f32_16x16x32_bf16 v[92:95], v[178:181], v[230:233], v[92:95]
	v_mfma_f32_16x16x32_bf16 v[84:87], v[186:189], v[230:233], v[84:87]
	v_mfma_f32_16x16x32_bf16 v[76:79], v[178:181], v[238:241], v[76:79]
	v_mfma_f32_16x16x32_bf16 v[68:71], v[186:189], v[238:241], v[68:71]
	v_mfma_f32_16x16x32_bf16 v[120:123], v[190:193], v[206:209], v[120:123]
	v_mfma_f32_16x16x32_bf16 v[112:115], v[198:201], v[206:209], v[112:115]
	v_mfma_f32_16x16x32_bf16 v[104:107], v[190:193], v[218:221], v[104:107]
	v_mfma_f32_16x16x32_bf16 v[96:99], v[198:201], v[218:221], v[96:99]
	v_mfma_f32_16x16x32_bf16 v[88:91], v[190:193], v[226:229], v[88:91]
	v_mfma_f32_16x16x32_bf16 v[80:83], v[198:201], v[226:229], v[80:83]
	v_mfma_f32_16x16x32_bf16 v[72:75], v[190:193], v[234:237], v[72:75]
	v_mfma_f32_16x16x32_bf16 v[64:67], v[198:201], v[234:237], v[64:67]
	v_mfma_f32_16x16x32_bf16 v[120:123], v[194:197], v[210:213], v[120:123]
	v_mfma_f32_16x16x32_bf16 v[112:115], v[202:205], v[210:213], v[112:115]
	v_mfma_f32_16x16x32_bf16 v[104:107], v[194:197], v[222:225], v[104:107]
	v_mfma_f32_16x16x32_bf16 v[96:99], v[202:205], v[222:225], v[96:99]
	v_mfma_f32_16x16x32_bf16 v[88:91], v[194:197], v[230:233], v[88:91]
	v_mfma_f32_16x16x32_bf16 v[80:83], v[202:205], v[230:233], v[80:83]
	v_mfma_f32_16x16x32_bf16 v[72:75], v[194:197], v[238:241], v[72:75]
	v_mfma_f32_16x16x32_bf16 v[64:67], v[202:205], v[238:241], v[64:67]
	s_setprio 0
	s_barrier
	s_add_i32 s10, s10, s3
	v_lshl_add_u64 v[214:215], v[244:245], 0, s[16:17]
	s_mov_b32 m0, s10
	ds_read_b128 v[206:209], v170 offset:49152
	ds_read_b128 v[210:213], v170 offset:50176
	ds_read_b128 v[218:221], v170 offset:51200
	ds_read_b128 v[222:225], v170 offset:52224
	ds_read_b128 v[226:229], v170 offset:53248
	ds_read_b128 v[230:233], v170 offset:54272
	ds_read_b128 v[234:237], v170 offset:55296
	ds_read_b128 v[238:241], v170 offset:56320
	global_load_lds_dwordx4 v[214:215], off
	v_lshl_add_u64 v[214:215], v[246:247], 0, s[16:17]
	s_add_i32 m0, s10, 0x2000
	s_add_i32 s10, s11, s3
	global_load_lds_dwordx4 v[214:215], off
	v_lshl_add_u64 v[214:215], v[242:243], 0, s[18:19]
	v_lshl_add_u64 v[242:243], v[214:215], 0, v[136:137]
	s_mov_b32 m0, s10
	v_lshl_add_u64 v[214:215], v[214:215], 0, v[140:141]
	global_load_lds_dwordx4 v[242:243], off
	s_add_i32 m0, s10, 0x2000
	s_nop 0
	global_load_lds_dwordx4 v[214:215], off
	v_lshl_add_u64 v[214:215], v[248:249], 0, s[16:17]
	s_mov_b32 m0, s40
	s_nop 0
	global_load_lds_dwordx4 v[214:215], off
	v_lshl_add_u64 v[214:215], v[250:251], 0, s[16:17]
	s_mov_b32 m0, s41
	s_nop 0
	global_load_lds_dwordx4 v[214:215], off
	s_waitcnt vmcnt(8)
	s_waitcnt lgkmcnt(0)
	s_barrier
	s_setprio 1
	v_mfma_f32_16x16x32_bf16 v[60:63], v[172:175], v[206:209], v[60:63]
	v_mfma_f32_16x16x32_bf16 v[52:55], v[182:185], v[206:209], v[52:55]
	v_mfma_f32_16x16x32_bf16 v[44:47], v[172:175], v[218:221], v[44:47]
	v_mfma_f32_16x16x32_bf16 v[36:39], v[182:185], v[218:221], v[36:39]
	v_mfma_f32_16x16x32_bf16 v[28:31], v[172:175], v[226:229], v[28:31]
	v_mfma_f32_16x16x32_bf16 v[20:23], v[182:185], v[226:229], v[20:23]
	v_mfma_f32_16x16x32_bf16 v[12:15], v[172:175], v[234:237], v[12:15]
	v_mfma_f32_16x16x32_bf16 v[4:7], v[182:185], v[234:237], v[4:7]
	v_mfma_f32_16x16x32_bf16 v[60:63], v[178:181], v[210:213], v[60:63]
	v_mfma_f32_16x16x32_bf16 v[52:55], v[186:189], v[210:213], v[52:55]
	v_mfma_f32_16x16x32_bf16 v[44:47], v[178:181], v[222:225], v[44:47]
	v_mfma_f32_16x16x32_bf16 v[36:39], v[186:189], v[222:225], v[36:39]
	v_mfma_f32_16x16x32_bf16 v[28:31], v[178:181], v[230:233], v[28:31]
	v_mfma_f32_16x16x32_bf16 v[20:23], v[186:189], v[230:233], v[20:23]
	v_mfma_f32_16x16x32_bf16 v[12:15], v[178:181], v[238:241], v[12:15]
	v_mfma_f32_16x16x32_bf16 v[4:7], v[186:189], v[238:241], v[4:7]
	v_mfma_f32_16x16x32_bf16 v[56:59], v[190:193], v[206:209], v[56:59]
	v_mfma_f32_16x16x32_bf16 v[48:51], v[198:201], v[206:209], v[48:51]
	v_mfma_f32_16x16x32_bf16 v[40:43], v[190:193], v[218:221], v[40:43]
	v_mfma_f32_16x16x32_bf16 v[32:35], v[198:201], v[218:221], v[32:35]
	v_mfma_f32_16x16x32_bf16 v[24:27], v[190:193], v[226:229], v[24:27]
	v_mfma_f32_16x16x32_bf16 v[16:19], v[198:201], v[226:229], v[16:19]
	v_mfma_f32_16x16x32_bf16 v[8:11], v[190:193], v[234:237], v[8:11]
	v_mfma_f32_16x16x32_bf16 v[0:3], v[198:201], v[234:237], v[0:3]
	v_mfma_f32_16x16x32_bf16 v[56:59], v[194:197], v[210:213], v[56:59]
	v_mfma_f32_16x16x32_bf16 v[48:51], v[202:205], v[210:213], v[48:51]
	v_mfma_f32_16x16x32_bf16 v[40:43], v[194:197], v[222:225], v[40:43]
	v_mfma_f32_16x16x32_bf16 v[32:35], v[202:205], v[222:225], v[32:35]
	v_mfma_f32_16x16x32_bf16 v[24:27], v[194:197], v[230:233], v[24:27]
	v_mfma_f32_16x16x32_bf16 v[16:19], v[202:205], v[230:233], v[16:19]
	v_mfma_f32_16x16x32_bf16 v[8:11], v[194:197], v[238:241], v[8:11]
	v_mfma_f32_16x16x32_bf16 v[0:3], v[202:205], v[238:241], v[0:3]
	s_setprio 0
	s_barrier
	s_add_i32 s31, s31, 2
	v_lshl_add_u64 v[162:163], v[162:163], 0, s[22:23]
	s_cmp_gt_u32 s31, 13
	v_lshl_add_u64 v[164:165], v[164:165], 0, s[22:23]
	s_cbranch_scc1 .LBB0_623

.LBB0_696:
	ds_read_b128 v[120:123], v222
	ds_read_b128 v[124:127], v222 offset:1024
	ds_read_b128 v[144:147], v222 offset:2048
	ds_read_b128 v[148:151], v222 offset:3072
	ds_read_b128 v[152:155], v223
	ds_read_b128 v[156:159], v223 offset:1024
	ds_read_b128 v[160:163], v223 offset:2048
	ds_read_b128 v[164:167], v223 offset:3072
	s_cmp_eq_u32 s10, 40
	v_lshl_add_u64 v[108:109], v[106:107], 0, s[30:31]
	s_cselect_b64 vcc, -1, 0
	v_cndmask_b32_e32 v215, v109, v199, vcc
	v_cndmask_b32_e32 v214, v108, v198, vcc
	v_cndmask_b32_e32 v243, v105, v201, vcc
	v_cndmask_b32_e32 v242, v104, v200, vcc
	s_mov_b32 m0, s66
	v_lshl_add_u64 v[110:111], v[106:107], 0, v[192:193]
	ds_read_b128 v[168:171], v224
	ds_read_b128 v[172:175], v224 offset:1024
	ds_read_b128 v[202:205], v224 offset:2048
	ds_read_b128 v[206:209], v224 offset:3072
	ds_read_b128 v[210:213], v224 offset:4096
	ds_read_b128 v[230:233], v224 offset:5120
	ds_read_b128 v[234:237], v224 offset:6144
	ds_read_b128 v[238:241], v224 offset:7168
	global_load_lds_dwordx4 v[110:111], off
	v_lshl_add_u64 v[106:107], v[106:107], 0, v[190:191]
	s_mov_b32 m0, s67
	s_nop 0
	global_load_lds_dwordx4 v[106:107], off
	s_waitcnt vmcnt(8)
	s_waitcnt lgkmcnt(0)
	s_barrier
	s_setprio 1
	v_mfma_f32_16x16x32_bf16 v[140:143], v[120:123], v[168:171], v[140:143]
	v_mfma_f32_16x16x32_bf16 v[136:139], v[144:147], v[168:171], v[136:139]
	v_mfma_f32_16x16x32_bf16 v[116:119], v[120:123], v[202:205], v[116:119]
	v_mfma_f32_16x16x32_bf16 v[110:113], v[144:147], v[202:205], v[112:115]
	v_mfma_f32_16x16x32_bf16 v[92:95], v[120:123], v[210:213], v[92:95]
	v_mfma_f32_16x16x32_bf16 v[88:91], v[144:147], v[210:213], v[88:91]
	v_mfma_f32_16x16x32_bf16 v[76:79], v[120:123], v[234:237], v[76:79]
	v_mfma_f32_16x16x32_bf16 v[72:75], v[144:147], v[234:237], v[72:75]
	v_mfma_f32_16x16x32_bf16 v[140:143], v[124:127], v[172:175], v[140:143]
	v_mfma_f32_16x16x32_bf16 v[136:139], v[148:151], v[172:175], v[136:139]
	v_mfma_f32_16x16x32_bf16 v[116:119], v[124:127], v[206:209], v[116:119]
	v_mfma_f32_16x16x32_bf16 v[110:113], v[148:151], v[206:209], v[110:113]
	v_mfma_f32_16x16x32_bf16 v[92:95], v[124:127], v[230:233], v[92:95]
	v_mfma_f32_16x16x32_bf16 v[88:91], v[148:151], v[230:233], v[88:91]
	v_mfma_f32_16x16x32_bf16 v[76:79], v[124:127], v[238:241], v[76:79]
	v_mfma_f32_16x16x32_bf16 v[72:75], v[148:151], v[238:241], v[72:75]
	v_mfma_f32_16x16x32_bf16 v[132:135], v[152:155], v[168:171], v[132:135]
	v_mfma_f32_16x16x32_bf16 v[128:131], v[160:163], v[168:171], v[128:131]
	v_mfma_f32_16x16x32_bf16 v[100:103], v[152:155], v[202:205], v[100:103]
	v_mfma_f32_16x16x32_bf16 v[96:99], v[160:163], v[202:205], v[96:99]
	v_mfma_f32_16x16x32_bf16 v[84:87], v[152:155], v[210:213], v[84:87]
	v_mfma_f32_16x16x32_bf16 v[80:83], v[160:163], v[210:213], v[80:83]
	v_mfma_f32_16x16x32_bf16 v[68:71], v[152:155], v[234:237], v[68:71]
	v_mfma_f32_16x16x32_bf16 v[64:67], v[160:163], v[234:237], v[64:67]
	v_mfma_f32_16x16x32_bf16 v[132:135], v[156:159], v[172:175], v[132:135]
	v_mfma_f32_16x16x32_bf16 v[128:131], v[164:167], v[172:175], v[128:131]
	v_mfma_f32_16x16x32_bf16 v[100:103], v[156:159], v[206:209], v[100:103]
	v_mfma_f32_16x16x32_bf16 v[96:99], v[164:167], v[206:209], v[96:99]
	v_mfma_f32_16x16x32_bf16 v[84:87], v[156:159], v[230:233], v[84:87]
	v_mfma_f32_16x16x32_bf16 v[80:83], v[164:167], v[230:233], v[80:83]
	v_mfma_f32_16x16x32_bf16 v[68:71], v[156:159], v[238:241], v[68:71]
	v_mfma_f32_16x16x32_bf16 v[64:67], v[164:167], v[238:241], v[64:67]
	s_setprio 0
	s_barrier
	s_mov_b32 m0, s70
	v_lshl_add_u64 v[106:107], v[242:243], 0, v[184:185]
	ds_read_b128 v[168:171], v224 offset:16384
	ds_read_b128 v[172:175], v224 offset:17408
	ds_read_b128 v[202:205], v224 offset:18432
	ds_read_b128 v[206:209], v224 offset:19456
	ds_read_b128 v[210:213], v224 offset:20480
	ds_read_b128 v[230:233], v224 offset:21504
	ds_read_b128 v[234:237], v224 offset:22528
	ds_read_b128 v[238:241], v224 offset:23552
	global_load_lds_dwordx4 v[106:107], off
	v_lshl_add_u64 v[244:245], v[242:243], 0, v[188:189]
	s_mov_b32 m0, s71
	v_lshl_add_u64 v[114:115], v[242:243], 0, s[16:17]
	global_load_lds_dwordx4 v[244:245], off
	v_lshl_add_u64 v[246:247], v[114:115], 0, v[184:185]
	s_mov_b32 m0, s72
	v_lshl_add_u64 v[114:115], v[114:115], 0, v[188:189]
	global_load_lds_dwordx4 v[246:247], off
	s_mov_b32 m0, s73
	v_lshl_add_u64 v[246:247], v[214:215], 0, v[182:183]
	global_load_lds_dwordx4 v[114:115], off
	s_mov_b32 m0, s42
	v_lshl_add_u64 v[248:249], v[214:215], 0, v[186:187]
	global_load_lds_dwordx4 v[246:247], off
	s_mov_b32 m0, s43
	s_nop 0
	global_load_lds_dwordx4 v[248:249], off
	s_waitcnt vmcnt(8)
	s_waitcnt lgkmcnt(0)
	s_barrier
	s_setprio 1
	v_mfma_f32_16x16x32_bf16 v[60:63], v[120:123], v[168:171], v[60:63]
	v_mfma_f32_16x16x32_bf16 v[56:59], v[144:147], v[168:171], v[56:59]
	v_mfma_f32_16x16x32_bf16 v[44:47], v[120:123], v[202:205], v[44:47]
	v_mfma_f32_16x16x32_bf16 v[40:43], v[144:147], v[202:205], v[40:43]
	v_mfma_f32_16x16x32_bf16 v[28:31], v[120:123], v[210:213], v[28:31]
	v_mfma_f32_16x16x32_bf16 v[24:27], v[144:147], v[210:213], v[24:27]
	v_mfma_f32_16x16x32_bf16 v[12:15], v[120:123], v[234:237], v[12:15]
	v_mfma_f32_16x16x32_bf16 v[8:11], v[144:147], v[234:237], v[8:11]
	v_mfma_f32_16x16x32_bf16 v[60:63], v[124:127], v[172:175], v[60:63]
	v_mfma_f32_16x16x32_bf16 v[56:59], v[148:151], v[172:175], v[56:59]
	v_mfma_f32_16x16x32_bf16 v[44:47], v[124:127], v[206:209], v[44:47]
	v_mfma_f32_16x16x32_bf16 v[40:43], v[148:151], v[206:209], v[40:43]
	v_mfma_f32_16x16x32_bf16 v[28:31], v[124:127], v[230:233], v[28:31]
	v_mfma_f32_16x16x32_bf16 v[24:27], v[148:151], v[230:233], v[24:27]
	v_mfma_f32_16x16x32_bf16 v[12:15], v[124:127], v[238:241], v[12:15]
	v_mfma_f32_16x16x32_bf16 v[8:11], v[148:151], v[238:241], v[8:11]
	v_mfma_f32_16x16x32_bf16 v[52:55], v[152:155], v[168:171], v[52:55]
	v_mfma_f32_16x16x32_bf16 v[48:51], v[160:163], v[168:171], v[48:51]
	v_mfma_f32_16x16x32_bf16 v[36:39], v[152:155], v[202:205], v[36:39]
	v_mfma_f32_16x16x32_bf16 v[32:35], v[160:163], v[202:205], v[32:35]
	v_mfma_f32_16x16x32_bf16 v[20:23], v[152:155], v[210:213], v[20:23]
	v_mfma_f32_16x16x32_bf16 v[16:19], v[160:163], v[210:213], v[16:19]
	v_mfma_f32_16x16x32_bf16 v[4:7], v[152:155], v[234:237], v[4:7]
	v_mfma_f32_16x16x32_bf16 v[0:3], v[160:163], v[234:237], v[0:3]
	v_mfma_f32_16x16x32_bf16 v[52:55], v[156:159], v[172:175], v[52:55]
	v_mfma_f32_16x16x32_bf16 v[48:51], v[164:167], v[172:175], v[48:51]
	v_mfma_f32_16x16x32_bf16 v[36:39], v[156:159], v[206:209], v[36:39]
	v_mfma_f32_16x16x32_bf16 v[32:35], v[164:167], v[206:209], v[32:35]
	v_mfma_f32_16x16x32_bf16 v[20:23], v[156:159], v[230:233], v[20:23]
	v_mfma_f32_16x16x32_bf16 v[16:19], v[164:167], v[230:233], v[16:19]
	v_mfma_f32_16x16x32_bf16 v[4:7], v[156:159], v[238:241], v[4:7]
	v_mfma_f32_16x16x32_bf16 v[0:3], v[164:167], v[238:241], v[0:3]
	s_setprio 0
	s_barrier
	s_add_i32 s11, 0, 0x1c000
	v_add_u32_e32 v114, s11, v221
	ds_read_b128 v[120:123], v225
	ds_read_b128 v[124:127], v225 offset:1024
	ds_read_b128 v[144:147], v225 offset:2048
	ds_read_b128 v[148:151], v225 offset:3072
	ds_read_b128 v[152:155], v114
	ds_read_b128 v[156:159], v114 offset:1024
	ds_read_b128 v[160:163], v114 offset:2048
	ds_read_b128 v[164:167], v114 offset:3072
	v_lshl_add_u64 v[114:115], v[214:215], 0, s[16:17]
	s_mov_b32 m0, s44
	v_lshl_add_u64 v[214:215], v[114:115], 0, v[182:183]
	ds_read_b128 v[168:171], v224 offset:32768
	ds_read_b128 v[172:175], v224 offset:33792
	ds_read_b128 v[202:205], v224 offset:34816
	ds_read_b128 v[206:209], v224 offset:35840
	ds_read_b128 v[210:213], v224 offset:36864
	ds_read_b128 v[230:233], v224 offset:37888
	ds_read_b128 v[234:237], v224 offset:38912
	ds_read_b128 v[238:241], v224 offset:39936
	global_load_lds_dwordx4 v[214:215], off
	v_lshl_add_u64 v[114:115], v[114:115], 0, v[186:187]
	s_mov_b32 m0, s45
	s_nop 0
	global_load_lds_dwordx4 v[114:115], off
	s_waitcnt vmcnt(8)
	s_waitcnt lgkmcnt(0)
	s_barrier
	s_setprio 1
	v_mfma_f32_16x16x32_bf16 v[140:143], v[120:123], v[168:171], v[140:143]
	v_mfma_f32_16x16x32_bf16 v[136:139], v[144:147], v[168:171], v[136:139]
	v_mfma_f32_16x16x32_bf16 v[114:117], v[120:123], v[202:205], v[116:119]
	v_mfma_f32_16x16x32_bf16 v[110:113], v[144:147], v[202:205], v[110:113]
	v_mfma_f32_16x16x32_bf16 v[92:95], v[120:123], v[210:213], v[92:95]
	v_mfma_f32_16x16x32_bf16 v[88:91], v[144:147], v[210:213], v[88:91]
	v_mfma_f32_16x16x32_bf16 v[76:79], v[120:123], v[234:237], v[76:79]
	v_mfma_f32_16x16x32_bf16 v[72:75], v[144:147], v[234:237], v[72:75]
	v_mfma_f32_16x16x32_bf16 v[140:143], v[124:127], v[172:175], v[140:143]
	v_mfma_f32_16x16x32_bf16 v[136:139], v[148:151], v[172:175], v[136:139]
	v_mfma_f32_16x16x32_bf16 v[116:119], v[124:127], v[206:209], v[114:117]
	v_mfma_f32_16x16x32_bf16 v[112:115], v[148:151], v[206:209], v[110:113]
	v_mfma_f32_16x16x32_bf16 v[92:95], v[124:127], v[230:233], v[92:95]
	v_mfma_f32_16x16x32_bf16 v[88:91], v[148:151], v[230:233], v[88:91]
	v_mfma_f32_16x16x32_bf16 v[76:79], v[124:127], v[238:241], v[76:79]
	v_mfma_f32_16x16x32_bf16 v[72:75], v[148:151], v[238:241], v[72:75]
	v_mfma_f32_16x16x32_bf16 v[132:135], v[152:155], v[168:171], v[132:135]
	v_mfma_f32_16x16x32_bf16 v[128:131], v[160:163], v[168:171], v[128:131]
	v_mfma_f32_16x16x32_bf16 v[100:103], v[152:155], v[202:205], v[100:103]
	v_mfma_f32_16x16x32_bf16 v[96:99], v[160:163], v[202:205], v[96:99]
	v_mfma_f32_16x16x32_bf16 v[84:87], v[152:155], v[210:213], v[84:87]
	v_mfma_f32_16x16x32_bf16 v[80:83], v[160:163], v[210:213], v[80:83]
	v_mfma_f32_16x16x32_bf16 v[68:71], v[152:155], v[234:237], v[68:71]
	v_mfma_f32_16x16x32_bf16 v[64:67], v[160:163], v[234:237], v[64:67]
	v_mfma_f32_16x16x32_bf16 v[132:135], v[156:159], v[172:175], v[132:135]
	v_mfma_f32_16x16x32_bf16 v[128:131], v[164:167], v[172:175], v[128:131]
	v_mfma_f32_16x16x32_bf16 v[100:103], v[156:159], v[206:209], v[100:103]
	v_mfma_f32_16x16x32_bf16 v[96:99], v[164:167], v[206:209], v[96:99]
	v_mfma_f32_16x16x32_bf16 v[84:87], v[156:159], v[230:233], v[84:87]
	v_mfma_f32_16x16x32_bf16 v[80:83], v[164:167], v[230:233], v[80:83]
	v_mfma_f32_16x16x32_bf16 v[68:71], v[156:159], v[238:241], v[68:71]
	v_mfma_f32_16x16x32_bf16 v[64:67], v[164:167], v[238:241], v[64:67]
	s_setprio 0
	s_barrier
	s_add_i32 s13, s74, s3
	v_lshl_add_u64 v[106:107], v[106:107], 0, s[22:23]
	s_mov_b32 m0, s13
	ds_read_b128 v[168:171], v224 offset:49152
	ds_read_b128 v[172:175], v224 offset:50176
	ds_read_b128 v[202:205], v224 offset:51200
	ds_read_b128 v[206:209], v224 offset:52224
	ds_read_b128 v[210:213], v224 offset:53248
	ds_read_b128 v[230:233], v224 offset:54272
	ds_read_b128 v[234:237], v224 offset:55296
	ds_read_b128 v[238:241], v224 offset:56320
	global_load_lds_dwordx4 v[106:107], off
	v_lshl_add_u64 v[106:107], v[244:245], 0, s[22:23]
	s_add_i32 m0, s13, 0x2000
	s_add_i32 s11, s11, s3
	global_load_lds_dwordx4 v[106:107], off
	v_lshl_add_u64 v[106:107], v[242:243], 0, s[26:27]
	v_lshl_add_u64 v[110:111], v[106:107], 0, v[184:185]
	s_mov_b32 m0, s11
	v_lshl_add_u64 v[106:107], v[106:107], 0, v[188:189]
	global_load_lds_dwordx4 v[110:111], off
	s_add_i32 m0, s11, 0x2000
	s_nop 0
	global_load_lds_dwordx4 v[106:107], off
	v_lshl_add_u64 v[106:107], v[246:247], 0, s[22:23]
	s_mov_b32 m0, s63
	s_nop 0
	global_load_lds_dwordx4 v[106:107], off
	v_lshl_add_u64 v[106:107], v[248:249], 0, s[22:23]
	s_mov_b32 m0, s64
	s_nop 0
	global_load_lds_dwordx4 v[106:107], off
	s_waitcnt vmcnt(8)
	s_waitcnt lgkmcnt(0)
	s_barrier
	s_setprio 1
	v_mfma_f32_16x16x32_bf16 v[60:63], v[120:123], v[168:171], v[60:63]
	v_mfma_f32_16x16x32_bf16 v[56:59], v[144:147], v[168:171], v[56:59]
	v_mfma_f32_16x16x32_bf16 v[44:47], v[120:123], v[202:205], v[44:47]
	v_mfma_f32_16x16x32_bf16 v[40:43], v[144:147], v[202:205], v[40:43]
	v_mfma_f32_16x16x32_bf16 v[28:31], v[120:123], v[210:213], v[28:31]
	v_mfma_f32_16x16x32_bf16 v[24:27], v[144:147], v[210:213], v[24:27]
	v_mfma_f32_16x16x32_bf16 v[12:15], v[120:123], v[234:237], v[12:15]
	v_mfma_f32_16x16x32_bf16 v[8:11], v[144:147], v[234:237], v[8:11]
	v_mfma_f32_16x16x32_bf16 v[60:63], v[124:127], v[172:175], v[60:63]
	v_mfma_f32_16x16x32_bf16 v[56:59], v[148:151], v[172:175], v[56:59]
	v_mfma_f32_16x16x32_bf16 v[44:47], v[124:127], v[206:209], v[44:47]
	v_mfma_f32_16x16x32_bf16 v[40:43], v[148:151], v[206:209], v[40:43]
	v_mfma_f32_16x16x32_bf16 v[28:31], v[124:127], v[230:233], v[28:31]
	v_mfma_f32_16x16x32_bf16 v[24:27], v[148:151], v[230:233], v[24:27]
	v_mfma_f32_16x16x32_bf16 v[12:15], v[124:127], v[238:241], v[12:15]
	v_mfma_f32_16x16x32_bf16 v[8:11], v[148:151], v[238:241], v[8:11]
	v_mfma_f32_16x16x32_bf16 v[52:55], v[152:155], v[168:171], v[52:55]
	v_mfma_f32_16x16x32_bf16 v[48:51], v[160:163], v[168:171], v[48:51]
	v_mfma_f32_16x16x32_bf16 v[36:39], v[152:155], v[202:205], v[36:39]
	v_mfma_f32_16x16x32_bf16 v[32:35], v[160:163], v[202:205], v[32:35]
	v_mfma_f32_16x16x32_bf16 v[20:23], v[152:155], v[210:213], v[20:23]
	v_mfma_f32_16x16x32_bf16 v[16:19], v[160:163], v[210:213], v[16:19]
	v_mfma_f32_16x16x32_bf16 v[4:7], v[152:155], v[234:237], v[4:7]
	v_mfma_f32_16x16x32_bf16 v[0:3], v[160:163], v[234:237], v[0:3]
	v_mfma_f32_16x16x32_bf16 v[52:55], v[156:159], v[172:175], v[52:55]
	v_mfma_f32_16x16x32_bf16 v[48:51], v[164:167], v[172:175], v[48:51]
	v_mfma_f32_16x16x32_bf16 v[36:39], v[156:159], v[206:209], v[36:39]
	v_mfma_f32_16x16x32_bf16 v[32:35], v[164:167], v[206:209], v[32:35]
	v_mfma_f32_16x16x32_bf16 v[20:23], v[156:159], v[230:233], v[20:23]
	v_mfma_f32_16x16x32_bf16 v[16:19], v[164:167], v[230:233], v[16:19]
	v_mfma_f32_16x16x32_bf16 v[4:7], v[156:159], v[238:241], v[4:7]
	v_mfma_f32_16x16x32_bf16 v[0:3], v[164:167], v[238:241], v[0:3]
	s_setprio 0
	s_barrier
	s_add_i32 s10, s10, 2
	v_lshl_add_u64 v[104:105], v[104:105], 0, s[30:31]
	s_cmp_gt_u32 s10, 41
	v_mov_b64_e32 v[106:107], v[108:109]
	s_cbranch_scc0 .LBB0_696
	s_and_b64 vcc, exec, s[28:29]
	s_cbranch_vccz .LBB0_699
	s_barrier

.LBB0_884:
	ds_read_b128 v[120:123], v222
	ds_read_b128 v[124:127], v222 offset:1024
	ds_read_b128 v[144:147], v222 offset:2048
	ds_read_b128 v[148:151], v222 offset:3072
	ds_read_b128 v[152:155], v223
	ds_read_b128 v[156:159], v223 offset:1024
	ds_read_b128 v[160:163], v223 offset:2048
	ds_read_b128 v[164:167], v223 offset:3072
	s_cmp_eq_u32 s10, 40
	v_lshl_add_u64 v[108:109], v[106:107], 0, s[30:31]
	s_cselect_b64 vcc, -1, 0
	v_cndmask_b32_e32 v215, v109, v199, vcc
	v_cndmask_b32_e32 v214, v108, v198, vcc
	v_cndmask_b32_e32 v243, v105, v201, vcc
	v_cndmask_b32_e32 v242, v104, v200, vcc
	s_mov_b32 m0, s70
	v_lshl_add_u64 v[110:111], v[106:107], 0, v[192:193]
	ds_read_b128 v[168:171], v224
	ds_read_b128 v[172:175], v224 offset:1024
	ds_read_b128 v[202:205], v224 offset:2048
	ds_read_b128 v[206:209], v224 offset:3072
	ds_read_b128 v[210:213], v224 offset:4096
	ds_read_b128 v[230:233], v224 offset:5120
	ds_read_b128 v[234:237], v224 offset:6144
	ds_read_b128 v[238:241], v224 offset:7168
	global_load_lds_dwordx4 v[110:111], off
	v_lshl_add_u64 v[106:107], v[106:107], 0, v[190:191]
	s_mov_b32 m0, s71
	s_nop 0
	global_load_lds_dwordx4 v[106:107], off
	s_waitcnt vmcnt(8)
	s_waitcnt lgkmcnt(0)
	s_barrier
	s_setprio 1
	v_mfma_f32_16x16x32_bf16 v[140:143], v[120:123], v[168:171], v[140:143]
	v_mfma_f32_16x16x32_bf16 v[136:139], v[144:147], v[168:171], v[136:139]
	v_mfma_f32_16x16x32_bf16 v[116:119], v[120:123], v[202:205], v[116:119]
	v_mfma_f32_16x16x32_bf16 v[110:113], v[144:147], v[202:205], v[112:115]
	v_mfma_f32_16x16x32_bf16 v[92:95], v[120:123], v[210:213], v[92:95]
	v_mfma_f32_16x16x32_bf16 v[88:91], v[144:147], v[210:213], v[88:91]
	v_mfma_f32_16x16x32_bf16 v[76:79], v[120:123], v[234:237], v[76:79]
	v_mfma_f32_16x16x32_bf16 v[72:75], v[144:147], v[234:237], v[72:75]
	v_mfma_f32_16x16x32_bf16 v[140:143], v[124:127], v[172:175], v[140:143]
	v_mfma_f32_16x16x32_bf16 v[136:139], v[148:151], v[172:175], v[136:139]
	v_mfma_f32_16x16x32_bf16 v[116:119], v[124:127], v[206:209], v[116:119]
	v_mfma_f32_16x16x32_bf16 v[110:113], v[148:151], v[206:209], v[110:113]
	v_mfma_f32_16x16x32_bf16 v[92:95], v[124:127], v[230:233], v[92:95]
	v_mfma_f32_16x16x32_bf16 v[88:91], v[148:151], v[230:233], v[88:91]
	v_mfma_f32_16x16x32_bf16 v[76:79], v[124:127], v[238:241], v[76:79]
	v_mfma_f32_16x16x32_bf16 v[72:75], v[148:151], v[238:241], v[72:75]
	v_mfma_f32_16x16x32_bf16 v[132:135], v[152:155], v[168:171], v[132:135]
	v_mfma_f32_16x16x32_bf16 v[128:131], v[160:163], v[168:171], v[128:131]
	v_mfma_f32_16x16x32_bf16 v[100:103], v[152:155], v[202:205], v[100:103]
	v_mfma_f32_16x16x32_bf16 v[96:99], v[160:163], v[202:205], v[96:99]
	v_mfma_f32_16x16x32_bf16 v[84:87], v[152:155], v[210:213], v[84:87]
	v_mfma_f32_16x16x32_bf16 v[80:83], v[160:163], v[210:213], v[80:83]
	v_mfma_f32_16x16x32_bf16 v[68:71], v[152:155], v[234:237], v[68:71]
	v_mfma_f32_16x16x32_bf16 v[64:67], v[160:163], v[234:237], v[64:67]
	v_mfma_f32_16x16x32_bf16 v[132:135], v[156:159], v[172:175], v[132:135]
	v_mfma_f32_16x16x32_bf16 v[128:131], v[164:167], v[172:175], v[128:131]
	v_mfma_f32_16x16x32_bf16 v[100:103], v[156:159], v[206:209], v[100:103]
	v_mfma_f32_16x16x32_bf16 v[96:99], v[164:167], v[206:209], v[96:99]
	v_mfma_f32_16x16x32_bf16 v[84:87], v[156:159], v[230:233], v[84:87]
	v_mfma_f32_16x16x32_bf16 v[80:83], v[164:167], v[230:233], v[80:83]
	v_mfma_f32_16x16x32_bf16 v[68:71], v[156:159], v[238:241], v[68:71]
	v_mfma_f32_16x16x32_bf16 v[64:67], v[164:167], v[238:241], v[64:67]
	s_setprio 0
	s_barrier
	s_mov_b32 m0, s72
	v_lshl_add_u64 v[106:107], v[242:243], 0, v[184:185]
	ds_read_b128 v[168:171], v224 offset:16384
	ds_read_b128 v[172:175], v224 offset:17408
	ds_read_b128 v[202:205], v224 offset:18432
	ds_read_b128 v[206:209], v224 offset:19456
	ds_read_b128 v[210:213], v224 offset:20480
	ds_read_b128 v[230:233], v224 offset:21504
	ds_read_b128 v[234:237], v224 offset:22528
	ds_read_b128 v[238:241], v224 offset:23552
	global_load_lds_dwordx4 v[106:107], off
	v_lshl_add_u64 v[244:245], v[242:243], 0, v[188:189]
	s_mov_b32 m0, s73
	v_lshl_add_u64 v[114:115], v[242:243], 0, s[16:17]
	global_load_lds_dwordx4 v[244:245], off
	v_lshl_add_u64 v[246:247], v[114:115], 0, v[184:185]
	s_mov_b32 m0, s74
	v_lshl_add_u64 v[114:115], v[114:115], 0, v[188:189]
	global_load_lds_dwordx4 v[246:247], off
	s_mov_b32 m0, s75
	v_lshl_add_u64 v[246:247], v[214:215], 0, v[182:183]
	global_load_lds_dwordx4 v[114:115], off
	s_mov_b32 m0, s42
	v_lshl_add_u64 v[248:249], v[214:215], 0, v[186:187]
	global_load_lds_dwordx4 v[246:247], off
	s_mov_b32 m0, s43
	s_nop 0
	global_load_lds_dwordx4 v[248:249], off
	s_waitcnt vmcnt(8)
	s_waitcnt lgkmcnt(0)
	s_barrier
	s_setprio 1
	v_mfma_f32_16x16x32_bf16 v[60:63], v[120:123], v[168:171], v[60:63]
	v_mfma_f32_16x16x32_bf16 v[56:59], v[144:147], v[168:171], v[56:59]
	v_mfma_f32_16x16x32_bf16 v[44:47], v[120:123], v[202:205], v[44:47]
	v_mfma_f32_16x16x32_bf16 v[40:43], v[144:147], v[202:205], v[40:43]
	v_mfma_f32_16x16x32_bf16 v[28:31], v[120:123], v[210:213], v[28:31]
	v_mfma_f32_16x16x32_bf16 v[24:27], v[144:147], v[210:213], v[24:27]
	v_mfma_f32_16x16x32_bf16 v[12:15], v[120:123], v[234:237], v[12:15]
	v_mfma_f32_16x16x32_bf16 v[8:11], v[144:147], v[234:237], v[8:11]
	v_mfma_f32_16x16x32_bf16 v[60:63], v[124:127], v[172:175], v[60:63]
	v_mfma_f32_16x16x32_bf16 v[56:59], v[148:151], v[172:175], v[56:59]
	v_mfma_f32_16x16x32_bf16 v[44:47], v[124:127], v[206:209], v[44:47]
	v_mfma_f32_16x16x32_bf16 v[40:43], v[148:151], v[206:209], v[40:43]
	v_mfma_f32_16x16x32_bf16 v[28:31], v[124:127], v[230:233], v[28:31]
	v_mfma_f32_16x16x32_bf16 v[24:27], v[148:151], v[230:233], v[24:27]
	v_mfma_f32_16x16x32_bf16 v[12:15], v[124:127], v[238:241], v[12:15]
	v_mfma_f32_16x16x32_bf16 v[8:11], v[148:151], v[238:241], v[8:11]
	v_mfma_f32_16x16x32_bf16 v[52:55], v[152:155], v[168:171], v[52:55]
	v_mfma_f32_16x16x32_bf16 v[48:51], v[160:163], v[168:171], v[48:51]
	v_mfma_f32_16x16x32_bf16 v[36:39], v[152:155], v[202:205], v[36:39]
	v_mfma_f32_16x16x32_bf16 v[32:35], v[160:163], v[202:205], v[32:35]
	v_mfma_f32_16x16x32_bf16 v[20:23], v[152:155], v[210:213], v[20:23]
	v_mfma_f32_16x16x32_bf16 v[16:19], v[160:163], v[210:213], v[16:19]
	v_mfma_f32_16x16x32_bf16 v[4:7], v[152:155], v[234:237], v[4:7]
	v_mfma_f32_16x16x32_bf16 v[0:3], v[160:163], v[234:237], v[0:3]
	v_mfma_f32_16x16x32_bf16 v[52:55], v[156:159], v[172:175], v[52:55]
	v_mfma_f32_16x16x32_bf16 v[48:51], v[164:167], v[172:175], v[48:51]
	v_mfma_f32_16x16x32_bf16 v[36:39], v[156:159], v[206:209], v[36:39]
	v_mfma_f32_16x16x32_bf16 v[32:35], v[164:167], v[206:209], v[32:35]
	v_mfma_f32_16x16x32_bf16 v[20:23], v[156:159], v[230:233], v[20:23]
	v_mfma_f32_16x16x32_bf16 v[16:19], v[164:167], v[230:233], v[16:19]
	v_mfma_f32_16x16x32_bf16 v[4:7], v[156:159], v[238:241], v[4:7]
	v_mfma_f32_16x16x32_bf16 v[0:3], v[164:167], v[238:241], v[0:3]
	s_setprio 0
	s_barrier
	s_add_i32 s11, 0, 0x1c000
	v_add_u32_e32 v114, s11, v221
	ds_read_b128 v[120:123], v225
	ds_read_b128 v[124:127], v225 offset:1024
	ds_read_b128 v[144:147], v225 offset:2048
	ds_read_b128 v[148:151], v225 offset:3072
	ds_read_b128 v[152:155], v114
	ds_read_b128 v[156:159], v114 offset:1024
	ds_read_b128 v[160:163], v114 offset:2048
	ds_read_b128 v[164:167], v114 offset:3072
	v_lshl_add_u64 v[114:115], v[214:215], 0, s[16:17]
	s_mov_b32 m0, s44
	v_lshl_add_u64 v[214:215], v[114:115], 0, v[182:183]
	ds_read_b128 v[168:171], v224 offset:32768
	ds_read_b128 v[172:175], v224 offset:33792
	ds_read_b128 v[202:205], v224 offset:34816
	ds_read_b128 v[206:209], v224 offset:35840
	ds_read_b128 v[210:213], v224 offset:36864
	ds_read_b128 v[230:233], v224 offset:37888
	ds_read_b128 v[234:237], v224 offset:38912
	ds_read_b128 v[238:241], v224 offset:39936
	global_load_lds_dwordx4 v[214:215], off
	v_lshl_add_u64 v[114:115], v[114:115], 0, v[186:187]
	s_mov_b32 m0, s45
	s_nop 0
	global_load_lds_dwordx4 v[114:115], off
	s_waitcnt vmcnt(8)
	s_waitcnt lgkmcnt(0)
	s_barrier
	s_setprio 1
	v_mfma_f32_16x16x32_bf16 v[140:143], v[120:123], v[168:171], v[140:143]
	v_mfma_f32_16x16x32_bf16 v[136:139], v[144:147], v[168:171], v[136:139]
	v_mfma_f32_16x16x32_bf16 v[114:117], v[120:123], v[202:205], v[116:119]
	v_mfma_f32_16x16x32_bf16 v[110:113], v[144:147], v[202:205], v[110:113]
	v_mfma_f32_16x16x32_bf16 v[92:95], v[120:123], v[210:213], v[92:95]
	v_mfma_f32_16x16x32_bf16 v[88:91], v[144:147], v[210:213], v[88:91]
	v_mfma_f32_16x16x32_bf16 v[76:79], v[120:123], v[234:237], v[76:79]
	v_mfma_f32_16x16x32_bf16 v[72:75], v[144:147], v[234:237], v[72:75]
	v_mfma_f32_16x16x32_bf16 v[140:143], v[124:127], v[172:175], v[140:143]
	v_mfma_f32_16x16x32_bf16 v[136:139], v[148:151], v[172:175], v[136:139]
	v_mfma_f32_16x16x32_bf16 v[116:119], v[124:127], v[206:209], v[114:117]
	v_mfma_f32_16x16x32_bf16 v[112:115], v[148:151], v[206:209], v[110:113]
	v_mfma_f32_16x16x32_bf16 v[92:95], v[124:127], v[230:233], v[92:95]
	v_mfma_f32_16x16x32_bf16 v[88:91], v[148:151], v[230:233], v[88:91]
	v_mfma_f32_16x16x32_bf16 v[76:79], v[124:127], v[238:241], v[76:79]
	v_mfma_f32_16x16x32_bf16 v[72:75], v[148:151], v[238:241], v[72:75]
	v_mfma_f32_16x16x32_bf16 v[132:135], v[152:155], v[168:171], v[132:135]
	v_mfma_f32_16x16x32_bf16 v[128:131], v[160:163], v[168:171], v[128:131]
	v_mfma_f32_16x16x32_bf16 v[100:103], v[152:155], v[202:205], v[100:103]
	v_mfma_f32_16x16x32_bf16 v[96:99], v[160:163], v[202:205], v[96:99]
	v_mfma_f32_16x16x32_bf16 v[84:87], v[152:155], v[210:213], v[84:87]
	v_mfma_f32_16x16x32_bf16 v[80:83], v[160:163], v[210:213], v[80:83]
	v_mfma_f32_16x16x32_bf16 v[68:71], v[152:155], v[234:237], v[68:71]
	v_mfma_f32_16x16x32_bf16 v[64:67], v[160:163], v[234:237], v[64:67]
	v_mfma_f32_16x16x32_bf16 v[132:135], v[156:159], v[172:175], v[132:135]
	v_mfma_f32_16x16x32_bf16 v[128:131], v[164:167], v[172:175], v[128:131]
	v_mfma_f32_16x16x32_bf16 v[100:103], v[156:159], v[206:209], v[100:103]
	v_mfma_f32_16x16x32_bf16 v[96:99], v[164:167], v[206:209], v[96:99]
	v_mfma_f32_16x16x32_bf16 v[84:87], v[156:159], v[230:233], v[84:87]
	v_mfma_f32_16x16x32_bf16 v[80:83], v[164:167], v[230:233], v[80:83]
	v_mfma_f32_16x16x32_bf16 v[68:71], v[156:159], v[238:241], v[68:71]
	v_mfma_f32_16x16x32_bf16 v[64:67], v[164:167], v[238:241], v[64:67]
	s_setprio 0
	s_barrier
	s_add_i32 s12, s76, s3
	v_lshl_add_u64 v[106:107], v[106:107], 0, s[22:23]
	s_mov_b32 m0, s12
	ds_read_b128 v[168:171], v224 offset:49152
	ds_read_b128 v[172:175], v224 offset:50176
	ds_read_b128 v[202:205], v224 offset:51200
	ds_read_b128 v[206:209], v224 offset:52224
	ds_read_b128 v[210:213], v224 offset:53248
	ds_read_b128 v[230:233], v224 offset:54272
	ds_read_b128 v[234:237], v224 offset:55296
	ds_read_b128 v[238:241], v224 offset:56320
	global_load_lds_dwordx4 v[106:107], off
	v_lshl_add_u64 v[106:107], v[244:245], 0, s[22:23]
	s_add_i32 m0, s12, 0x2000
	s_add_i32 s11, s11, s3
	global_load_lds_dwordx4 v[106:107], off
	v_lshl_add_u64 v[106:107], v[242:243], 0, s[26:27]
	v_lshl_add_u64 v[110:111], v[106:107], 0, v[184:185]
	s_mov_b32 m0, s11
	v_lshl_add_u64 v[106:107], v[106:107], 0, v[188:189]
	global_load_lds_dwordx4 v[110:111], off
	s_add_i32 m0, s11, 0x2000
	s_nop 0
	global_load_lds_dwordx4 v[106:107], off
	v_lshl_add_u64 v[106:107], v[246:247], 0, s[22:23]
	s_mov_b32 m0, s65
	s_nop 0
	global_load_lds_dwordx4 v[106:107], off
	v_lshl_add_u64 v[106:107], v[248:249], 0, s[22:23]
	s_mov_b32 m0, s66
	s_nop 0
	global_load_lds_dwordx4 v[106:107], off
	s_waitcnt vmcnt(8)
	s_waitcnt lgkmcnt(0)
	s_barrier
	s_setprio 1
	v_mfma_f32_16x16x32_bf16 v[60:63], v[120:123], v[168:171], v[60:63]
	v_mfma_f32_16x16x32_bf16 v[56:59], v[144:147], v[168:171], v[56:59]
	v_mfma_f32_16x16x32_bf16 v[44:47], v[120:123], v[202:205], v[44:47]
	v_mfma_f32_16x16x32_bf16 v[40:43], v[144:147], v[202:205], v[40:43]
	v_mfma_f32_16x16x32_bf16 v[28:31], v[120:123], v[210:213], v[28:31]
	v_mfma_f32_16x16x32_bf16 v[24:27], v[144:147], v[210:213], v[24:27]
	v_mfma_f32_16x16x32_bf16 v[12:15], v[120:123], v[234:237], v[12:15]
	v_mfma_f32_16x16x32_bf16 v[8:11], v[144:147], v[234:237], v[8:11]
	v_mfma_f32_16x16x32_bf16 v[60:63], v[124:127], v[172:175], v[60:63]
	v_mfma_f32_16x16x32_bf16 v[56:59], v[148:151], v[172:175], v[56:59]
	v_mfma_f32_16x16x32_bf16 v[44:47], v[124:127], v[206:209], v[44:47]
	v_mfma_f32_16x16x32_bf16 v[40:43], v[148:151], v[206:209], v[40:43]
	v_mfma_f32_16x16x32_bf16 v[28:31], v[124:127], v[230:233], v[28:31]
	v_mfma_f32_16x16x32_bf16 v[24:27], v[148:151], v[230:233], v[24:27]
	v_mfma_f32_16x16x32_bf16 v[12:15], v[124:127], v[238:241], v[12:15]
	v_mfma_f32_16x16x32_bf16 v[8:11], v[148:151], v[238:241], v[8:11]
	v_mfma_f32_16x16x32_bf16 v[52:55], v[152:155], v[168:171], v[52:55]
	v_mfma_f32_16x16x32_bf16 v[48:51], v[160:163], v[168:171], v[48:51]
	v_mfma_f32_16x16x32_bf16 v[36:39], v[152:155], v[202:205], v[36:39]
	v_mfma_f32_16x16x32_bf16 v[32:35], v[160:163], v[202:205], v[32:35]
	v_mfma_f32_16x16x32_bf16 v[20:23], v[152:155], v[210:213], v[20:23]
	v_mfma_f32_16x16x32_bf16 v[16:19], v[160:163], v[210:213], v[16:19]
	v_mfma_f32_16x16x32_bf16 v[4:7], v[152:155], v[234:237], v[4:7]
	v_mfma_f32_16x16x32_bf16 v[0:3], v[160:163], v[234:237], v[0:3]
	v_mfma_f32_16x16x32_bf16 v[52:55], v[156:159], v[172:175], v[52:55]
	v_mfma_f32_16x16x32_bf16 v[48:51], v[164:167], v[172:175], v[48:51]
	v_mfma_f32_16x16x32_bf16 v[36:39], v[156:159], v[206:209], v[36:39]
	v_mfma_f32_16x16x32_bf16 v[32:35], v[164:167], v[206:209], v[32:35]
	v_mfma_f32_16x16x32_bf16 v[20:23], v[156:159], v[230:233], v[20:23]
	v_mfma_f32_16x16x32_bf16 v[16:19], v[164:167], v[230:233], v[16:19]
	v_mfma_f32_16x16x32_bf16 v[4:7], v[156:159], v[238:241], v[4:7]
	v_mfma_f32_16x16x32_bf16 v[0:3], v[164:167], v[238:241], v[0:3]
	s_setprio 0
	s_barrier
	s_add_i32 s10, s10, 2
	v_lshl_add_u64 v[104:105], v[104:105], 0, s[30:31]
	s_cmp_gt_u32 s10, 41
	v_mov_b64_e32 v[106:107], v[108:109]
	s_cbranch_scc0 .LBB0_884
	s_and_b64 vcc, exec, s[28:29]
	s_cbranch_vccz .LBB0_887
	s_barrier

.LBB0_995:
	v_add_u32_e32 v186, s42, v167
	v_add_u32_e32 v202, s43, v167
	ds_read_b128 v[172:175], v186
	ds_read_b128 v[178:181], v186 offset:1024
	ds_read_b128 v[182:185], v186 offset:2048
	ds_read_b128 v[186:189], v186 offset:3072
	ds_read_b128 v[190:193], v202
	ds_read_b128 v[194:197], v202 offset:1024
	ds_read_b128 v[198:201], v202 offset:2048
	ds_read_b128 v[202:205], v202 offset:3072
	v_lshl_add_u64 v[206:207], v[164:165], 0, s[26:27]
	v_cndmask_b32_e64 v215, v207, v157, s[10:11]
	v_cndmask_b32_e64 v214, v206, v156, s[10:11]
	v_cndmask_b32_e64 v243, v163, v159, s[10:11]
	v_cndmask_b32_e64 v242, v162, v158, s[10:11]
	s_mov_b32 m0, s44
	v_lshl_add_u64 v[244:245], v[164:165], 0, v[146:147]
	ds_read_b128 v[206:209], v170
	ds_read_b128 v[210:213], v170 offset:1024
	ds_read_b128 v[218:221], v170 offset:2048
	ds_read_b128 v[222:225], v170 offset:3072
	ds_read_b128 v[226:229], v170 offset:4096
	ds_read_b128 v[230:233], v170 offset:5120
	ds_read_b128 v[234:237], v170 offset:6144
	ds_read_b128 v[238:241], v170 offset:7168
	global_load_lds_dwordx4 v[244:245], off
	v_lshl_add_u64 v[244:245], v[164:165], 0, v[144:145]
	s_mov_b32 m0, s45
	s_nop 0
	global_load_lds_dwordx4 v[244:245], off
	s_waitcnt vmcnt(8)
	s_waitcnt lgkmcnt(0)
	s_barrier
	s_setprio 1
	v_mfma_f32_16x16x32_bf16 v[124:127], v[172:175], v[206:209], v[124:127]
	v_mfma_f32_16x16x32_bf16 v[120:123], v[182:185], v[206:209], v[120:123]
	v_mfma_f32_16x16x32_bf16 v[108:111], v[172:175], v[218:221], v[108:111]
	v_mfma_f32_16x16x32_bf16 v[104:107], v[182:185], v[218:221], v[104:107]
	v_mfma_f32_16x16x32_bf16 v[92:95], v[172:175], v[226:229], v[92:95]
	v_mfma_f32_16x16x32_bf16 v[88:91], v[182:185], v[226:229], v[88:91]
	v_mfma_f32_16x16x32_bf16 v[76:79], v[172:175], v[234:237], v[76:79]
	v_mfma_f32_16x16x32_bf16 v[72:75], v[182:185], v[234:237], v[72:75]
	v_mfma_f32_16x16x32_bf16 v[124:127], v[178:181], v[210:213], v[124:127]
	v_mfma_f32_16x16x32_bf16 v[120:123], v[186:189], v[210:213], v[120:123]
	v_mfma_f32_16x16x32_bf16 v[108:111], v[178:181], v[222:225], v[108:111]
	v_mfma_f32_16x16x32_bf16 v[104:107], v[186:189], v[222:225], v[104:107]
	v_mfma_f32_16x16x32_bf16 v[92:95], v[178:181], v[230:233], v[92:95]
	v_mfma_f32_16x16x32_bf16 v[88:91], v[186:189], v[230:233], v[88:91]
	v_mfma_f32_16x16x32_bf16 v[76:79], v[178:181], v[238:241], v[76:79]
	v_mfma_f32_16x16x32_bf16 v[72:75], v[186:189], v[238:241], v[72:75]
	v_mfma_f32_16x16x32_bf16 v[116:119], v[190:193], v[206:209], v[116:119]
	v_mfma_f32_16x16x32_bf16 v[112:115], v[198:201], v[206:209], v[112:115]
	v_mfma_f32_16x16x32_bf16 v[100:103], v[190:193], v[218:221], v[100:103]
	v_mfma_f32_16x16x32_bf16 v[96:99], v[198:201], v[218:221], v[96:99]
	v_mfma_f32_16x16x32_bf16 v[84:87], v[190:193], v[226:229], v[84:87]
	v_mfma_f32_16x16x32_bf16 v[80:83], v[198:201], v[226:229], v[80:83]
	v_mfma_f32_16x16x32_bf16 v[68:71], v[190:193], v[234:237], v[68:71]
	v_mfma_f32_16x16x32_bf16 v[64:67], v[198:201], v[234:237], v[64:67]
	v_mfma_f32_16x16x32_bf16 v[116:119], v[194:197], v[210:213], v[116:119]
	v_mfma_f32_16x16x32_bf16 v[112:115], v[202:205], v[210:213], v[112:115]
	v_mfma_f32_16x16x32_bf16 v[100:103], v[194:197], v[222:225], v[100:103]
	v_mfma_f32_16x16x32_bf16 v[96:99], v[202:205], v[222:225], v[96:99]
	v_mfma_f32_16x16x32_bf16 v[84:87], v[194:197], v[230:233], v[84:87]
	v_mfma_f32_16x16x32_bf16 v[80:83], v[202:205], v[230:233], v[80:83]
	v_mfma_f32_16x16x32_bf16 v[68:71], v[194:197], v[238:241], v[68:71]
	v_mfma_f32_16x16x32_bf16 v[64:67], v[202:205], v[238:241], v[64:67]
	s_setprio 0
	s_barrier
	s_add_i32 s10, s42, s3
	v_lshl_add_u64 v[244:245], v[242:243], 0, v[134:135]
	s_mov_b32 m0, s10
	ds_read_b128 v[206:209], v170 offset:16384
	ds_read_b128 v[210:213], v170 offset:17408
	ds_read_b128 v[218:221], v170 offset:18432
	ds_read_b128 v[222:225], v170 offset:19456
	ds_read_b128 v[226:229], v170 offset:20480
	ds_read_b128 v[230:233], v170 offset:21504
	ds_read_b128 v[234:237], v170 offset:22528
	ds_read_b128 v[238:241], v170 offset:23552
	global_load_lds_dwordx4 v[244:245], off
	v_lshl_add_u64 v[246:247], v[242:243], 0, v[140:141]
	s_add_i32 m0, s10, 0x2000
	v_lshl_add_u64 v[248:249], v[242:243], 0, s[12:13]
	s_add_i32 s10, s43, s3
	global_load_lds_dwordx4 v[246:247], off
	v_lshl_add_u64 v[250:251], v[248:249], 0, v[134:135]
	s_mov_b32 m0, s10
	v_lshl_add_u64 v[248:249], v[248:249], 0, v[140:141]
	global_load_lds_dwordx4 v[250:251], off
	s_add_i32 m0, s10, 0x2000
	v_lshl_add_u64 v[250:251], v[214:215], 0, v[138:139]
	global_load_lds_dwordx4 v[248:249], off
	v_lshl_add_u64 v[248:249], v[214:215], 0, v[136:137]
	s_mov_b32 m0, s35
	s_nop 0
	global_load_lds_dwordx4 v[248:249], off
	s_mov_b32 m0, s36
	s_nop 0
	global_load_lds_dwordx4 v[250:251], off
	s_waitcnt vmcnt(8)
	s_waitcnt lgkmcnt(0)
	s_barrier
	s_setprio 1
	v_mfma_f32_16x16x32_bf16 v[60:63], v[172:175], v[206:209], v[60:63]
	v_mfma_f32_16x16x32_bf16 v[56:59], v[182:185], v[206:209], v[56:59]
	v_mfma_f32_16x16x32_bf16 v[44:47], v[172:175], v[218:221], v[44:47]
	v_mfma_f32_16x16x32_bf16 v[40:43], v[182:185], v[218:221], v[40:43]
	v_mfma_f32_16x16x32_bf16 v[28:31], v[172:175], v[226:229], v[28:31]
	v_mfma_f32_16x16x32_bf16 v[24:27], v[182:185], v[226:229], v[24:27]
	v_mfma_f32_16x16x32_bf16 v[12:15], v[172:175], v[234:237], v[12:15]
	v_mfma_f32_16x16x32_bf16 v[8:11], v[182:185], v[234:237], v[8:11]
	v_mfma_f32_16x16x32_bf16 v[60:63], v[178:181], v[210:213], v[60:63]
	v_mfma_f32_16x16x32_bf16 v[56:59], v[186:189], v[210:213], v[56:59]
	v_mfma_f32_16x16x32_bf16 v[44:47], v[178:181], v[222:225], v[44:47]
	v_mfma_f32_16x16x32_bf16 v[40:43], v[186:189], v[222:225], v[40:43]
	v_mfma_f32_16x16x32_bf16 v[28:31], v[178:181], v[230:233], v[28:31]
	v_mfma_f32_16x16x32_bf16 v[24:27], v[186:189], v[230:233], v[24:27]
	v_mfma_f32_16x16x32_bf16 v[12:15], v[178:181], v[238:241], v[12:15]
	v_mfma_f32_16x16x32_bf16 v[8:11], v[186:189], v[238:241], v[8:11]
	v_mfma_f32_16x16x32_bf16 v[52:55], v[190:193], v[206:209], v[52:55]
	v_mfma_f32_16x16x32_bf16 v[48:51], v[198:201], v[206:209], v[48:51]
	v_mfma_f32_16x16x32_bf16 v[36:39], v[190:193], v[218:221], v[36:39]
	v_mfma_f32_16x16x32_bf16 v[32:35], v[198:201], v[218:221], v[32:35]
	v_mfma_f32_16x16x32_bf16 v[20:23], v[190:193], v[226:229], v[20:23]
	v_mfma_f32_16x16x32_bf16 v[16:19], v[198:201], v[226:229], v[16:19]
	v_mfma_f32_16x16x32_bf16 v[4:7], v[190:193], v[234:237], v[4:7]
	v_mfma_f32_16x16x32_bf16 v[0:3], v[198:201], v[234:237], v[0:3]
	v_mfma_f32_16x16x32_bf16 v[52:55], v[194:197], v[210:213], v[52:55]
	v_mfma_f32_16x16x32_bf16 v[48:51], v[202:205], v[210:213], v[48:51]
	v_mfma_f32_16x16x32_bf16 v[36:39], v[194:197], v[222:225], v[36:39]
	v_mfma_f32_16x16x32_bf16 v[32:35], v[202:205], v[222:225], v[32:35]
	v_mfma_f32_16x16x32_bf16 v[20:23], v[194:197], v[230:233], v[20:23]
	v_mfma_f32_16x16x32_bf16 v[16:19], v[202:205], v[230:233], v[16:19]
	v_mfma_f32_16x16x32_bf16 v[4:7], v[194:197], v[238:241], v[4:7]
	v_mfma_f32_16x16x32_bf16 v[0:3], v[202:205], v[238:241], v[0:3]
	s_setprio 0
	s_barrier
	s_add_i32 s10, 0, 0x18000
	s_add_i32 s11, 0, 0x1c000
	v_add_u32_e32 v186, s10, v167
	v_add_u32_e32 v202, s11, v167
	ds_read_b128 v[172:175], v186
	ds_read_b128 v[178:181], v186 offset:1024
	ds_read_b128 v[182:185], v186 offset:2048
	ds_read_b128 v[186:189], v186 offset:3072
	ds_read_b128 v[190:193], v202
	ds_read_b128 v[194:197], v202 offset:1024
	ds_read_b128 v[198:201], v202 offset:2048
	ds_read_b128 v[202:205], v202 offset:3072
	v_lshl_add_u64 v[214:215], v[214:215], 0, s[12:13]
	s_mov_b32 m0, s37
	v_lshl_add_u64 v[252:253], v[214:215], 0, v[136:137]
	ds_read_b128 v[206:209], v170 offset:32768
	ds_read_b128 v[210:213], v170 offset:33792
	ds_read_b128 v[218:221], v170 offset:34816
	ds_read_b128 v[222:225], v170 offset:35840
	ds_read_b128 v[226:229], v170 offset:36864
	ds_read_b128 v[230:233], v170 offset:37888
	ds_read_b128 v[234:237], v170 offset:38912
	ds_read_b128 v[238:241], v170 offset:39936
	global_load_lds_dwordx4 v[252:253], off
	v_lshl_add_u64 v[214:215], v[214:215], 0, v[138:139]
	s_mov_b32 m0, s38
	s_nop 0
	global_load_lds_dwordx4 v[214:215], off
	s_waitcnt vmcnt(8)
	s_waitcnt lgkmcnt(0)
	s_barrier
	s_setprio 1
	v_mfma_f32_16x16x32_bf16 v[124:127], v[172:175], v[206:209], v[124:127]
	v_mfma_f32_16x16x32_bf16 v[120:123], v[182:185], v[206:209], v[120:123]
	v_mfma_f32_16x16x32_bf16 v[108:111], v[172:175], v[218:221], v[108:111]
	v_mfma_f32_16x16x32_bf16 v[104:107], v[182:185], v[218:221], v[104:107]
	v_mfma_f32_16x16x32_bf16 v[92:95], v[172:175], v[226:229], v[92:95]
	v_mfma_f32_16x16x32_bf16 v[88:91], v[182:185], v[226:229], v[88:91]
	v_mfma_f32_16x16x32_bf16 v[76:79], v[172:175], v[234:237], v[76:79]
	v_mfma_f32_16x16x32_bf16 v[72:75], v[182:185], v[234:237], v[72:75]
	v_mfma_f32_16x16x32_bf16 v[124:127], v[178:181], v[210:213], v[124:127]
	v_mfma_f32_16x16x32_bf16 v[120:123], v[186:189], v[210:213], v[120:123]
	v_mfma_f32_16x16x32_bf16 v[108:111], v[178:181], v[222:225], v[108:111]
	v_mfma_f32_16x16x32_bf16 v[104:107], v[186:189], v[222:225], v[104:107]
	v_mfma_f32_16x16x32_bf16 v[92:95], v[178:181], v[230:233], v[92:95]
	v_mfma_f32_16x16x32_bf16 v[88:91], v[186:189], v[230:233], v[88:91]
	v_mfma_f32_16x16x32_bf16 v[76:79], v[178:181], v[238:241], v[76:79]
	v_mfma_f32_16x16x32_bf16 v[72:75], v[186:189], v[238:241], v[72:75]
	v_mfma_f32_16x16x32_bf16 v[116:119], v[190:193], v[206:209], v[116:119]
	v_mfma_f32_16x16x32_bf16 v[112:115], v[198:201], v[206:209], v[112:115]
	v_mfma_f32_16x16x32_bf16 v[100:103], v[190:193], v[218:221], v[100:103]
	v_mfma_f32_16x16x32_bf16 v[96:99], v[198:201], v[218:221], v[96:99]
	v_mfma_f32_16x16x32_bf16 v[84:87], v[190:193], v[226:229], v[84:87]
	v_mfma_f32_16x16x32_bf16 v[80:83], v[198:201], v[226:229], v[80:83]
	v_mfma_f32_16x16x32_bf16 v[68:71], v[190:193], v[234:237], v[68:71]
	v_mfma_f32_16x16x32_bf16 v[64:67], v[198:201], v[234:237], v[64:67]
	v_mfma_f32_16x16x32_bf16 v[116:119], v[194:197], v[210:213], v[116:119]
	v_mfma_f32_16x16x32_bf16 v[112:115], v[202:205], v[210:213], v[112:115]
	v_mfma_f32_16x16x32_bf16 v[100:103], v[194:197], v[222:225], v[100:103]
	v_mfma_f32_16x16x32_bf16 v[96:99], v[202:205], v[222:225], v[96:99]
	v_mfma_f32_16x16x32_bf16 v[84:87], v[194:197], v[230:233], v[84:87]
	v_mfma_f32_16x16x32_bf16 v[80:83], v[202:205], v[230:233], v[80:83]
	v_mfma_f32_16x16x32_bf16 v[68:71], v[194:197], v[238:241], v[68:71]
	v_mfma_f32_16x16x32_bf16 v[64:67], v[202:205], v[238:241], v[64:67]
	s_setprio 0
	s_barrier
	s_add_i32 s10, s10, s3
	v_lshl_add_u64 v[214:215], v[244:245], 0, s[16:17]
	s_mov_b32 m0, s10
	ds_read_b128 v[206:209], v170 offset:49152
	ds_read_b128 v[210:213], v170 offset:50176
	ds_read_b128 v[218:221], v170 offset:51200
	ds_read_b128 v[222:225], v170 offset:52224
	ds_read_b128 v[226:229], v170 offset:53248
	ds_read_b128 v[230:233], v170 offset:54272
	ds_read_b128 v[234:237], v170 offset:55296
	ds_read_b128 v[238:241], v170 offset:56320
	global_load_lds_dwordx4 v[214:215], off
	v_lshl_add_u64 v[214:215], v[246:247], 0, s[16:17]
	s_add_i32 m0, s10, 0x2000
	s_add_i32 s10, s11, s3
	global_load_lds_dwordx4 v[214:215], off
	v_lshl_add_u64 v[214:215], v[242:243], 0, s[18:19]
	v_lshl_add_u64 v[242:243], v[214:215], 0, v[134:135]
	s_mov_b32 m0, s10
	v_lshl_add_u64 v[214:215], v[214:215], 0, v[140:141]
	global_load_lds_dwordx4 v[242:243], off
	s_add_i32 m0, s10, 0x2000
	s_nop 0
	global_load_lds_dwordx4 v[214:215], off
	v_lshl_add_u64 v[214:215], v[248:249], 0, s[16:17]
	s_mov_b32 m0, s39
	s_nop 0
	global_load_lds_dwordx4 v[214:215], off
	v_lshl_add_u64 v[214:215], v[250:251], 0, s[16:17]
	s_mov_b32 m0, s40
	s_nop 0
	global_load_lds_dwordx4 v[214:215], off
	s_waitcnt vmcnt(8)
	s_waitcnt lgkmcnt(0)
	s_barrier
	s_setprio 1
	v_mfma_f32_16x16x32_bf16 v[60:63], v[172:175], v[206:209], v[60:63]
	v_mfma_f32_16x16x32_bf16 v[56:59], v[182:185], v[206:209], v[56:59]
	v_mfma_f32_16x16x32_bf16 v[44:47], v[172:175], v[218:221], v[44:47]
	v_mfma_f32_16x16x32_bf16 v[40:43], v[182:185], v[218:221], v[40:43]
	v_mfma_f32_16x16x32_bf16 v[28:31], v[172:175], v[226:229], v[28:31]
	v_mfma_f32_16x16x32_bf16 v[24:27], v[182:185], v[226:229], v[24:27]
	v_mfma_f32_16x16x32_bf16 v[12:15], v[172:175], v[234:237], v[12:15]
	v_mfma_f32_16x16x32_bf16 v[8:11], v[182:185], v[234:237], v[8:11]
	v_mfma_f32_16x16x32_bf16 v[60:63], v[178:181], v[210:213], v[60:63]
	v_mfma_f32_16x16x32_bf16 v[56:59], v[186:189], v[210:213], v[56:59]
	v_mfma_f32_16x16x32_bf16 v[44:47], v[178:181], v[222:225], v[44:47]
	v_mfma_f32_16x16x32_bf16 v[40:43], v[186:189], v[222:225], v[40:43]
	v_mfma_f32_16x16x32_bf16 v[28:31], v[178:181], v[230:233], v[28:31]
	v_mfma_f32_16x16x32_bf16 v[24:27], v[186:189], v[230:233], v[24:27]
	v_mfma_f32_16x16x32_bf16 v[12:15], v[178:181], v[238:241], v[12:15]
	v_mfma_f32_16x16x32_bf16 v[8:11], v[186:189], v[238:241], v[8:11]
	v_mfma_f32_16x16x32_bf16 v[52:55], v[190:193], v[206:209], v[52:55]
	v_mfma_f32_16x16x32_bf16 v[48:51], v[198:201], v[206:209], v[48:51]
	v_mfma_f32_16x16x32_bf16 v[36:39], v[190:193], v[218:221], v[36:39]
	v_mfma_f32_16x16x32_bf16 v[32:35], v[198:201], v[218:221], v[32:35]
	v_mfma_f32_16x16x32_bf16 v[20:23], v[190:193], v[226:229], v[20:23]
	v_mfma_f32_16x16x32_bf16 v[16:19], v[198:201], v[226:229], v[16:19]
	v_mfma_f32_16x16x32_bf16 v[4:7], v[190:193], v[234:237], v[4:7]
	v_mfma_f32_16x16x32_bf16 v[0:3], v[198:201], v[234:237], v[0:3]
	v_mfma_f32_16x16x32_bf16 v[52:55], v[194:197], v[210:213], v[52:55]
	v_mfma_f32_16x16x32_bf16 v[48:51], v[202:205], v[210:213], v[48:51]
	v_mfma_f32_16x16x32_bf16 v[36:39], v[194:197], v[222:225], v[36:39]
	v_mfma_f32_16x16x32_bf16 v[32:35], v[202:205], v[222:225], v[32:35]
	v_mfma_f32_16x16x32_bf16 v[20:23], v[194:197], v[230:233], v[20:23]
	v_mfma_f32_16x16x32_bf16 v[16:19], v[202:205], v[230:233], v[16:19]
	v_mfma_f32_16x16x32_bf16 v[4:7], v[194:197], v[238:241], v[4:7]
	v_mfma_f32_16x16x32_bf16 v[0:3], v[202:205], v[238:241], v[0:3]
	s_setprio 0
	s_barrier
	s_add_i32 s31, s31, 2
	v_lshl_add_u64 v[162:163], v[162:163], 0, s[22:23]
	s_cmp_gt_u32 s31, 13
	v_lshl_add_u64 v[164:165], v[164:165], 0, s[22:23]
	s_cbranch_scc1 .LBB0_999

.LBB0_1245:
	ds_read_b128 v[120:123], v220
	ds_read_b128 v[124:127], v220 offset:1024
	ds_read_b128 v[144:147], v220 offset:2048
	ds_read_b128 v[148:151], v220 offset:3072
	ds_read_b128 v[152:155], v221
	ds_read_b128 v[156:159], v221 offset:1024
	ds_read_b128 v[160:163], v221 offset:2048
	ds_read_b128 v[164:167], v221 offset:3072
	s_cmp_eq_u32 s10, 12
	v_lshl_add_u64 v[168:169], v[110:111], 0, s[34:35]
	s_cselect_b64 vcc, -1, 0
	v_cndmask_b32_e32 v215, v169, v105, vcc
	v_cndmask_b32_e32 v214, v168, v104, vcc
	v_cndmask_b32_e32 v243, v109, v107, vcc
	v_cndmask_b32_e32 v242, v108, v106, vcc
	s_mov_b32 m0, s74
	v_lshl_add_u64 v[244:245], v[110:111], 0, v[192:193]
	ds_read_b128 v[168:171], v222
	ds_read_b128 v[172:175], v222 offset:1024
	ds_read_b128 v[202:205], v222 offset:2048
	ds_read_b128 v[206:209], v222 offset:3072
	ds_read_b128 v[210:213], v222 offset:4096
	ds_read_b128 v[230:233], v222 offset:5120
	ds_read_b128 v[234:237], v222 offset:6144
	ds_read_b128 v[238:241], v222 offset:7168
	global_load_lds_dwordx4 v[244:245], off
	v_lshl_add_u64 v[244:245], v[110:111], 0, v[190:191]
	s_mov_b32 m0, s75
	s_nop 0
	global_load_lds_dwordx4 v[244:245], off
	s_waitcnt vmcnt(8)
	s_waitcnt lgkmcnt(0)
	s_barrier
	s_setprio 1
	v_mfma_f32_16x16x32_bf16 v[140:143], v[120:123], v[168:171], v[140:143]
	v_mfma_f32_16x16x32_bf16 v[136:139], v[144:147], v[168:171], v[136:139]
	v_mfma_f32_16x16x32_bf16 v[116:119], v[120:123], v[202:205], v[116:119]
	v_mfma_f32_16x16x32_bf16 v[112:115], v[144:147], v[202:205], v[112:115]
	v_mfma_f32_16x16x32_bf16 v[92:95], v[120:123], v[210:213], v[92:95]
	v_mfma_f32_16x16x32_bf16 v[88:91], v[144:147], v[210:213], v[88:91]
	v_mfma_f32_16x16x32_bf16 v[76:79], v[120:123], v[234:237], v[76:79]
	v_mfma_f32_16x16x32_bf16 v[72:75], v[144:147], v[234:237], v[72:75]
	v_mfma_f32_16x16x32_bf16 v[140:143], v[124:127], v[172:175], v[140:143]
	v_mfma_f32_16x16x32_bf16 v[136:139], v[148:151], v[172:175], v[136:139]
	v_mfma_f32_16x16x32_bf16 v[116:119], v[124:127], v[206:209], v[116:119]
	v_mfma_f32_16x16x32_bf16 v[112:115], v[148:151], v[206:209], v[112:115]
	v_mfma_f32_16x16x32_bf16 v[92:95], v[124:127], v[230:233], v[92:95]
	v_mfma_f32_16x16x32_bf16 v[88:91], v[148:151], v[230:233], v[88:91]
	v_mfma_f32_16x16x32_bf16 v[76:79], v[124:127], v[238:241], v[76:79]
	v_mfma_f32_16x16x32_bf16 v[72:75], v[148:151], v[238:241], v[72:75]
	v_mfma_f32_16x16x32_bf16 v[132:135], v[152:155], v[168:171], v[132:135]
	v_mfma_f32_16x16x32_bf16 v[128:131], v[160:163], v[168:171], v[128:131]
	v_mfma_f32_16x16x32_bf16 v[100:103], v[152:155], v[202:205], v[100:103]
	v_mfma_f32_16x16x32_bf16 v[96:99], v[160:163], v[202:205], v[96:99]
	v_mfma_f32_16x16x32_bf16 v[84:87], v[152:155], v[210:213], v[84:87]
	v_mfma_f32_16x16x32_bf16 v[80:83], v[160:163], v[210:213], v[80:83]
	v_mfma_f32_16x16x32_bf16 v[68:71], v[152:155], v[234:237], v[68:71]
	v_mfma_f32_16x16x32_bf16 v[64:67], v[160:163], v[234:237], v[64:67]
	v_mfma_f32_16x16x32_bf16 v[132:135], v[156:159], v[172:175], v[132:135]
	v_mfma_f32_16x16x32_bf16 v[128:131], v[164:167], v[172:175], v[128:131]
	v_mfma_f32_16x16x32_bf16 v[100:103], v[156:159], v[206:209], v[100:103]
	v_mfma_f32_16x16x32_bf16 v[96:99], v[164:167], v[206:209], v[96:99]
	v_mfma_f32_16x16x32_bf16 v[84:87], v[156:159], v[230:233], v[84:87]
	v_mfma_f32_16x16x32_bf16 v[80:83], v[164:167], v[230:233], v[80:83]
	v_mfma_f32_16x16x32_bf16 v[68:71], v[156:159], v[238:241], v[68:71]
	v_mfma_f32_16x16x32_bf16 v[64:67], v[164:167], v[238:241], v[64:67]
	s_setprio 0
	s_barrier
	s_mov_b32 m0, s76
	v_lshl_add_u64 v[244:245], v[242:243], 0, v[184:185]
	ds_read_b128 v[168:171], v222 offset:16384
	ds_read_b128 v[172:175], v222 offset:17408
	ds_read_b128 v[202:205], v222 offset:18432
	ds_read_b128 v[206:209], v222 offset:19456
	ds_read_b128 v[210:213], v222 offset:20480
	ds_read_b128 v[230:233], v222 offset:21504
	ds_read_b128 v[234:237], v222 offset:22528
	ds_read_b128 v[238:241], v222 offset:23552
	global_load_lds_dwordx4 v[244:245], off
	v_lshl_add_u64 v[246:247], v[242:243], 0, v[188:189]
	s_mov_b32 m0, s77
	v_lshl_add_u64 v[248:249], v[242:243], 0, s[16:17]
	global_load_lds_dwordx4 v[246:247], off
	v_lshl_add_u64 v[250:251], v[248:249], 0, v[184:185]
	s_mov_b32 m0, s78
	v_lshl_add_u64 v[248:249], v[248:249], 0, v[188:189]
	global_load_lds_dwordx4 v[250:251], off
	s_mov_b32 m0, s79
	v_lshl_add_u64 v[250:251], v[214:215], 0, v[186:187]
	global_load_lds_dwordx4 v[248:249], off
	v_lshl_add_u64 v[248:249], v[214:215], 0, v[182:183]
	s_mov_b32 m0, s42
	s_nop 0
	global_load_lds_dwordx4 v[248:249], off
	s_mov_b32 m0, s43
	s_nop 0
	global_load_lds_dwordx4 v[250:251], off
	s_waitcnt vmcnt(8)
	s_waitcnt lgkmcnt(0)
	s_barrier
	s_setprio 1
	v_mfma_f32_16x16x32_bf16 v[60:63], v[120:123], v[168:171], v[60:63]
	v_mfma_f32_16x16x32_bf16 v[56:59], v[144:147], v[168:171], v[56:59]
	v_mfma_f32_16x16x32_bf16 v[44:47], v[120:123], v[202:205], v[44:47]
	v_mfma_f32_16x16x32_bf16 v[40:43], v[144:147], v[202:205], v[40:43]
	v_mfma_f32_16x16x32_bf16 v[28:31], v[120:123], v[210:213], v[28:31]
	v_mfma_f32_16x16x32_bf16 v[24:27], v[144:147], v[210:213], v[24:27]
	v_mfma_f32_16x16x32_bf16 v[12:15], v[120:123], v[234:237], v[12:15]
	v_mfma_f32_16x16x32_bf16 v[8:11], v[144:147], v[234:237], v[8:11]
	v_mfma_f32_16x16x32_bf16 v[60:63], v[124:127], v[172:175], v[60:63]
	v_mfma_f32_16x16x32_bf16 v[56:59], v[148:151], v[172:175], v[56:59]
	v_mfma_f32_16x16x32_bf16 v[44:47], v[124:127], v[206:209], v[44:47]
	v_mfma_f32_16x16x32_bf16 v[40:43], v[148:151], v[206:209], v[40:43]
	v_mfma_f32_16x16x32_bf16 v[28:31], v[124:127], v[230:233], v[28:31]
	v_mfma_f32_16x16x32_bf16 v[24:27], v[148:151], v[230:233], v[24:27]
	v_mfma_f32_16x16x32_bf16 v[12:15], v[124:127], v[238:241], v[12:15]
	v_mfma_f32_16x16x32_bf16 v[8:11], v[148:151], v[238:241], v[8:11]
	v_mfma_f32_16x16x32_bf16 v[52:55], v[152:155], v[168:171], v[52:55]
	v_mfma_f32_16x16x32_bf16 v[48:51], v[160:163], v[168:171], v[48:51]
	v_mfma_f32_16x16x32_bf16 v[36:39], v[152:155], v[202:205], v[36:39]
	v_mfma_f32_16x16x32_bf16 v[32:35], v[160:163], v[202:205], v[32:35]
	v_mfma_f32_16x16x32_bf16 v[20:23], v[152:155], v[210:213], v[20:23]
	v_mfma_f32_16x16x32_bf16 v[16:19], v[160:163], v[210:213], v[16:19]
	v_mfma_f32_16x16x32_bf16 v[4:7], v[152:155], v[234:237], v[4:7]
	v_mfma_f32_16x16x32_bf16 v[0:3], v[160:163], v[234:237], v[0:3]
	v_mfma_f32_16x16x32_bf16 v[52:55], v[156:159], v[172:175], v[52:55]
	v_mfma_f32_16x16x32_bf16 v[48:51], v[164:167], v[172:175], v[48:51]
	v_mfma_f32_16x16x32_bf16 v[36:39], v[156:159], v[206:209], v[36:39]
	v_mfma_f32_16x16x32_bf16 v[32:35], v[164:167], v[206:209], v[32:35]
	v_mfma_f32_16x16x32_bf16 v[20:23], v[156:159], v[230:233], v[20:23]
	v_mfma_f32_16x16x32_bf16 v[16:19], v[164:167], v[230:233], v[16:19]
	v_mfma_f32_16x16x32_bf16 v[4:7], v[156:159], v[238:241], v[4:7]
	v_mfma_f32_16x16x32_bf16 v[0:3], v[164:167], v[238:241], v[0:3]
	s_setprio 0
	s_barrier
	ds_read_b128 v[120:123], v223
	ds_read_b128 v[124:127], v223 offset:1024
	ds_read_b128 v[144:147], v223 offset:2048
	ds_read_b128 v[148:151], v223 offset:3072
	ds_read_b128 v[152:155], v224
	ds_read_b128 v[156:159], v224 offset:1024
	ds_read_b128 v[160:163], v224 offset:2048
	ds_read_b128 v[164:167], v224 offset:3072
	v_lshl_add_u64 v[214:215], v[214:215], 0, s[16:17]
	s_mov_b32 m0, s44
	v_lshl_add_u64 v[252:253], v[214:215], 0, v[182:183]
	ds_read_b128 v[168:171], v222 offset:32768
	ds_read_b128 v[172:175], v222 offset:33792
	ds_read_b128 v[202:205], v222 offset:34816
	ds_read_b128 v[206:209], v222 offset:35840
	ds_read_b128 v[210:213], v222 offset:36864
	ds_read_b128 v[230:233], v222 offset:37888
	ds_read_b128 v[234:237], v222 offset:38912
	ds_read_b128 v[238:241], v222 offset:39936
	global_load_lds_dwordx4 v[252:253], off
	v_lshl_add_u64 v[214:215], v[214:215], 0, v[186:187]
	s_mov_b32 m0, s45
	s_nop 0
	global_load_lds_dwordx4 v[214:215], off
	s_waitcnt vmcnt(8)
	s_waitcnt lgkmcnt(0)
	s_barrier
	s_setprio 1
	v_mfma_f32_16x16x32_bf16 v[140:143], v[120:123], v[168:171], v[140:143]
	v_mfma_f32_16x16x32_bf16 v[136:139], v[144:147], v[168:171], v[136:139]
	v_mfma_f32_16x16x32_bf16 v[116:119], v[120:123], v[202:205], v[116:119]
	v_mfma_f32_16x16x32_bf16 v[112:115], v[144:147], v[202:205], v[112:115]
	v_mfma_f32_16x16x32_bf16 v[92:95], v[120:123], v[210:213], v[92:95]
	v_mfma_f32_16x16x32_bf16 v[88:91], v[144:147], v[210:213], v[88:91]
	v_mfma_f32_16x16x32_bf16 v[76:79], v[120:123], v[234:237], v[76:79]
	v_mfma_f32_16x16x32_bf16 v[72:75], v[144:147], v[234:237], v[72:75]
	v_mfma_f32_16x16x32_bf16 v[140:143], v[124:127], v[172:175], v[140:143]
	v_mfma_f32_16x16x32_bf16 v[136:139], v[148:151], v[172:175], v[136:139]
	v_mfma_f32_16x16x32_bf16 v[116:119], v[124:127], v[206:209], v[116:119]
	v_mfma_f32_16x16x32_bf16 v[112:115], v[148:151], v[206:209], v[112:115]
	v_mfma_f32_16x16x32_bf16 v[92:95], v[124:127], v[230:233], v[92:95]
	v_mfma_f32_16x16x32_bf16 v[88:91], v[148:151], v[230:233], v[88:91]
	v_mfma_f32_16x16x32_bf16 v[76:79], v[124:127], v[238:241], v[76:79]
	v_mfma_f32_16x16x32_bf16 v[72:75], v[148:151], v[238:241], v[72:75]
	v_mfma_f32_16x16x32_bf16 v[132:135], v[152:155], v[168:171], v[132:135]
	v_mfma_f32_16x16x32_bf16 v[128:131], v[160:163], v[168:171], v[128:131]
	v_mfma_f32_16x16x32_bf16 v[100:103], v[152:155], v[202:205], v[100:103]
	v_mfma_f32_16x16x32_bf16 v[96:99], v[160:163], v[202:205], v[96:99]
	v_mfma_f32_16x16x32_bf16 v[84:87], v[152:155], v[210:213], v[84:87]
	v_mfma_f32_16x16x32_bf16 v[80:83], v[160:163], v[210:213], v[80:83]
	v_mfma_f32_16x16x32_bf16 v[68:71], v[152:155], v[234:237], v[68:71]
	v_mfma_f32_16x16x32_bf16 v[64:67], v[160:163], v[234:237], v[64:67]
	v_mfma_f32_16x16x32_bf16 v[132:135], v[156:159], v[172:175], v[132:135]
	v_mfma_f32_16x16x32_bf16 v[128:131], v[164:167], v[172:175], v[128:131]
	v_mfma_f32_16x16x32_bf16 v[100:103], v[156:159], v[206:209], v[100:103]
	v_mfma_f32_16x16x32_bf16 v[96:99], v[164:167], v[206:209], v[96:99]
	v_mfma_f32_16x16x32_bf16 v[84:87], v[156:159], v[230:233], v[84:87]
	v_mfma_f32_16x16x32_bf16 v[80:83], v[164:167], v[230:233], v[80:83]
	v_mfma_f32_16x16x32_bf16 v[68:71], v[156:159], v[238:241], v[68:71]
	v_mfma_f32_16x16x32_bf16 v[64:67], v[164:167], v[238:241], v[64:67]
	s_setprio 0
	s_barrier
	s_mov_b32 m0, s81
	v_lshl_add_u64 v[214:215], v[244:245], 0, s[22:23]
	ds_read_b128 v[168:171], v222 offset:49152
	ds_read_b128 v[172:175], v222 offset:50176
	ds_read_b128 v[202:205], v222 offset:51200
	ds_read_b128 v[206:209], v222 offset:52224
	ds_read_b128 v[210:213], v222 offset:53248
	ds_read_b128 v[230:233], v222 offset:54272
	ds_read_b128 v[234:237], v222 offset:55296
	ds_read_b128 v[238:241], v222 offset:56320
	global_load_lds_dwordx4 v[214:215], off
	v_lshl_add_u64 v[214:215], v[246:247], 0, s[22:23]
	s_mov_b32 m0, s82
	s_add_i32 s11, s80, s3
	global_load_lds_dwordx4 v[214:215], off
	v_lshl_add_u64 v[214:215], v[242:243], 0, s[26:27]
	v_lshl_add_u64 v[242:243], v[214:215], 0, v[184:185]
	s_mov_b32 m0, s11
	v_lshl_add_u64 v[214:215], v[214:215], 0, v[188:189]
	global_load_lds_dwordx4 v[242:243], off
	s_add_i32 m0, s11, 0x2000
	s_nop 0
	global_load_lds_dwordx4 v[214:215], off
	v_lshl_add_u64 v[214:215], v[248:249], 0, s[22:23]
	s_mov_b32 m0, s71
	s_nop 0
	global_load_lds_dwordx4 v[214:215], off
	v_lshl_add_u64 v[214:215], v[250:251], 0, s[22:23]
	s_mov_b32 m0, s72
	s_nop 0
	global_load_lds_dwordx4 v[214:215], off
	s_waitcnt vmcnt(8)
	s_waitcnt lgkmcnt(0)
	s_barrier
	s_setprio 1
	v_mfma_f32_16x16x32_bf16 v[60:63], v[120:123], v[168:171], v[60:63]
	v_mfma_f32_16x16x32_bf16 v[56:59], v[144:147], v[168:171], v[56:59]
	v_mfma_f32_16x16x32_bf16 v[44:47], v[120:123], v[202:205], v[44:47]
	v_mfma_f32_16x16x32_bf16 v[40:43], v[144:147], v[202:205], v[40:43]
	v_mfma_f32_16x16x32_bf16 v[28:31], v[120:123], v[210:213], v[28:31]
	v_mfma_f32_16x16x32_bf16 v[24:27], v[144:147], v[210:213], v[24:27]
	v_mfma_f32_16x16x32_bf16 v[12:15], v[120:123], v[234:237], v[12:15]
	v_mfma_f32_16x16x32_bf16 v[8:11], v[144:147], v[234:237], v[8:11]
	v_mfma_f32_16x16x32_bf16 v[60:63], v[124:127], v[172:175], v[60:63]
	v_mfma_f32_16x16x32_bf16 v[56:59], v[148:151], v[172:175], v[56:59]
	v_mfma_f32_16x16x32_bf16 v[44:47], v[124:127], v[206:209], v[44:47]
	v_mfma_f32_16x16x32_bf16 v[40:43], v[148:151], v[206:209], v[40:43]
	v_mfma_f32_16x16x32_bf16 v[28:31], v[124:127], v[230:233], v[28:31]
	v_mfma_f32_16x16x32_bf16 v[24:27], v[148:151], v[230:233], v[24:27]
	v_mfma_f32_16x16x32_bf16 v[12:15], v[124:127], v[238:241], v[12:15]
	v_mfma_f32_16x16x32_bf16 v[8:11], v[148:151], v[238:241], v[8:11]
	v_mfma_f32_16x16x32_bf16 v[52:55], v[152:155], v[168:171], v[52:55]
	v_mfma_f32_16x16x32_bf16 v[48:51], v[160:163], v[168:171], v[48:51]
	v_mfma_f32_16x16x32_bf16 v[36:39], v[152:155], v[202:205], v[36:39]
	v_mfma_f32_16x16x32_bf16 v[32:35], v[160:163], v[202:205], v[32:35]
	v_mfma_f32_16x16x32_bf16 v[20:23], v[152:155], v[210:213], v[20:23]
	v_mfma_f32_16x16x32_bf16 v[16:19], v[160:163], v[210:213], v[16:19]
	v_mfma_f32_16x16x32_bf16 v[4:7], v[152:155], v[234:237], v[4:7]
	v_mfma_f32_16x16x32_bf16 v[0:3], v[160:163], v[234:237], v[0:3]
	v_mfma_f32_16x16x32_bf16 v[52:55], v[156:159], v[172:175], v[52:55]
	v_mfma_f32_16x16x32_bf16 v[48:51], v[164:167], v[172:175], v[48:51]
	v_mfma_f32_16x16x32_bf16 v[36:39], v[156:159], v[206:209], v[36:39]
	v_mfma_f32_16x16x32_bf16 v[32:35], v[164:167], v[206:209], v[32:35]
	v_mfma_f32_16x16x32_bf16 v[20:23], v[156:159], v[230:233], v[20:23]
	v_mfma_f32_16x16x32_bf16 v[16:19], v[164:167], v[230:233], v[16:19]
	v_mfma_f32_16x16x32_bf16 v[4:7], v[156:159], v[238:241], v[4:7]
	v_mfma_f32_16x16x32_bf16 v[0:3], v[164:167], v[238:241], v[0:3]
	s_setprio 0
	s_barrier
	s_add_i32 s10, s10, 2
	v_lshl_add_u64 v[108:109], v[108:109], 0, s[30:31]
	s_cmp_gt_u32 s10, 13
	v_lshl_add_u64 v[110:111], v[110:111], 0, s[30:31]
	s_cbranch_scc0 .LBB0_1245
	s_and_b64 vcc, exec, s[28:29]
	s_cbranch_vccz .LBB0_1248
	s_barrier

.LBB0_1356:
	v_add_u32_e32 v186, s41, v167
	v_add_u32_e32 v202, s42, v167
	ds_read_b128 v[172:175], v186
	ds_read_b128 v[178:181], v186 offset:1024
	ds_read_b128 v[182:185], v186 offset:2048
	ds_read_b128 v[186:189], v186 offset:3072
	ds_read_b128 v[190:193], v202
	ds_read_b128 v[194:197], v202 offset:1024
	ds_read_b128 v[198:201], v202 offset:2048
	ds_read_b128 v[202:205], v202 offset:3072
	v_lshl_add_u64 v[206:207], v[164:165], 0, s[22:23]
	v_cndmask_b32_e64 v215, v207, v157, s[8:9]
	v_cndmask_b32_e64 v214, v206, v156, s[8:9]
	v_cndmask_b32_e64 v243, v163, v159, s[8:9]
	v_cndmask_b32_e64 v242, v162, v158, s[8:9]
	s_mov_b32 m0, s43
	v_lshl_add_u64 v[244:245], v[164:165], 0, v[146:147]
	ds_read_b128 v[206:209], v170
	ds_read_b128 v[210:213], v170 offset:1024
	ds_read_b128 v[218:221], v170 offset:2048
	ds_read_b128 v[222:225], v170 offset:3072
	ds_read_b128 v[226:229], v170 offset:4096
	ds_read_b128 v[230:233], v170 offset:5120
	ds_read_b128 v[234:237], v170 offset:6144
	ds_read_b128 v[238:241], v170 offset:7168
	global_load_lds_dwordx4 v[244:245], off
	v_lshl_add_u64 v[244:245], v[164:165], 0, v[144:145]
	s_mov_b32 m0, s44
	s_nop 0
	global_load_lds_dwordx4 v[244:245], off
	s_waitcnt vmcnt(8)
	s_waitcnt lgkmcnt(0)
	s_barrier
	s_setprio 1
	v_mfma_f32_16x16x32_bf16 v[124:127], v[172:175], v[206:209], v[124:127]
	v_mfma_f32_16x16x32_bf16 v[116:119], v[182:185], v[206:209], v[116:119]
	v_mfma_f32_16x16x32_bf16 v[108:111], v[172:175], v[218:221], v[108:111]
	v_mfma_f32_16x16x32_bf16 v[100:103], v[182:185], v[218:221], v[100:103]
	v_mfma_f32_16x16x32_bf16 v[92:95], v[172:175], v[226:229], v[92:95]
	v_mfma_f32_16x16x32_bf16 v[84:87], v[182:185], v[226:229], v[84:87]
	v_mfma_f32_16x16x32_bf16 v[76:79], v[172:175], v[234:237], v[76:79]
	v_mfma_f32_16x16x32_bf16 v[68:71], v[182:185], v[234:237], v[68:71]
	v_mfma_f32_16x16x32_bf16 v[124:127], v[178:181], v[210:213], v[124:127]
	v_mfma_f32_16x16x32_bf16 v[116:119], v[186:189], v[210:213], v[116:119]
	v_mfma_f32_16x16x32_bf16 v[108:111], v[178:181], v[222:225], v[108:111]
	v_mfma_f32_16x16x32_bf16 v[100:103], v[186:189], v[222:225], v[100:103]
	v_mfma_f32_16x16x32_bf16 v[92:95], v[178:181], v[230:233], v[92:95]
	v_mfma_f32_16x16x32_bf16 v[84:87], v[186:189], v[230:233], v[84:87]
	v_mfma_f32_16x16x32_bf16 v[76:79], v[178:181], v[238:241], v[76:79]
	v_mfma_f32_16x16x32_bf16 v[68:71], v[186:189], v[238:241], v[68:71]
	v_mfma_f32_16x16x32_bf16 v[120:123], v[190:193], v[206:209], v[120:123]
	v_mfma_f32_16x16x32_bf16 v[112:115], v[198:201], v[206:209], v[112:115]
	v_mfma_f32_16x16x32_bf16 v[104:107], v[190:193], v[218:221], v[104:107]
	v_mfma_f32_16x16x32_bf16 v[96:99], v[198:201], v[218:221], v[96:99]
	v_mfma_f32_16x16x32_bf16 v[88:91], v[190:193], v[226:229], v[88:91]
	v_mfma_f32_16x16x32_bf16 v[80:83], v[198:201], v[226:229], v[80:83]
	v_mfma_f32_16x16x32_bf16 v[72:75], v[190:193], v[234:237], v[72:75]
	v_mfma_f32_16x16x32_bf16 v[64:67], v[198:201], v[234:237], v[64:67]
	v_mfma_f32_16x16x32_bf16 v[120:123], v[194:197], v[210:213], v[120:123]
	v_mfma_f32_16x16x32_bf16 v[112:115], v[202:205], v[210:213], v[112:115]
	v_mfma_f32_16x16x32_bf16 v[104:107], v[194:197], v[222:225], v[104:107]
	v_mfma_f32_16x16x32_bf16 v[96:99], v[202:205], v[222:225], v[96:99]
	v_mfma_f32_16x16x32_bf16 v[88:91], v[194:197], v[230:233], v[88:91]
	v_mfma_f32_16x16x32_bf16 v[80:83], v[202:205], v[230:233], v[80:83]
	v_mfma_f32_16x16x32_bf16 v[72:75], v[194:197], v[238:241], v[72:75]
	v_mfma_f32_16x16x32_bf16 v[64:67], v[202:205], v[238:241], v[64:67]
	s_setprio 0
	s_barrier
	s_add_i32 s8, s41, s3
	v_lshl_add_u64 v[244:245], v[242:243], 0, v[136:137]
	s_mov_b32 m0, s8
	ds_read_b128 v[206:209], v170 offset:16384
	ds_read_b128 v[210:213], v170 offset:17408
	ds_read_b128 v[218:221], v170 offset:18432
	ds_read_b128 v[222:225], v170 offset:19456
	ds_read_b128 v[226:229], v170 offset:20480
	ds_read_b128 v[230:233], v170 offset:21504
	ds_read_b128 v[234:237], v170 offset:22528
	ds_read_b128 v[238:241], v170 offset:23552
	global_load_lds_dwordx4 v[244:245], off
	v_lshl_add_u64 v[246:247], v[242:243], 0, v[140:141]
	s_add_i32 m0, s8, 0x2000
	v_lshl_add_u64 v[248:249], v[242:243], 0, s[10:11]
	s_add_i32 s8, s42, s3
	global_load_lds_dwordx4 v[246:247], off
	v_lshl_add_u64 v[250:251], v[248:249], 0, v[136:137]
	s_mov_b32 m0, s8
	v_lshl_add_u64 v[248:249], v[248:249], 0, v[140:141]
	global_load_lds_dwordx4 v[250:251], off
	s_add_i32 m0, s8, 0x2000
	v_lshl_add_u64 v[250:251], v[214:215], 0, v[138:139]
	global_load_lds_dwordx4 v[248:249], off
	v_lshl_add_u64 v[248:249], v[214:215], 0, v[134:135]
	s_mov_b32 m0, s31
	s_nop 0
	global_load_lds_dwordx4 v[248:249], off
	s_mov_b32 m0, s35
	s_nop 0
	global_load_lds_dwordx4 v[250:251], off
	s_waitcnt vmcnt(8)
	s_waitcnt lgkmcnt(0)
	s_barrier
	s_setprio 1
	v_mfma_f32_16x16x32_bf16 v[60:63], v[172:175], v[206:209], v[60:63]
	v_mfma_f32_16x16x32_bf16 v[52:55], v[182:185], v[206:209], v[52:55]
	v_mfma_f32_16x16x32_bf16 v[44:47], v[172:175], v[218:221], v[44:47]
	v_mfma_f32_16x16x32_bf16 v[36:39], v[182:185], v[218:221], v[36:39]
	v_mfma_f32_16x16x32_bf16 v[28:31], v[172:175], v[226:229], v[28:31]
	v_mfma_f32_16x16x32_bf16 v[20:23], v[182:185], v[226:229], v[20:23]
	v_mfma_f32_16x16x32_bf16 v[12:15], v[172:175], v[234:237], v[12:15]
	v_mfma_f32_16x16x32_bf16 v[4:7], v[182:185], v[234:237], v[4:7]
	v_mfma_f32_16x16x32_bf16 v[60:63], v[178:181], v[210:213], v[60:63]
	v_mfma_f32_16x16x32_bf16 v[52:55], v[186:189], v[210:213], v[52:55]
	v_mfma_f32_16x16x32_bf16 v[44:47], v[178:181], v[222:225], v[44:47]
	v_mfma_f32_16x16x32_bf16 v[36:39], v[186:189], v[222:225], v[36:39]
	v_mfma_f32_16x16x32_bf16 v[28:31], v[178:181], v[230:233], v[28:31]
	v_mfma_f32_16x16x32_bf16 v[20:23], v[186:189], v[230:233], v[20:23]
	v_mfma_f32_16x16x32_bf16 v[12:15], v[178:181], v[238:241], v[12:15]
	v_mfma_f32_16x16x32_bf16 v[4:7], v[186:189], v[238:241], v[4:7]
	v_mfma_f32_16x16x32_bf16 v[56:59], v[190:193], v[206:209], v[56:59]
	v_mfma_f32_16x16x32_bf16 v[48:51], v[198:201], v[206:209], v[48:51]
	v_mfma_f32_16x16x32_bf16 v[40:43], v[190:193], v[218:221], v[40:43]
	v_mfma_f32_16x16x32_bf16 v[32:35], v[198:201], v[218:221], v[32:35]
	v_mfma_f32_16x16x32_bf16 v[24:27], v[190:193], v[226:229], v[24:27]
	v_mfma_f32_16x16x32_bf16 v[16:19], v[198:201], v[226:229], v[16:19]
	v_mfma_f32_16x16x32_bf16 v[8:11], v[190:193], v[234:237], v[8:11]
	v_mfma_f32_16x16x32_bf16 v[0:3], v[198:201], v[234:237], v[0:3]
	v_mfma_f32_16x16x32_bf16 v[56:59], v[194:197], v[210:213], v[56:59]
	v_mfma_f32_16x16x32_bf16 v[48:51], v[202:205], v[210:213], v[48:51]
	v_mfma_f32_16x16x32_bf16 v[40:43], v[194:197], v[222:225], v[40:43]
	v_mfma_f32_16x16x32_bf16 v[32:35], v[202:205], v[222:225], v[32:35]
	v_mfma_f32_16x16x32_bf16 v[24:27], v[194:197], v[230:233], v[24:27]
	v_mfma_f32_16x16x32_bf16 v[16:19], v[202:205], v[230:233], v[16:19]
	v_mfma_f32_16x16x32_bf16 v[8:11], v[194:197], v[238:241], v[8:11]
	v_mfma_f32_16x16x32_bf16 v[0:3], v[202:205], v[238:241], v[0:3]
	s_setprio 0
	s_barrier
	s_add_i32 s8, 0, 0x18000
	s_add_i32 s9, 0, 0x1c000
	v_add_u32_e32 v186, s8, v167
	v_add_u32_e32 v202, s9, v167
	ds_read_b128 v[172:175], v186
	ds_read_b128 v[178:181], v186 offset:1024
	ds_read_b128 v[182:185], v186 offset:2048
	ds_read_b128 v[186:189], v186 offset:3072
	ds_read_b128 v[190:193], v202
	ds_read_b128 v[194:197], v202 offset:1024
	ds_read_b128 v[198:201], v202 offset:2048
	ds_read_b128 v[202:205], v202 offset:3072
	v_lshl_add_u64 v[214:215], v[214:215], 0, s[10:11]
	s_mov_b32 m0, s36
	v_lshl_add_u64 v[252:253], v[214:215], 0, v[134:135]
	ds_read_b128 v[206:209], v170 offset:32768
	ds_read_b128 v[210:213], v170 offset:33792
	ds_read_b128 v[218:221], v170 offset:34816
	ds_read_b128 v[222:225], v170 offset:35840
	ds_read_b128 v[226:229], v170 offset:36864
	ds_read_b128 v[230:233], v170 offset:37888
	ds_read_b128 v[234:237], v170 offset:38912
	ds_read_b128 v[238:241], v170 offset:39936
	global_load_lds_dwordx4 v[252:253], off
	v_lshl_add_u64 v[214:215], v[214:215], 0, v[138:139]
	s_mov_b32 m0, s37
	s_nop 0
	global_load_lds_dwordx4 v[214:215], off
	s_waitcnt vmcnt(8)
	s_waitcnt lgkmcnt(0)
	s_barrier
	s_setprio 1
	v_mfma_f32_16x16x32_bf16 v[124:127], v[172:175], v[206:209], v[124:127]
	v_mfma_f32_16x16x32_bf16 v[116:119], v[182:185], v[206:209], v[116:119]
	v_mfma_f32_16x16x32_bf16 v[108:111], v[172:175], v[218:221], v[108:111]
	v_mfma_f32_16x16x32_bf16 v[100:103], v[182:185], v[218:221], v[100:103]
	v_mfma_f32_16x16x32_bf16 v[92:95], v[172:175], v[226:229], v[92:95]
	v_mfma_f32_16x16x32_bf16 v[84:87], v[182:185], v[226:229], v[84:87]
	v_mfma_f32_16x16x32_bf16 v[76:79], v[172:175], v[234:237], v[76:79]
	v_mfma_f32_16x16x32_bf16 v[68:71], v[182:185], v[234:237], v[68:71]
	v_mfma_f32_16x16x32_bf16 v[124:127], v[178:181], v[210:213], v[124:127]
	v_mfma_f32_16x16x32_bf16 v[116:119], v[186:189], v[210:213], v[116:119]
	v_mfma_f32_16x16x32_bf16 v[108:111], v[178:181], v[222:225], v[108:111]
	v_mfma_f32_16x16x32_bf16 v[100:103], v[186:189], v[222:225], v[100:103]
	v_mfma_f32_16x16x32_bf16 v[92:95], v[178:181], v[230:233], v[92:95]
	v_mfma_f32_16x16x32_bf16 v[84:87], v[186:189], v[230:233], v[84:87]
	v_mfma_f32_16x16x32_bf16 v[76:79], v[178:181], v[238:241], v[76:79]
	v_mfma_f32_16x16x32_bf16 v[68:71], v[186:189], v[238:241], v[68:71]
	v_mfma_f32_16x16x32_bf16 v[120:123], v[190:193], v[206:209], v[120:123]
	v_mfma_f32_16x16x32_bf16 v[112:115], v[198:201], v[206:209], v[112:115]
	v_mfma_f32_16x16x32_bf16 v[104:107], v[190:193], v[218:221], v[104:107]
	v_mfma_f32_16x16x32_bf16 v[96:99], v[198:201], v[218:221], v[96:99]
	v_mfma_f32_16x16x32_bf16 v[88:91], v[190:193], v[226:229], v[88:91]
	v_mfma_f32_16x16x32_bf16 v[80:83], v[198:201], v[226:229], v[80:83]
	v_mfma_f32_16x16x32_bf16 v[72:75], v[190:193], v[234:237], v[72:75]
	v_mfma_f32_16x16x32_bf16 v[64:67], v[198:201], v[234:237], v[64:67]
	v_mfma_f32_16x16x32_bf16 v[120:123], v[194:197], v[210:213], v[120:123]
	v_mfma_f32_16x16x32_bf16 v[112:115], v[202:205], v[210:213], v[112:115]
	v_mfma_f32_16x16x32_bf16 v[104:107], v[194:197], v[222:225], v[104:107]
	v_mfma_f32_16x16x32_bf16 v[96:99], v[202:205], v[222:225], v[96:99]
	v_mfma_f32_16x16x32_bf16 v[88:91], v[194:197], v[230:233], v[88:91]
	v_mfma_f32_16x16x32_bf16 v[80:83], v[202:205], v[230:233], v[80:83]
	v_mfma_f32_16x16x32_bf16 v[72:75], v[194:197], v[238:241], v[72:75]
	v_mfma_f32_16x16x32_bf16 v[64:67], v[202:205], v[238:241], v[64:67]
	s_setprio 0
	s_barrier
	s_add_i32 s8, s8, s3
	v_lshl_add_u64 v[214:215], v[244:245], 0, s[14:15]
	s_mov_b32 m0, s8
	ds_read_b128 v[206:209], v170 offset:49152
	ds_read_b128 v[210:213], v170 offset:50176
	ds_read_b128 v[218:221], v170 offset:51200
	ds_read_b128 v[222:225], v170 offset:52224
	ds_read_b128 v[226:229], v170 offset:53248
	ds_read_b128 v[230:233], v170 offset:54272
	ds_read_b128 v[234:237], v170 offset:55296
	ds_read_b128 v[238:241], v170 offset:56320
	global_load_lds_dwordx4 v[214:215], off
	v_lshl_add_u64 v[214:215], v[246:247], 0, s[14:15]
	s_add_i32 m0, s8, 0x2000
	s_add_i32 s8, s9, s3
	global_load_lds_dwordx4 v[214:215], off
	v_lshl_add_u64 v[214:215], v[242:243], 0, s[16:17]
	v_lshl_add_u64 v[242:243], v[214:215], 0, v[136:137]
	s_mov_b32 m0, s8
	v_lshl_add_u64 v[214:215], v[214:215], 0, v[140:141]
	global_load_lds_dwordx4 v[242:243], off
	s_add_i32 m0, s8, 0x2000
	s_nop 0
	global_load_lds_dwordx4 v[214:215], off
	v_lshl_add_u64 v[214:215], v[248:249], 0, s[14:15]
	s_mov_b32 m0, s38
	s_nop 0
	global_load_lds_dwordx4 v[214:215], off
	v_lshl_add_u64 v[214:215], v[250:251], 0, s[14:15]
	s_mov_b32 m0, s39
	s_nop 0
	global_load_lds_dwordx4 v[214:215], off
	s_waitcnt vmcnt(8)
	s_waitcnt lgkmcnt(0)
	s_barrier
	s_setprio 1
	v_mfma_f32_16x16x32_bf16 v[60:63], v[172:175], v[206:209], v[60:63]
	v_mfma_f32_16x16x32_bf16 v[52:55], v[182:185], v[206:209], v[52:55]
	v_mfma_f32_16x16x32_bf16 v[44:47], v[172:175], v[218:221], v[44:47]
	v_mfma_f32_16x16x32_bf16 v[36:39], v[182:185], v[218:221], v[36:39]
	v_mfma_f32_16x16x32_bf16 v[28:31], v[172:175], v[226:229], v[28:31]
	v_mfma_f32_16x16x32_bf16 v[20:23], v[182:185], v[226:229], v[20:23]
	v_mfma_f32_16x16x32_bf16 v[12:15], v[172:175], v[234:237], v[12:15]
	v_mfma_f32_16x16x32_bf16 v[4:7], v[182:185], v[234:237], v[4:7]
	v_mfma_f32_16x16x32_bf16 v[60:63], v[178:181], v[210:213], v[60:63]
	v_mfma_f32_16x16x32_bf16 v[52:55], v[186:189], v[210:213], v[52:55]
	v_mfma_f32_16x16x32_bf16 v[44:47], v[178:181], v[222:225], v[44:47]
	v_mfma_f32_16x16x32_bf16 v[36:39], v[186:189], v[222:225], v[36:39]
	v_mfma_f32_16x16x32_bf16 v[28:31], v[178:181], v[230:233], v[28:31]
	v_mfma_f32_16x16x32_bf16 v[20:23], v[186:189], v[230:233], v[20:23]
	v_mfma_f32_16x16x32_bf16 v[12:15], v[178:181], v[238:241], v[12:15]
	v_mfma_f32_16x16x32_bf16 v[4:7], v[186:189], v[238:241], v[4:7]
	v_mfma_f32_16x16x32_bf16 v[56:59], v[190:193], v[206:209], v[56:59]
	v_mfma_f32_16x16x32_bf16 v[48:51], v[198:201], v[206:209], v[48:51]
	v_mfma_f32_16x16x32_bf16 v[40:43], v[190:193], v[218:221], v[40:43]
	v_mfma_f32_16x16x32_bf16 v[32:35], v[198:201], v[218:221], v[32:35]
	v_mfma_f32_16x16x32_bf16 v[24:27], v[190:193], v[226:229], v[24:27]
	v_mfma_f32_16x16x32_bf16 v[16:19], v[198:201], v[226:229], v[16:19]
	v_mfma_f32_16x16x32_bf16 v[8:11], v[190:193], v[234:237], v[8:11]
	v_mfma_f32_16x16x32_bf16 v[0:3], v[198:201], v[234:237], v[0:3]
	v_mfma_f32_16x16x32_bf16 v[56:59], v[194:197], v[210:213], v[56:59]
	v_mfma_f32_16x16x32_bf16 v[48:51], v[202:205], v[210:213], v[48:51]
	v_mfma_f32_16x16x32_bf16 v[40:43], v[194:197], v[222:225], v[40:43]
	v_mfma_f32_16x16x32_bf16 v[32:35], v[202:205], v[222:225], v[32:35]
	v_mfma_f32_16x16x32_bf16 v[24:27], v[194:197], v[230:233], v[24:27]
	v_mfma_f32_16x16x32_bf16 v[16:19], v[202:205], v[230:233], v[16:19]
	v_mfma_f32_16x16x32_bf16 v[8:11], v[194:197], v[238:241], v[8:11]
	v_mfma_f32_16x16x32_bf16 v[0:3], v[202:205], v[238:241], v[0:3]
	s_setprio 0
	s_barrier
	s_add_i32 s29, s29, 2
	v_lshl_add_u64 v[162:163], v[162:163], 0, s[20:21]
	s_cmp_gt_u32 s29, 13
	v_lshl_add_u64 v[164:165], v[164:165], 0, s[20:21]
	s_cbranch_scc1 .LBB0_1360

.LBB0_1430:
	ds_read_b128 v[134:137], v225
	ds_read_b128 v[138:141], v225 offset:1024
	ds_read_b128 v[142:145], v225 offset:2048
	ds_read_b128 v[146:149], v225 offset:3072
	ds_read_b128 v[150:153], v226
	ds_read_b128 v[154:157], v226 offset:1024
	ds_read_b128 v[158:161], v226 offset:2048
	ds_read_b128 v[162:165], v226 offset:3072
	s_cmp_eq_u32 s4, 40
	v_lshl_add_u64 v[132:133], v[130:131], 0, s[20:21]
	s_cselect_b64 vcc, -1, 0
	v_cndmask_b32_e32 v219, v133, v199, vcc
	v_cndmask_b32_e32 v218, v132, v198, vcc
	v_cndmask_b32_e32 v239, v129, v201, vcc
	v_cndmask_b32_e32 v238, v128, v200, vcc
	s_mov_b32 m0, s52
	v_lshl_add_u64 v[240:241], v[130:131], 0, v[192:193]
	ds_read_b128 v[166:169], v227
	ds_read_b128 v[170:173], v227 offset:1024
	ds_read_b128 v[174:177], v227 offset:2048
	ds_read_b128 v[202:205], v227 offset:3072
	ds_read_b128 v[206:209], v227 offset:4096
	ds_read_b128 v[210:213], v227 offset:5120
	ds_read_b128 v[214:217], v227 offset:6144
	ds_read_b128 v[234:237], v227 offset:7168
	global_load_lds_dwordx4 v[240:241], off
	v_lshl_add_u64 v[130:131], v[130:131], 0, v[190:191]
	s_mov_b32 m0, s53
	s_nop 0
	global_load_lds_dwordx4 v[130:131], off
	s_waitcnt vmcnt(8)
	s_waitcnt lgkmcnt(0)
	s_barrier
	s_setprio 1
	v_mfma_f32_16x16x32_bf16 v[124:127], v[134:137], v[166:169], v[124:127]
	v_mfma_f32_16x16x32_bf16 v[120:123], v[142:145], v[166:169], v[120:123]
	v_mfma_f32_16x16x32_bf16 v[108:111], v[134:137], v[174:177], v[108:111]
	v_mfma_f32_16x16x32_bf16 v[104:107], v[142:145], v[174:177], v[104:107]
	v_mfma_f32_16x16x32_bf16 v[92:95], v[134:137], v[206:209], v[92:95]
	v_mfma_f32_16x16x32_bf16 v[88:91], v[142:145], v[206:209], v[88:91]
	v_mfma_f32_16x16x32_bf16 v[76:79], v[134:137], v[214:217], v[76:79]
	v_mfma_f32_16x16x32_bf16 v[72:75], v[142:145], v[214:217], v[72:75]
	v_mfma_f32_16x16x32_bf16 v[124:127], v[138:141], v[170:173], v[124:127]
	v_mfma_f32_16x16x32_bf16 v[120:123], v[146:149], v[170:173], v[120:123]
	v_mfma_f32_16x16x32_bf16 v[108:111], v[138:141], v[202:205], v[108:111]
	v_mfma_f32_16x16x32_bf16 v[104:107], v[146:149], v[202:205], v[104:107]
	v_mfma_f32_16x16x32_bf16 v[92:95], v[138:141], v[210:213], v[92:95]
	v_mfma_f32_16x16x32_bf16 v[88:91], v[146:149], v[210:213], v[88:91]
	v_mfma_f32_16x16x32_bf16 v[76:79], v[138:141], v[234:237], v[76:79]
	v_mfma_f32_16x16x32_bf16 v[72:75], v[146:149], v[234:237], v[72:75]
	v_mfma_f32_16x16x32_bf16 v[116:119], v[150:153], v[166:169], v[116:119]
	v_mfma_f32_16x16x32_bf16 v[112:115], v[158:161], v[166:169], v[112:115]
	v_mfma_f32_16x16x32_bf16 v[100:103], v[150:153], v[174:177], v[100:103]
	v_mfma_f32_16x16x32_bf16 v[96:99], v[158:161], v[174:177], v[96:99]
	v_mfma_f32_16x16x32_bf16 v[84:87], v[150:153], v[206:209], v[84:87]
	v_mfma_f32_16x16x32_bf16 v[80:83], v[158:161], v[206:209], v[80:83]
	v_mfma_f32_16x16x32_bf16 v[68:71], v[150:153], v[214:217], v[68:71]
	v_mfma_f32_16x16x32_bf16 v[64:67], v[158:161], v[214:217], v[64:67]
	v_mfma_f32_16x16x32_bf16 v[116:119], v[154:157], v[170:173], v[116:119]
	v_mfma_f32_16x16x32_bf16 v[112:115], v[162:165], v[170:173], v[112:115]
	v_mfma_f32_16x16x32_bf16 v[100:103], v[154:157], v[202:205], v[100:103]
	v_mfma_f32_16x16x32_bf16 v[96:99], v[162:165], v[202:205], v[96:99]
	v_mfma_f32_16x16x32_bf16 v[84:87], v[154:157], v[210:213], v[84:87]
	v_mfma_f32_16x16x32_bf16 v[80:83], v[162:165], v[210:213], v[80:83]
	v_mfma_f32_16x16x32_bf16 v[68:71], v[154:157], v[234:237], v[68:71]
	v_mfma_f32_16x16x32_bf16 v[64:67], v[162:165], v[234:237], v[64:67]
	s_setprio 0
	s_barrier
	s_mov_b32 m0, s54
	v_lshl_add_u64 v[130:131], v[238:239], 0, v[184:185]
	ds_read_b128 v[166:169], v227 offset:16384
	ds_read_b128 v[170:173], v227 offset:17408
	ds_read_b128 v[174:177], v227 offset:18432
	ds_read_b128 v[202:205], v227 offset:19456
	ds_read_b128 v[206:209], v227 offset:20480
	ds_read_b128 v[210:213], v227 offset:21504
	ds_read_b128 v[214:217], v227 offset:22528
	ds_read_b128 v[234:237], v227 offset:23552
	global_load_lds_dwordx4 v[130:131], off
	v_lshl_add_u64 v[240:241], v[238:239], 0, v[188:189]
	s_mov_b32 m0, s55
	v_lshl_add_u64 v[242:243], v[238:239], 0, s[8:9]
	global_load_lds_dwordx4 v[240:241], off
	v_lshl_add_u64 v[244:245], v[242:243], 0, v[184:185]
	s_mov_b32 m0, s56
	v_lshl_add_u64 v[242:243], v[242:243], 0, v[188:189]
	global_load_lds_dwordx4 v[244:245], off
	s_mov_b32 m0, s57
	v_lshl_add_u64 v[244:245], v[218:219], 0, v[186:187]
	global_load_lds_dwordx4 v[242:243], off
	v_lshl_add_u64 v[242:243], v[218:219], 0, v[182:183]
	s_mov_b32 m0, s44
	s_nop 0
	global_load_lds_dwordx4 v[242:243], off
	s_mov_b32 m0, s45
	s_nop 0
	global_load_lds_dwordx4 v[244:245], off
	s_waitcnt vmcnt(8)
	s_waitcnt lgkmcnt(0)
	s_barrier
	s_setprio 1
	v_mfma_f32_16x16x32_bf16 v[60:63], v[134:137], v[166:169], v[60:63]
	v_mfma_f32_16x16x32_bf16 v[56:59], v[142:145], v[166:169], v[56:59]
	v_mfma_f32_16x16x32_bf16 v[44:47], v[134:137], v[174:177], v[44:47]
	v_mfma_f32_16x16x32_bf16 v[40:43], v[142:145], v[174:177], v[40:43]
	v_mfma_f32_16x16x32_bf16 v[28:31], v[134:137], v[206:209], v[28:31]
	v_mfma_f32_16x16x32_bf16 v[24:27], v[142:145], v[206:209], v[24:27]
	v_mfma_f32_16x16x32_bf16 v[12:15], v[134:137], v[214:217], v[12:15]
	v_mfma_f32_16x16x32_bf16 v[8:11], v[142:145], v[214:217], v[8:11]
	v_mfma_f32_16x16x32_bf16 v[60:63], v[138:141], v[170:173], v[60:63]
	v_mfma_f32_16x16x32_bf16 v[56:59], v[146:149], v[170:173], v[56:59]
	v_mfma_f32_16x16x32_bf16 v[44:47], v[138:141], v[202:205], v[44:47]
	v_mfma_f32_16x16x32_bf16 v[40:43], v[146:149], v[202:205], v[40:43]
	v_mfma_f32_16x16x32_bf16 v[28:31], v[138:141], v[210:213], v[28:31]
	v_mfma_f32_16x16x32_bf16 v[24:27], v[146:149], v[210:213], v[24:27]
	v_mfma_f32_16x16x32_bf16 v[12:15], v[138:141], v[234:237], v[12:15]
	v_mfma_f32_16x16x32_bf16 v[8:11], v[146:149], v[234:237], v[8:11]
	v_mfma_f32_16x16x32_bf16 v[52:55], v[150:153], v[166:169], v[52:55]
	v_mfma_f32_16x16x32_bf16 v[48:51], v[158:161], v[166:169], v[48:51]
	v_mfma_f32_16x16x32_bf16 v[36:39], v[150:153], v[174:177], v[36:39]
	v_mfma_f32_16x16x32_bf16 v[32:35], v[158:161], v[174:177], v[32:35]
	v_mfma_f32_16x16x32_bf16 v[20:23], v[150:153], v[206:209], v[20:23]
	v_mfma_f32_16x16x32_bf16 v[16:19], v[158:161], v[206:209], v[16:19]
	v_mfma_f32_16x16x32_bf16 v[4:7], v[150:153], v[214:217], v[4:7]
	v_mfma_f32_16x16x32_bf16 v[0:3], v[158:161], v[214:217], v[0:3]
	v_mfma_f32_16x16x32_bf16 v[52:55], v[154:157], v[170:173], v[52:55]
	v_mfma_f32_16x16x32_bf16 v[48:51], v[162:165], v[170:173], v[48:51]
	v_mfma_f32_16x16x32_bf16 v[36:39], v[154:157], v[202:205], v[36:39]
	v_mfma_f32_16x16x32_bf16 v[32:35], v[162:165], v[202:205], v[32:35]
	v_mfma_f32_16x16x32_bf16 v[20:23], v[154:157], v[210:213], v[20:23]
	v_mfma_f32_16x16x32_bf16 v[16:19], v[162:165], v[210:213], v[16:19]
	v_mfma_f32_16x16x32_bf16 v[4:7], v[154:157], v[234:237], v[4:7]
	v_mfma_f32_16x16x32_bf16 v[0:3], v[162:165], v[234:237], v[0:3]
	s_setprio 0
	s_barrier
	s_add_i32 s5, 0, 0x1c000
	v_add_u32_e32 v162, s5, v224
	ds_read_b128 v[134:137], v228
	ds_read_b128 v[138:141], v228 offset:1024
	ds_read_b128 v[142:145], v228 offset:2048
	ds_read_b128 v[146:149], v228 offset:3072
	ds_read_b128 v[150:153], v162
	ds_read_b128 v[154:157], v162 offset:1024
	ds_read_b128 v[158:161], v162 offset:2048
	ds_read_b128 v[162:165], v162 offset:3072
	v_lshl_add_u64 v[218:219], v[218:219], 0, s[8:9]
	s_mov_b32 m0, s46
	v_lshl_add_u64 v[246:247], v[218:219], 0, v[182:183]
	ds_read_b128 v[166:169], v227 offset:32768
	ds_read_b128 v[170:173], v227 offset:33792
	ds_read_b128 v[174:177], v227 offset:34816
	ds_read_b128 v[202:205], v227 offset:35840
	ds_read_b128 v[206:209], v227 offset:36864
	ds_read_b128 v[210:213], v227 offset:37888
	ds_read_b128 v[214:217], v227 offset:38912
	ds_read_b128 v[234:237], v227 offset:39936
	global_load_lds_dwordx4 v[246:247], off
	v_lshl_add_u64 v[218:219], v[218:219], 0, v[186:187]
	s_mov_b32 m0, s47
	s_nop 0
	global_load_lds_dwordx4 v[218:219], off
	s_waitcnt vmcnt(8)
	s_waitcnt lgkmcnt(0)
	s_barrier
	s_setprio 1
	v_mfma_f32_16x16x32_bf16 v[124:127], v[134:137], v[166:169], v[124:127]
	v_mfma_f32_16x16x32_bf16 v[120:123], v[142:145], v[166:169], v[120:123]
	v_mfma_f32_16x16x32_bf16 v[108:111], v[134:137], v[174:177], v[108:111]
	v_mfma_f32_16x16x32_bf16 v[104:107], v[142:145], v[174:177], v[104:107]
	v_mfma_f32_16x16x32_bf16 v[92:95], v[134:137], v[206:209], v[92:95]
	v_mfma_f32_16x16x32_bf16 v[88:91], v[142:145], v[206:209], v[88:91]
	v_mfma_f32_16x16x32_bf16 v[76:79], v[134:137], v[214:217], v[76:79]
	v_mfma_f32_16x16x32_bf16 v[72:75], v[142:145], v[214:217], v[72:75]
	v_mfma_f32_16x16x32_bf16 v[124:127], v[138:141], v[170:173], v[124:127]
	v_mfma_f32_16x16x32_bf16 v[120:123], v[146:149], v[170:173], v[120:123]
	v_mfma_f32_16x16x32_bf16 v[108:111], v[138:141], v[202:205], v[108:111]
	v_mfma_f32_16x16x32_bf16 v[104:107], v[146:149], v[202:205], v[104:107]
	v_mfma_f32_16x16x32_bf16 v[92:95], v[138:141], v[210:213], v[92:95]
	v_mfma_f32_16x16x32_bf16 v[88:91], v[146:149], v[210:213], v[88:91]
	v_mfma_f32_16x16x32_bf16 v[76:79], v[138:141], v[234:237], v[76:79]
	v_mfma_f32_16x16x32_bf16 v[72:75], v[146:149], v[234:237], v[72:75]
	v_mfma_f32_16x16x32_bf16 v[116:119], v[150:153], v[166:169], v[116:119]
	v_mfma_f32_16x16x32_bf16 v[112:115], v[158:161], v[166:169], v[112:115]
	v_mfma_f32_16x16x32_bf16 v[100:103], v[150:153], v[174:177], v[100:103]
	v_mfma_f32_16x16x32_bf16 v[96:99], v[158:161], v[174:177], v[96:99]
	v_mfma_f32_16x16x32_bf16 v[84:87], v[150:153], v[206:209], v[84:87]
	v_mfma_f32_16x16x32_bf16 v[80:83], v[158:161], v[206:209], v[80:83]
	v_mfma_f32_16x16x32_bf16 v[68:71], v[150:153], v[214:217], v[68:71]
	v_mfma_f32_16x16x32_bf16 v[64:67], v[158:161], v[214:217], v[64:67]
	v_mfma_f32_16x16x32_bf16 v[116:119], v[154:157], v[170:173], v[116:119]
	v_mfma_f32_16x16x32_bf16 v[112:115], v[162:165], v[170:173], v[112:115]
	v_mfma_f32_16x16x32_bf16 v[100:103], v[154:157], v[202:205], v[100:103]
	v_mfma_f32_16x16x32_bf16 v[96:99], v[162:165], v[202:205], v[96:99]
	v_mfma_f32_16x16x32_bf16 v[84:87], v[154:157], v[210:213], v[84:87]
	v_mfma_f32_16x16x32_bf16 v[80:83], v[162:165], v[210:213], v[80:83]
	v_mfma_f32_16x16x32_bf16 v[68:71], v[154:157], v[234:237], v[68:71]
	v_mfma_f32_16x16x32_bf16 v[64:67], v[162:165], v[234:237], v[64:67]
	s_setprio 0
	s_barrier
	s_add_i32 s30, s58, s3
	v_lshl_add_u64 v[130:131], v[130:131], 0, s[14:15]
	s_mov_b32 m0, s30
	ds_read_b128 v[166:169], v227 offset:49152
	ds_read_b128 v[170:173], v227 offset:50176
	ds_read_b128 v[174:177], v227 offset:51200
	ds_read_b128 v[202:205], v227 offset:52224
	ds_read_b128 v[206:209], v227 offset:53248
	ds_read_b128 v[210:213], v227 offset:54272
	ds_read_b128 v[214:217], v227 offset:55296
	ds_read_b128 v[234:237], v227 offset:56320
	global_load_lds_dwordx4 v[130:131], off
	v_lshl_add_u64 v[130:131], v[240:241], 0, s[14:15]
	s_add_i32 m0, s30, 0x2000
	s_add_i32 s5, s5, s3
	global_load_lds_dwordx4 v[130:131], off
	v_lshl_add_u64 v[130:131], v[238:239], 0, s[16:17]
	v_lshl_add_u64 v[218:219], v[130:131], 0, v[184:185]
	s_mov_b32 m0, s5
	v_lshl_add_u64 v[130:131], v[130:131], 0, v[188:189]
	global_load_lds_dwordx4 v[218:219], off
	s_add_i32 m0, s5, 0x2000
	s_nop 0
	global_load_lds_dwordx4 v[130:131], off
	v_lshl_add_u64 v[130:131], v[242:243], 0, s[14:15]
	s_mov_b32 m0, s49
	s_nop 0
	global_load_lds_dwordx4 v[130:131], off
	v_lshl_add_u64 v[130:131], v[244:245], 0, s[14:15]
	s_mov_b32 m0, s50
	s_nop 0
	global_load_lds_dwordx4 v[130:131], off
	s_waitcnt vmcnt(8)
	s_waitcnt lgkmcnt(0)
	s_barrier
	s_setprio 1
	v_mfma_f32_16x16x32_bf16 v[60:63], v[134:137], v[166:169], v[60:63]
	v_mfma_f32_16x16x32_bf16 v[56:59], v[142:145], v[166:169], v[56:59]
	v_mfma_f32_16x16x32_bf16 v[44:47], v[134:137], v[174:177], v[44:47]
	v_mfma_f32_16x16x32_bf16 v[40:43], v[142:145], v[174:177], v[40:43]
	v_mfma_f32_16x16x32_bf16 v[28:31], v[134:137], v[206:209], v[28:31]
	v_mfma_f32_16x16x32_bf16 v[24:27], v[142:145], v[206:209], v[24:27]
	v_mfma_f32_16x16x32_bf16 v[12:15], v[134:137], v[214:217], v[12:15]
	v_mfma_f32_16x16x32_bf16 v[8:11], v[142:145], v[214:217], v[8:11]
	v_mfma_f32_16x16x32_bf16 v[60:63], v[138:141], v[170:173], v[60:63]
	v_mfma_f32_16x16x32_bf16 v[56:59], v[146:149], v[170:173], v[56:59]
	v_mfma_f32_16x16x32_bf16 v[44:47], v[138:141], v[202:205], v[44:47]
	v_mfma_f32_16x16x32_bf16 v[40:43], v[146:149], v[202:205], v[40:43]
	v_mfma_f32_16x16x32_bf16 v[28:31], v[138:141], v[210:213], v[28:31]
	v_mfma_f32_16x16x32_bf16 v[24:27], v[146:149], v[210:213], v[24:27]
	v_mfma_f32_16x16x32_bf16 v[12:15], v[138:141], v[234:237], v[12:15]
	v_mfma_f32_16x16x32_bf16 v[8:11], v[146:149], v[234:237], v[8:11]
	v_mfma_f32_16x16x32_bf16 v[52:55], v[150:153], v[166:169], v[52:55]
	v_mfma_f32_16x16x32_bf16 v[48:51], v[158:161], v[166:169], v[48:51]
	v_mfma_f32_16x16x32_bf16 v[36:39], v[150:153], v[174:177], v[36:39]
	v_mfma_f32_16x16x32_bf16 v[32:35], v[158:161], v[174:177], v[32:35]
	v_mfma_f32_16x16x32_bf16 v[20:23], v[150:153], v[206:209], v[20:23]
	v_mfma_f32_16x16x32_bf16 v[16:19], v[158:161], v[206:209], v[16:19]
	v_mfma_f32_16x16x32_bf16 v[4:7], v[150:153], v[214:217], v[4:7]
	v_mfma_f32_16x16x32_bf16 v[0:3], v[158:161], v[214:217], v[0:3]
	v_mfma_f32_16x16x32_bf16 v[52:55], v[154:157], v[170:173], v[52:55]
	v_mfma_f32_16x16x32_bf16 v[48:51], v[162:165], v[170:173], v[48:51]
	v_mfma_f32_16x16x32_bf16 v[36:39], v[154:157], v[202:205], v[36:39]
	v_mfma_f32_16x16x32_bf16 v[32:35], v[162:165], v[202:205], v[32:35]
	v_mfma_f32_16x16x32_bf16 v[20:23], v[154:157], v[210:213], v[20:23]
	v_mfma_f32_16x16x32_bf16 v[16:19], v[162:165], v[210:213], v[16:19]
	v_mfma_f32_16x16x32_bf16 v[4:7], v[154:157], v[234:237], v[4:7]
	v_mfma_f32_16x16x32_bf16 v[0:3], v[162:165], v[234:237], v[0:3]
	s_setprio 0
	s_barrier
	s_add_i32 s4, s4, 2
	v_lshl_add_u64 v[128:129], v[128:129], 0, s[20:21]
	s_cmp_gt_u32 s4, 41
	v_mov_b64_e32 v[130:131], v[132:133]
	s_cbranch_scc0 .LBB0_1430
	s_and_b64 vcc, exec, s[18:19]
	s_cbranch_vccz .LBB0_1433
	s_barrier
